# GEMM mainloop without the mid-segment priority drop (s_setprio 0/1 pair removed), on top of mixing edits
# speedup vs baseline: 1.0099x; 1.0039x over previous
.LBB0_41:
	s_add_u32 s40, s36, 0xfffc0080
	s_addc_u32 s41, s37, -1
	s_add_i32 s97, 0, 0x10000
	s_cmp_eq_u32 s90, 12
	s_cselect_b32 s47, s17, s41
	s_cselect_b32 s46, s68, s40
	v_add_u32_e32 v140, s97, v142
	s_cselect_b32 s45, s15, s89
	s_cselect_b32 s44, s69, s88
	s_add_i32 s40, 0, 0x14000
	ds_read_b128 v[146:149], v140
	ds_read_b128 v[150:153], v140 offset:1024
	ds_read_b128 v[154:157], v140 offset:2048
	ds_read_b128 v[158:161], v140 offset:3072
	v_add_u32_e32 v140, s40, v142
	ds_read_b128 v[162:165], v140
	ds_read_b128 v[166:169], v140 offset:1024
	ds_read_b128 v[170:173], v140 offset:2048
	ds_read_b128 v[174:177], v140 offset:3072
	v_lshl_add_u64 v[140:141], s[36:37], 0, v[136:137]
	s_add_i32 m0, s51, 0xc000
	ds_read_b128 v[190:193], v145
	ds_read_b128 v[194:197], v145 offset:1024
	ds_read_b128 v[198:201], v145 offset:2048
	ds_read_b128 v[202:205], v145 offset:3072
	ds_read_b128 v[206:209], v145 offset:4096
	ds_read_b128 v[228:231], v145 offset:5120
	ds_read_b128 v[232:235], v145 offset:6144
	ds_read_b128 v[236:239], v145 offset:7168
	global_load_lds_dwordx4 v[140:141], off
	v_lshl_add_u64 v[140:141], s[36:37], 0, v[138:139]
	s_add_i32 m0, s51, 0xe000
	s_nop 0
	global_load_lds_dwordx4 v[140:141], off
	s_waitcnt vmcnt(8)
	s_waitcnt lgkmcnt(0)
	s_barrier
	s_setprio 1
	s_waitcnt lgkmcnt(0)
	v_mfma_f32_16x16x32_bf16 v[124:127], v[146:149], v[190:193], v[124:127]
	v_mfma_f32_16x16x32_bf16 v[116:119], v[154:157], v[190:193], v[116:119]
	v_mfma_f32_16x16x32_bf16 v[108:111], v[146:149], v[198:201], v[108:111]
	v_mfma_f32_16x16x32_bf16 v[100:103], v[154:157], v[198:201], v[100:103]
	v_mfma_f32_16x16x32_bf16 v[92:95], v[146:149], v[206:209], v[92:95]
	v_mfma_f32_16x16x32_bf16 v[84:87], v[154:157], v[206:209], v[84:87]
	v_mfma_f32_16x16x32_bf16 v[76:79], v[146:149], v[232:235], v[76:79]
	v_mfma_f32_16x16x32_bf16 v[68:71], v[154:157], v[232:235], v[68:71]
	v_mfma_f32_16x16x32_bf16 v[124:127], v[150:153], v[194:197], v[124:127]
	v_mfma_f32_16x16x32_bf16 v[116:119], v[158:161], v[194:197], v[116:119]
	v_mfma_f32_16x16x32_bf16 v[108:111], v[150:153], v[202:205], v[108:111]
	v_mfma_f32_16x16x32_bf16 v[100:103], v[158:161], v[202:205], v[100:103]
	v_mfma_f32_16x16x32_bf16 v[92:95], v[150:153], v[228:231], v[92:95]
	v_mfma_f32_16x16x32_bf16 v[84:87], v[158:161], v[228:231], v[84:87]
	v_mfma_f32_16x16x32_bf16 v[76:79], v[150:153], v[236:239], v[76:79]
	v_mfma_f32_16x16x32_bf16 v[68:71], v[158:161], v[236:239], v[68:71]
	v_mfma_f32_16x16x32_bf16 v[128:131], v[162:165], v[190:193], v[128:131]
	v_mfma_f32_16x16x32_bf16 v[120:123], v[170:173], v[190:193], v[120:123]
	v_mfma_f32_16x16x32_bf16 v[112:115], v[162:165], v[198:201], v[112:115]
	v_mfma_f32_16x16x32_bf16 v[104:107], v[170:173], v[198:201], v[104:107]
	v_mfma_f32_16x16x32_bf16 v[96:99], v[162:165], v[206:209], v[96:99]
	v_mfma_f32_16x16x32_bf16 v[88:91], v[170:173], v[206:209], v[88:91]
	v_mfma_f32_16x16x32_bf16 v[80:83], v[162:165], v[232:235], v[80:83]
	v_mfma_f32_16x16x32_bf16 v[72:75], v[170:173], v[232:235], v[72:75]
	v_mfma_f32_16x16x32_bf16 v[128:131], v[166:169], v[194:197], v[128:131]
	v_mfma_f32_16x16x32_bf16 v[120:123], v[174:177], v[194:197], v[120:123]
	v_mfma_f32_16x16x32_bf16 v[112:115], v[166:169], v[202:205], v[112:115]
	v_mfma_f32_16x16x32_bf16 v[104:107], v[174:177], v[202:205], v[104:107]
	v_mfma_f32_16x16x32_bf16 v[96:99], v[166:169], v[228:231], v[96:99]
	v_mfma_f32_16x16x32_bf16 v[88:91], v[174:177], v[228:231], v[88:91]
	v_mfma_f32_16x16x32_bf16 v[80:83], v[166:169], v[236:239], v[80:83]
	v_mfma_f32_16x16x32_bf16 v[72:75], v[174:177], v[236:239], v[72:75]
	s_setprio 0
	s_barrier
	s_add_i32 s41, s97, s50
	v_lshl_add_u64 v[140:141], s[44:45], 0, v[180:181]
	s_mov_b32 m0, s41
	ds_read_b128 v[190:193], v145 offset:16384
	ds_read_b128 v[194:197], v145 offset:17408
	ds_read_b128 v[198:201], v145 offset:18432
	ds_read_b128 v[202:205], v145 offset:19456
	ds_read_b128 v[206:209], v145 offset:20480
	ds_read_b128 v[228:231], v145 offset:21504
	ds_read_b128 v[232:235], v145 offset:22528
	ds_read_b128 v[236:239], v145 offset:23552
	global_load_lds_dwordx4 v[140:141], off
	s_add_i32 m0, s41, 0x2000
	s_add_u32 vcc_lo, s44, 0x40000
	v_lshl_add_u64 v[178:179], s[44:45], 0, v[134:135]
	s_addc_u32 vcc_hi, s45, 0
	s_add_i32 s40, s40, s50
	global_load_lds_dwordx4 v[178:179], off
	v_lshl_add_u64 v[210:211], vcc, 0, v[180:181]
	s_mov_b32 m0, s40
	v_lshl_add_u64 v[218:219], s[46:47], 0, v[132:133]
	global_load_lds_dwordx4 v[210:211], off
	v_lshl_add_u64 v[210:211], vcc, 0, v[134:135]
	s_add_i32 m0, s40, 0x2000
	s_nop 0
	global_load_lds_dwordx4 v[210:211], off
	v_lshl_add_u64 v[210:211], s[46:47], 0, v[0:1]
	s_mov_b32 m0, s51
	s_nop 0
	global_load_lds_dwordx4 v[210:211], off
	s_mov_b32 m0, s52
	s_nop 0
	global_load_lds_dwordx4 v[218:219], off
	s_waitcnt vmcnt(8)
	s_waitcnt lgkmcnt(0)
	s_barrier
	s_setprio 1
	s_waitcnt lgkmcnt(0)
	v_mfma_f32_16x16x32_bf16 v[60:63], v[146:149], v[190:193], v[60:63]
	v_mfma_f32_16x16x32_bf16 v[52:55], v[154:157], v[190:193], v[52:55]
	v_mfma_f32_16x16x32_bf16 v[44:47], v[146:149], v[198:201], v[44:47]
	v_mfma_f32_16x16x32_bf16 v[36:39], v[154:157], v[198:201], v[36:39]
	v_mfma_f32_16x16x32_bf16 v[28:31], v[146:149], v[206:209], v[28:31]
	v_mfma_f32_16x16x32_bf16 v[20:23], v[154:157], v[206:209], v[20:23]
	v_mfma_f32_16x16x32_bf16 v[12:15], v[146:149], v[232:235], v[12:15]
	v_mfma_f32_16x16x32_bf16 v[8:11], v[154:157], v[232:235], v[8:11]
	v_mfma_f32_16x16x32_bf16 v[60:63], v[150:153], v[194:197], v[60:63]
	v_mfma_f32_16x16x32_bf16 v[52:55], v[158:161], v[194:197], v[52:55]
	v_mfma_f32_16x16x32_bf16 v[44:47], v[150:153], v[202:205], v[44:47]
	v_mfma_f32_16x16x32_bf16 v[36:39], v[158:161], v[202:205], v[36:39]
	v_mfma_f32_16x16x32_bf16 v[28:31], v[150:153], v[228:231], v[28:31]
	v_mfma_f32_16x16x32_bf16 v[20:23], v[158:161], v[228:231], v[20:23]
	v_mfma_f32_16x16x32_bf16 v[12:15], v[150:153], v[236:239], v[12:15]
	v_mfma_f32_16x16x32_bf16 v[8:11], v[158:161], v[236:239], v[8:11]
	v_mfma_f32_16x16x32_bf16 v[64:67], v[162:165], v[190:193], v[64:67]
	v_mfma_f32_16x16x32_bf16 v[56:59], v[170:173], v[190:193], v[56:59]
	v_mfma_f32_16x16x32_bf16 v[48:51], v[162:165], v[198:201], v[48:51]
	v_mfma_f32_16x16x32_bf16 v[40:43], v[170:173], v[198:201], v[40:43]
	v_mfma_f32_16x16x32_bf16 v[32:35], v[162:165], v[206:209], v[32:35]
	v_mfma_f32_16x16x32_bf16 v[24:27], v[170:173], v[206:209], v[24:27]
	v_mfma_f32_16x16x32_bf16 v[16:19], v[162:165], v[232:235], v[16:19]
	v_mfma_f32_16x16x32_bf16 v[4:7], v[170:173], v[232:235], v[4:7]
	v_mfma_f32_16x16x32_bf16 v[64:67], v[166:169], v[194:197], v[64:67]
	v_mfma_f32_16x16x32_bf16 v[56:59], v[174:177], v[194:197], v[56:59]
	v_mfma_f32_16x16x32_bf16 v[48:51], v[166:169], v[202:205], v[48:51]
	v_mfma_f32_16x16x32_bf16 v[40:43], v[174:177], v[202:205], v[40:43]
	v_mfma_f32_16x16x32_bf16 v[32:35], v[166:169], v[228:231], v[32:35]
	v_mfma_f32_16x16x32_bf16 v[24:27], v[174:177], v[228:231], v[24:27]
	v_mfma_f32_16x16x32_bf16 v[16:19], v[166:169], v[236:239], v[16:19]
	v_mfma_f32_16x16x32_bf16 v[4:7], v[174:177], v[236:239], v[4:7]
	s_setprio 0
	s_barrier
	s_add_i32 s40, 0, 0x18000
	s_add_i32 s41, 0, 0x1c000
	v_add_u32_e32 v158, s40, v142
	v_add_u32_e32 v174, s41, v142
	ds_read_b128 v[146:149], v158
	ds_read_b128 v[150:153], v158 offset:1024
	ds_read_b128 v[154:157], v158 offset:2048
	ds_read_b128 v[158:161], v158 offset:3072
	ds_read_b128 v[162:165], v174
	ds_read_b128 v[166:169], v174 offset:1024
	ds_read_b128 v[170:173], v174 offset:2048
	ds_read_b128 v[174:177], v174 offset:3072
	s_add_u32 s46, s46, 0x40000
	s_addc_u32 s47, s47, 0
	s_mov_b32 m0, s53
	v_lshl_add_u64 v[220:221], s[46:47], 0, v[0:1]
	ds_read_b128 v[190:193], v145 offset:32768
	ds_read_b128 v[194:197], v145 offset:33792
	ds_read_b128 v[198:201], v145 offset:34816
	ds_read_b128 v[202:205], v145 offset:35840
	ds_read_b128 v[206:209], v145 offset:36864
	ds_read_b128 v[228:231], v145 offset:37888
	ds_read_b128 v[232:235], v145 offset:38912
	ds_read_b128 v[236:239], v145 offset:39936
	global_load_lds_dwordx4 v[220:221], off
	v_lshl_add_u64 v[220:221], s[46:47], 0, v[132:133]
	s_mov_b32 m0, s54
	s_nop 0
	global_load_lds_dwordx4 v[220:221], off
	s_waitcnt vmcnt(8)
	s_waitcnt lgkmcnt(0)
	s_barrier
	s_setprio 1
	s_waitcnt lgkmcnt(0)
	v_mfma_f32_16x16x32_bf16 v[124:127], v[146:149], v[190:193], v[124:127]
	v_mfma_f32_16x16x32_bf16 v[116:119], v[154:157], v[190:193], v[116:119]
	v_mfma_f32_16x16x32_bf16 v[108:111], v[146:149], v[198:201], v[108:111]
	v_mfma_f32_16x16x32_bf16 v[100:103], v[154:157], v[198:201], v[100:103]
	v_mfma_f32_16x16x32_bf16 v[92:95], v[146:149], v[206:209], v[92:95]
	v_mfma_f32_16x16x32_bf16 v[84:87], v[154:157], v[206:209], v[84:87]
	v_mfma_f32_16x16x32_bf16 v[76:79], v[146:149], v[232:235], v[76:79]
	v_mfma_f32_16x16x32_bf16 v[68:71], v[154:157], v[232:235], v[68:71]
	v_mfma_f32_16x16x32_bf16 v[124:127], v[150:153], v[194:197], v[124:127]
	v_mfma_f32_16x16x32_bf16 v[116:119], v[158:161], v[194:197], v[116:119]
	v_mfma_f32_16x16x32_bf16 v[108:111], v[150:153], v[202:205], v[108:111]
	v_mfma_f32_16x16x32_bf16 v[100:103], v[158:161], v[202:205], v[100:103]
	v_mfma_f32_16x16x32_bf16 v[92:95], v[150:153], v[228:231], v[92:95]
	v_mfma_f32_16x16x32_bf16 v[84:87], v[158:161], v[228:231], v[84:87]
	v_mfma_f32_16x16x32_bf16 v[76:79], v[150:153], v[236:239], v[76:79]
	v_mfma_f32_16x16x32_bf16 v[68:71], v[158:161], v[236:239], v[68:71]
	v_mfma_f32_16x16x32_bf16 v[128:131], v[162:165], v[190:193], v[128:131]
	v_mfma_f32_16x16x32_bf16 v[120:123], v[170:173], v[190:193], v[120:123]
	v_mfma_f32_16x16x32_bf16 v[112:115], v[162:165], v[198:201], v[112:115]
	v_mfma_f32_16x16x32_bf16 v[104:107], v[170:173], v[198:201], v[104:107]
	v_mfma_f32_16x16x32_bf16 v[96:99], v[162:165], v[206:209], v[96:99]
	v_mfma_f32_16x16x32_bf16 v[88:91], v[170:173], v[206:209], v[88:91]
	v_mfma_f32_16x16x32_bf16 v[80:83], v[162:165], v[232:235], v[80:83]
	v_mfma_f32_16x16x32_bf16 v[72:75], v[170:173], v[232:235], v[72:75]
	v_mfma_f32_16x16x32_bf16 v[128:131], v[166:169], v[194:197], v[128:131]
	v_mfma_f32_16x16x32_bf16 v[120:123], v[174:177], v[194:197], v[120:123]
	v_mfma_f32_16x16x32_bf16 v[112:115], v[166:169], v[202:205], v[112:115]
	v_mfma_f32_16x16x32_bf16 v[104:107], v[174:177], v[202:205], v[104:107]
	v_mfma_f32_16x16x32_bf16 v[96:99], v[166:169], v[228:231], v[96:99]
	v_mfma_f32_16x16x32_bf16 v[88:91], v[174:177], v[228:231], v[88:91]
	v_mfma_f32_16x16x32_bf16 v[80:83], v[166:169], v[236:239], v[80:83]
	v_mfma_f32_16x16x32_bf16 v[72:75], v[174:177], v[236:239], v[72:75]
	s_setprio 0
	s_barrier
	s_add_i32 s40, s40, s50
	v_lshl_add_u64 v[140:141], v[140:141], 0, s[94:95]
	s_mov_b32 m0, s40
	ds_read_b128 v[190:193], v145 offset:49152
	ds_read_b128 v[194:197], v145 offset:50176
	ds_read_b128 v[198:201], v145 offset:51200
	ds_read_b128 v[202:205], v145 offset:52224
	ds_read_b128 v[206:209], v145 offset:53248
	ds_read_b128 v[228:231], v145 offset:54272
	ds_read_b128 v[232:235], v145 offset:55296
	ds_read_b128 v[236:239], v145 offset:56320
	global_load_lds_dwordx4 v[140:141], off
	s_add_i32 m0, s40, 0x2000
	s_add_u32 s44, s44, 0x40080
	v_lshl_add_u64 v[140:141], v[178:179], 0, s[94:95]
	s_addc_u32 s45, s45, 0
	s_add_i32 s40, s41, s50
	global_load_lds_dwordx4 v[140:141], off
	v_lshl_add_u64 v[140:141], s[44:45], 0, v[180:181]
	s_mov_b32 m0, s40
	s_nop 0
	global_load_lds_dwordx4 v[140:141], off
	v_lshl_add_u64 v[140:141], s[44:45], 0, v[134:135]
	s_add_i32 m0, s40, 0x2000
	s_nop 0
	global_load_lds_dwordx4 v[140:141], off
	v_lshl_add_u64 v[140:141], v[210:211], 0, s[94:95]
	s_mov_b32 m0, s55
	s_nop 0
	global_load_lds_dwordx4 v[140:141], off
	v_lshl_add_u64 v[140:141], v[218:219], 0, s[94:95]
	s_mov_b32 m0, s58
	s_nop 0
	global_load_lds_dwordx4 v[140:141], off
	s_waitcnt vmcnt(8)
	s_waitcnt lgkmcnt(0)
	s_barrier
	s_setprio 1
	s_waitcnt lgkmcnt(0)
	v_mfma_f32_16x16x32_bf16 v[60:63], v[146:149], v[190:193], v[60:63]
	v_mfma_f32_16x16x32_bf16 v[52:55], v[154:157], v[190:193], v[52:55]
	v_mfma_f32_16x16x32_bf16 v[44:47], v[146:149], v[198:201], v[44:47]
	v_mfma_f32_16x16x32_bf16 v[36:39], v[154:157], v[198:201], v[36:39]
	v_mfma_f32_16x16x32_bf16 v[28:31], v[146:149], v[206:209], v[28:31]
	v_mfma_f32_16x16x32_bf16 v[20:23], v[154:157], v[206:209], v[20:23]
	v_mfma_f32_16x16x32_bf16 v[12:15], v[146:149], v[232:235], v[12:15]
	v_mfma_f32_16x16x32_bf16 v[8:11], v[154:157], v[232:235], v[8:11]
	v_mfma_f32_16x16x32_bf16 v[60:63], v[150:153], v[194:197], v[60:63]
	v_mfma_f32_16x16x32_bf16 v[52:55], v[158:161], v[194:197], v[52:55]
	v_mfma_f32_16x16x32_bf16 v[44:47], v[150:153], v[202:205], v[44:47]
	v_mfma_f32_16x16x32_bf16 v[36:39], v[158:161], v[202:205], v[36:39]
	v_mfma_f32_16x16x32_bf16 v[28:31], v[150:153], v[228:231], v[28:31]
	v_mfma_f32_16x16x32_bf16 v[20:23], v[158:161], v[228:231], v[20:23]
	v_mfma_f32_16x16x32_bf16 v[12:15], v[150:153], v[236:239], v[12:15]
	v_mfma_f32_16x16x32_bf16 v[8:11], v[158:161], v[236:239], v[8:11]
	v_mfma_f32_16x16x32_bf16 v[64:67], v[162:165], v[190:193], v[64:67]
	v_mfma_f32_16x16x32_bf16 v[56:59], v[170:173], v[190:193], v[56:59]
	v_mfma_f32_16x16x32_bf16 v[48:51], v[162:165], v[198:201], v[48:51]
	v_mfma_f32_16x16x32_bf16 v[40:43], v[170:173], v[198:201], v[40:43]
	v_mfma_f32_16x16x32_bf16 v[32:35], v[162:165], v[206:209], v[32:35]
	v_mfma_f32_16x16x32_bf16 v[24:27], v[170:173], v[206:209], v[24:27]
	v_mfma_f32_16x16x32_bf16 v[16:19], v[162:165], v[232:235], v[16:19]
	v_mfma_f32_16x16x32_bf16 v[4:7], v[170:173], v[232:235], v[4:7]
	v_mfma_f32_16x16x32_bf16 v[64:67], v[166:169], v[194:197], v[64:67]
	v_mfma_f32_16x16x32_bf16 v[56:59], v[174:177], v[194:197], v[56:59]
	v_mfma_f32_16x16x32_bf16 v[48:51], v[166:169], v[202:205], v[48:51]
	v_mfma_f32_16x16x32_bf16 v[40:43], v[174:177], v[202:205], v[40:43]
	v_mfma_f32_16x16x32_bf16 v[32:35], v[166:169], v[228:231], v[32:35]
	v_mfma_f32_16x16x32_bf16 v[24:27], v[174:177], v[228:231], v[24:27]
	v_mfma_f32_16x16x32_bf16 v[16:19], v[166:169], v[236:239], v[16:19]
	v_mfma_f32_16x16x32_bf16 v[4:7], v[174:177], v[236:239], v[4:7]
	s_setprio 0
	s_barrier
	s_add_i32 s90, s90, 2
	s_add_u32 s36, s36, 0x100
	s_addc_u32 s37, s37, 0
	s_add_u32 s88, s88, 0x100
	s_addc_u32 s89, s89, 0
	s_cmp_gt_u32 s90, 13
	s_cbranch_scc0 .LBB0_41
	s_and_b64 vcc, exec, s[10:11]
	s_cbranch_vccz .LBB0_44
	s_barrier

.LBB0_83:
	s_add_u32 s10, s8, 0xfffc0080
	s_addc_u32 s11, s9, -1
	s_add_i32 s40, 0, 0x10000
	s_cmp_eq_u32 vcc_hi, 12
	s_cselect_b32 s53, s27, s11
	s_cselect_b32 s52, s89, s10
	s_cselect_b32 s11, s19, vcc_lo
	s_cselect_b32 s10, s90, s97
	s_add_i32 s25, 0, 0x14000
	v_add_u32_e32 v144, s40, v159
	v_add_u32_e32 v158, s25, v159
	ds_read_b128 v[132:135], v144
	ds_read_b128 v[136:139], v144 offset:1024
	ds_read_b128 v[140:143], v144 offset:2048
	ds_read_b128 v[144:147], v144 offset:3072
	ds_read_b128 v[190:193], v158
	ds_read_b128 v[194:197], v158 offset:1024
	ds_read_b128 v[198:201], v158 offset:2048
	ds_read_b128 v[202:205], v158 offset:3072
	v_lshl_add_u64 v[174:175], s[8:9], 0, v[154:155]
	s_add_i32 m0, s49, 0xc000
	ds_read_b128 v[206:209], v179
	ds_read_b128 v[228:231], v179 offset:1024
	ds_read_b128 v[232:235], v179 offset:2048
	ds_read_b128 v[236:239], v179 offset:3072
	ds_read_b128 v[240:243], v179 offset:4096
	ds_read_b128 v[244:247], v179 offset:5120
	ds_read_b128 v[224:227], v179 offset:6144
	ds_read_b128 v[218:221], v179 offset:7168
	global_load_lds_dwordx4 v[174:175], off
	v_lshl_add_u64 v[174:175], s[8:9], 0, v[156:157]
	s_add_i32 m0, s49, 0xe000
	s_nop 0
	global_load_lds_dwordx4 v[174:175], off
	s_waitcnt vmcnt(8)
	s_waitcnt lgkmcnt(0)
	s_barrier
	s_setprio 1
	s_waitcnt lgkmcnt(0)
	v_mfma_f32_16x16x32_bf16 v[128:131], v[132:135], v[206:209], v[128:131]
	v_mfma_f32_16x16x32_bf16 v[124:127], v[140:143], v[206:209], v[124:127]
	v_mfma_f32_16x16x32_bf16 v[112:115], v[132:135], v[232:235], v[112:115]
	v_mfma_f32_16x16x32_bf16 v[108:111], v[140:143], v[232:235], v[108:111]
	v_mfma_f32_16x16x32_bf16 v[96:99], v[132:135], v[240:243], v[96:99]
	v_mfma_f32_16x16x32_bf16 v[92:95], v[140:143], v[240:243], v[92:95]
	v_mfma_f32_16x16x32_bf16 v[80:83], v[132:135], v[224:227], v[80:83]
	v_mfma_f32_16x16x32_bf16 v[76:79], v[140:143], v[224:227], v[76:79]
	v_mfma_f32_16x16x32_bf16 v[128:131], v[136:139], v[228:231], v[128:131]
	v_mfma_f32_16x16x32_bf16 v[124:127], v[144:147], v[228:231], v[124:127]
	v_mfma_f32_16x16x32_bf16 v[112:115], v[136:139], v[236:239], v[112:115]
	v_mfma_f32_16x16x32_bf16 v[108:111], v[144:147], v[236:239], v[108:111]
	v_mfma_f32_16x16x32_bf16 v[96:99], v[136:139], v[244:247], v[96:99]
	v_mfma_f32_16x16x32_bf16 v[92:95], v[144:147], v[244:247], v[92:95]
	v_mfma_f32_16x16x32_bf16 v[80:83], v[136:139], v[218:221], v[80:83]
	v_mfma_f32_16x16x32_bf16 v[76:79], v[144:147], v[218:221], v[76:79]
	v_mfma_f32_16x16x32_bf16 v[120:123], v[190:193], v[206:209], v[120:123]
	v_mfma_f32_16x16x32_bf16 v[116:119], v[198:201], v[206:209], v[116:119]
	v_mfma_f32_16x16x32_bf16 v[104:107], v[190:193], v[232:235], v[104:107]
	v_mfma_f32_16x16x32_bf16 v[100:103], v[198:201], v[232:235], v[100:103]
	v_mfma_f32_16x16x32_bf16 v[88:91], v[190:193], v[240:243], v[88:91]
	v_mfma_f32_16x16x32_bf16 v[84:87], v[198:201], v[240:243], v[84:87]
	v_mfma_f32_16x16x32_bf16 v[72:75], v[190:193], v[224:227], v[72:75]
	v_mfma_f32_16x16x32_bf16 v[68:71], v[198:201], v[224:227], v[68:71]
	v_mfma_f32_16x16x32_bf16 v[120:123], v[194:197], v[228:231], v[120:123]
	v_mfma_f32_16x16x32_bf16 v[116:119], v[202:205], v[228:231], v[116:119]
	v_mfma_f32_16x16x32_bf16 v[104:107], v[194:197], v[236:239], v[104:107]
	v_mfma_f32_16x16x32_bf16 v[100:103], v[202:205], v[236:239], v[100:103]
	v_mfma_f32_16x16x32_bf16 v[88:91], v[194:197], v[244:247], v[88:91]
	v_mfma_f32_16x16x32_bf16 v[84:87], v[202:205], v[244:247], v[84:87]
	v_mfma_f32_16x16x32_bf16 v[72:75], v[194:197], v[218:221], v[72:75]
	v_mfma_f32_16x16x32_bf16 v[68:71], v[202:205], v[218:221], v[68:71]
	s_setprio 0
	s_barrier
	s_add_i32 s40, s40, s55
	v_lshl_add_u64 v[174:175], s[10:11], 0, v[180:181]
	s_mov_b32 m0, s40
	ds_read_b128 v[206:209], v179 offset:16384
	ds_read_b128 v[218:221], v179 offset:17408
	ds_read_b128 v[224:227], v179 offset:18432
	ds_read_b128 v[228:231], v179 offset:19456
	ds_read_b128 v[232:235], v179 offset:20480
	ds_read_b128 v[236:239], v179 offset:21504
	ds_read_b128 v[240:243], v179 offset:22528
	ds_read_b128 v[244:247], v179 offset:23552
	global_load_lds_dwordx4 v[174:175], off
	s_add_i32 m0, s40, 0x2000
	s_add_u32 s40, s10, 0x40000
	v_lshl_add_u64 v[210:211], s[10:11], 0, v[150:151]
	s_addc_u32 s41, s11, 0
	s_add_i32 s25, s25, s55
	global_load_lds_dwordx4 v[210:211], off
	v_lshl_add_u64 v[248:249], s[40:41], 0, v[180:181]
	s_mov_b32 m0, s25
	v_lshl_add_u64 v[182:183], s[52:53], 0, v[148:149]
	global_load_lds_dwordx4 v[248:249], off
	v_lshl_add_u64 v[248:249], s[40:41], 0, v[150:151]
	s_add_i32 m0, s25, 0x2000
	s_nop 0
	global_load_lds_dwordx4 v[248:249], off
	v_lshl_add_u64 v[248:249], s[52:53], 0, v[0:1]
	s_mov_b32 m0, s49
	s_nop 0
	global_load_lds_dwordx4 v[248:249], off
	s_mov_b32 m0, s51
	s_nop 0
	global_load_lds_dwordx4 v[182:183], off
	s_waitcnt vmcnt(8)
	s_waitcnt lgkmcnt(0)
	s_barrier
	s_setprio 1
	s_waitcnt lgkmcnt(0)
	v_mfma_f32_16x16x32_bf16 v[64:67], v[132:135], v[206:209], v[64:67]
	v_mfma_f32_16x16x32_bf16 v[60:63], v[140:143], v[206:209], v[60:63]
	v_mfma_f32_16x16x32_bf16 v[48:51], v[132:135], v[224:227], v[48:51]
	v_mfma_f32_16x16x32_bf16 v[44:47], v[140:143], v[224:227], v[44:47]
	v_mfma_f32_16x16x32_bf16 v[32:35], v[132:135], v[232:235], v[32:35]
	v_mfma_f32_16x16x32_bf16 v[28:31], v[140:143], v[232:235], v[28:31]
	v_mfma_f32_16x16x32_bf16 v[16:19], v[132:135], v[240:243], v[16:19]
	v_mfma_f32_16x16x32_bf16 v[12:15], v[140:143], v[240:243], v[12:15]
	v_mfma_f32_16x16x32_bf16 v[64:67], v[136:139], v[218:221], v[64:67]
	v_mfma_f32_16x16x32_bf16 v[60:63], v[144:147], v[218:221], v[60:63]
	v_mfma_f32_16x16x32_bf16 v[48:51], v[136:139], v[228:231], v[48:51]
	v_mfma_f32_16x16x32_bf16 v[44:47], v[144:147], v[228:231], v[44:47]
	v_mfma_f32_16x16x32_bf16 v[32:35], v[136:139], v[236:239], v[32:35]
	v_mfma_f32_16x16x32_bf16 v[28:31], v[144:147], v[236:239], v[28:31]
	v_mfma_f32_16x16x32_bf16 v[16:19], v[136:139], v[244:247], v[16:19]
	v_mfma_f32_16x16x32_bf16 v[12:15], v[144:147], v[244:247], v[12:15]
	v_mfma_f32_16x16x32_bf16 v[56:59], v[190:193], v[206:209], v[56:59]
	v_mfma_f32_16x16x32_bf16 v[52:55], v[198:201], v[206:209], v[52:55]
	v_mfma_f32_16x16x32_bf16 v[40:43], v[190:193], v[224:227], v[40:43]
	v_mfma_f32_16x16x32_bf16 v[36:39], v[198:201], v[224:227], v[36:39]
	v_mfma_f32_16x16x32_bf16 v[24:27], v[190:193], v[232:235], v[24:27]
	v_mfma_f32_16x16x32_bf16 v[20:23], v[198:201], v[232:235], v[20:23]
	v_mfma_f32_16x16x32_bf16 v[8:11], v[190:193], v[240:243], v[8:11]
	v_mfma_f32_16x16x32_bf16 v[4:7], v[198:201], v[240:243], v[4:7]
	v_mfma_f32_16x16x32_bf16 v[56:59], v[194:197], v[218:221], v[56:59]
	v_mfma_f32_16x16x32_bf16 v[52:55], v[202:205], v[218:221], v[52:55]
	v_mfma_f32_16x16x32_bf16 v[40:43], v[194:197], v[228:231], v[40:43]
	v_mfma_f32_16x16x32_bf16 v[36:39], v[202:205], v[228:231], v[36:39]
	v_mfma_f32_16x16x32_bf16 v[24:27], v[194:197], v[236:239], v[24:27]
	v_mfma_f32_16x16x32_bf16 v[20:23], v[202:205], v[236:239], v[20:23]
	v_mfma_f32_16x16x32_bf16 v[8:11], v[194:197], v[244:247], v[8:11]
	v_mfma_f32_16x16x32_bf16 v[4:7], v[202:205], v[244:247], v[4:7]
	s_setprio 0
	s_barrier
	s_add_i32 s25, 0, 0x18000
	s_add_i32 s70, 0, 0x1c000
	v_add_u32_e32 v144, s25, v159
	v_add_u32_e32 v158, s70, v159
	ds_read_b128 v[132:135], v144
	ds_read_b128 v[136:139], v144 offset:1024
	ds_read_b128 v[140:143], v144 offset:2048
	ds_read_b128 v[144:147], v144 offset:3072
	ds_read_b128 v[190:193], v158
	ds_read_b128 v[194:197], v158 offset:1024
	ds_read_b128 v[198:201], v158 offset:2048
	ds_read_b128 v[202:205], v158 offset:3072
	s_add_u32 s40, s52, 0x40000
	s_addc_u32 s41, s53, 0
	s_mov_b32 m0, s58
	v_lshl_add_u64 v[184:185], s[40:41], 0, v[0:1]
	ds_read_b128 v[206:209], v179 offset:32768
	ds_read_b128 v[218:221], v179 offset:33792
	ds_read_b128 v[224:227], v179 offset:34816
	ds_read_b128 v[228:231], v179 offset:35840
	ds_read_b128 v[232:235], v179 offset:36864
	ds_read_b128 v[236:239], v179 offset:37888
	ds_read_b128 v[240:243], v179 offset:38912
	ds_read_b128 v[244:247], v179 offset:39936
	global_load_lds_dwordx4 v[184:185], off
	v_lshl_add_u64 v[184:185], s[40:41], 0, v[148:149]
	s_mov_b32 m0, s59
	s_nop 0
	global_load_lds_dwordx4 v[184:185], off
	s_waitcnt vmcnt(8)
	s_waitcnt lgkmcnt(0)
	s_barrier
	s_setprio 1
	s_waitcnt lgkmcnt(0)
	v_mfma_f32_16x16x32_bf16 v[128:131], v[132:135], v[206:209], v[128:131]
	v_mfma_f32_16x16x32_bf16 v[124:127], v[140:143], v[206:209], v[124:127]
	v_mfma_f32_16x16x32_bf16 v[112:115], v[132:135], v[224:227], v[112:115]
	v_mfma_f32_16x16x32_bf16 v[108:111], v[140:143], v[224:227], v[108:111]
	v_mfma_f32_16x16x32_bf16 v[96:99], v[132:135], v[232:235], v[96:99]
	v_mfma_f32_16x16x32_bf16 v[92:95], v[140:143], v[232:235], v[92:95]
	v_mfma_f32_16x16x32_bf16 v[80:83], v[132:135], v[240:243], v[80:83]
	v_mfma_f32_16x16x32_bf16 v[76:79], v[140:143], v[240:243], v[76:79]
	v_mfma_f32_16x16x32_bf16 v[128:131], v[136:139], v[218:221], v[128:131]
	v_mfma_f32_16x16x32_bf16 v[124:127], v[144:147], v[218:221], v[124:127]
	v_mfma_f32_16x16x32_bf16 v[112:115], v[136:139], v[228:231], v[112:115]
	v_mfma_f32_16x16x32_bf16 v[108:111], v[144:147], v[228:231], v[108:111]
	v_mfma_f32_16x16x32_bf16 v[96:99], v[136:139], v[236:239], v[96:99]
	v_mfma_f32_16x16x32_bf16 v[92:95], v[144:147], v[236:239], v[92:95]
	v_mfma_f32_16x16x32_bf16 v[80:83], v[136:139], v[244:247], v[80:83]
	v_mfma_f32_16x16x32_bf16 v[76:79], v[144:147], v[244:247], v[76:79]
	v_mfma_f32_16x16x32_bf16 v[120:123], v[190:193], v[206:209], v[120:123]
	v_mfma_f32_16x16x32_bf16 v[116:119], v[198:201], v[206:209], v[116:119]
	v_mfma_f32_16x16x32_bf16 v[104:107], v[190:193], v[224:227], v[104:107]
	v_mfma_f32_16x16x32_bf16 v[100:103], v[198:201], v[224:227], v[100:103]
	v_mfma_f32_16x16x32_bf16 v[88:91], v[190:193], v[232:235], v[88:91]
	v_mfma_f32_16x16x32_bf16 v[84:87], v[198:201], v[232:235], v[84:87]
	v_mfma_f32_16x16x32_bf16 v[72:75], v[190:193], v[240:243], v[72:75]
	v_mfma_f32_16x16x32_bf16 v[68:71], v[198:201], v[240:243], v[68:71]
	v_mfma_f32_16x16x32_bf16 v[120:123], v[194:197], v[218:221], v[120:123]
	v_mfma_f32_16x16x32_bf16 v[116:119], v[202:205], v[218:221], v[116:119]
	v_mfma_f32_16x16x32_bf16 v[104:107], v[194:197], v[228:231], v[104:107]
	v_mfma_f32_16x16x32_bf16 v[100:103], v[202:205], v[228:231], v[100:103]
	v_mfma_f32_16x16x32_bf16 v[88:91], v[194:197], v[236:239], v[88:91]
	v_mfma_f32_16x16x32_bf16 v[84:87], v[202:205], v[236:239], v[84:87]
	v_mfma_f32_16x16x32_bf16 v[72:75], v[194:197], v[244:247], v[72:75]
	v_mfma_f32_16x16x32_bf16 v[68:71], v[202:205], v[244:247], v[68:71]
	s_setprio 0
	s_barrier
	s_add_i32 s25, s25, s55
	v_lshl_add_u64 v[174:175], v[174:175], 0, s[94:95]
	s_mov_b32 m0, s25
	ds_read_b128 v[206:209], v179 offset:49152
	ds_read_b128 v[218:221], v179 offset:50176
	ds_read_b128 v[224:227], v179 offset:51200
	ds_read_b128 v[228:231], v179 offset:52224
	ds_read_b128 v[232:235], v179 offset:53248
	ds_read_b128 v[236:239], v179 offset:54272
	ds_read_b128 v[240:243], v179 offset:55296
	ds_read_b128 v[244:247], v179 offset:56320
	global_load_lds_dwordx4 v[174:175], off
	s_add_i32 m0, s25, 0x2000
	s_add_u32 s10, s10, 0x40080
	v_lshl_add_u64 v[174:175], v[210:211], 0, s[94:95]
	s_addc_u32 s11, s11, 0
	s_add_i32 s25, s70, s55
	global_load_lds_dwordx4 v[174:175], off
	v_lshl_add_u64 v[174:175], s[10:11], 0, v[180:181]
	s_mov_b32 m0, s25
	s_nop 0
	global_load_lds_dwordx4 v[174:175], off
	v_lshl_add_u64 v[174:175], s[10:11], 0, v[150:151]
	s_add_i32 m0, s25, 0x2000
	s_nop 0
	global_load_lds_dwordx4 v[174:175], off
	v_lshl_add_u64 v[174:175], v[248:249], 0, s[94:95]
	s_mov_b32 m0, s64
	s_nop 0
	global_load_lds_dwordx4 v[174:175], off
	v_lshl_add_u64 v[174:175], v[182:183], 0, s[94:95]
	s_mov_b32 m0, s65
	s_nop 0
	global_load_lds_dwordx4 v[174:175], off
	s_waitcnt vmcnt(8)
	s_waitcnt lgkmcnt(0)
	s_barrier
	s_setprio 1
	s_waitcnt lgkmcnt(0)
	v_mfma_f32_16x16x32_bf16 v[64:67], v[132:135], v[206:209], v[64:67]
	v_mfma_f32_16x16x32_bf16 v[60:63], v[140:143], v[206:209], v[60:63]
	v_mfma_f32_16x16x32_bf16 v[48:51], v[132:135], v[224:227], v[48:51]
	v_mfma_f32_16x16x32_bf16 v[44:47], v[140:143], v[224:227], v[44:47]
	v_mfma_f32_16x16x32_bf16 v[32:35], v[132:135], v[232:235], v[32:35]
	v_mfma_f32_16x16x32_bf16 v[28:31], v[140:143], v[232:235], v[28:31]
	v_mfma_f32_16x16x32_bf16 v[16:19], v[132:135], v[240:243], v[16:19]
	v_mfma_f32_16x16x32_bf16 v[12:15], v[140:143], v[240:243], v[12:15]
	v_mfma_f32_16x16x32_bf16 v[64:67], v[136:139], v[218:221], v[64:67]
	v_mfma_f32_16x16x32_bf16 v[60:63], v[144:147], v[218:221], v[60:63]
	v_mfma_f32_16x16x32_bf16 v[48:51], v[136:139], v[228:231], v[48:51]
	v_mfma_f32_16x16x32_bf16 v[44:47], v[144:147], v[228:231], v[44:47]
	v_mfma_f32_16x16x32_bf16 v[32:35], v[136:139], v[236:239], v[32:35]
	v_mfma_f32_16x16x32_bf16 v[28:31], v[144:147], v[236:239], v[28:31]
	v_mfma_f32_16x16x32_bf16 v[16:19], v[136:139], v[244:247], v[16:19]
	v_mfma_f32_16x16x32_bf16 v[12:15], v[144:147], v[244:247], v[12:15]
	v_mfma_f32_16x16x32_bf16 v[56:59], v[190:193], v[206:209], v[56:59]
	v_mfma_f32_16x16x32_bf16 v[52:55], v[198:201], v[206:209], v[52:55]
	v_mfma_f32_16x16x32_bf16 v[40:43], v[190:193], v[224:227], v[40:43]
	v_mfma_f32_16x16x32_bf16 v[36:39], v[198:201], v[224:227], v[36:39]
	v_mfma_f32_16x16x32_bf16 v[24:27], v[190:193], v[232:235], v[24:27]
	v_mfma_f32_16x16x32_bf16 v[20:23], v[198:201], v[232:235], v[20:23]
	v_mfma_f32_16x16x32_bf16 v[8:11], v[190:193], v[240:243], v[8:11]
	v_mfma_f32_16x16x32_bf16 v[4:7], v[198:201], v[240:243], v[4:7]
	v_mfma_f32_16x16x32_bf16 v[56:59], v[194:197], v[218:221], v[56:59]
	v_mfma_f32_16x16x32_bf16 v[52:55], v[202:205], v[218:221], v[52:55]
	v_mfma_f32_16x16x32_bf16 v[40:43], v[194:197], v[228:231], v[40:43]
	v_mfma_f32_16x16x32_bf16 v[36:39], v[202:205], v[228:231], v[36:39]
	v_mfma_f32_16x16x32_bf16 v[24:27], v[194:197], v[236:239], v[24:27]
	v_mfma_f32_16x16x32_bf16 v[20:23], v[202:205], v[236:239], v[20:23]
	v_mfma_f32_16x16x32_bf16 v[8:11], v[194:197], v[244:247], v[8:11]
	v_mfma_f32_16x16x32_bf16 v[4:7], v[202:205], v[244:247], v[4:7]
	s_setprio 0
	s_barrier
	s_add_i32 vcc_hi, vcc_hi, 2
	s_add_u32 s8, s8, 0x100
	s_addc_u32 s9, s9, 0
	s_add_u32 s97, s97, 0x100
	s_addc_u32 vcc_lo, vcc_lo, 0
	s_cmp_gt_u32 vcc_hi, 13
	s_cbranch_scc0 .LBB0_83
	s_and_b64 vcc, exec, s[16:17]
	s_cbranch_vccz .LBB0_86
	s_barrier

.LBB0_142:
	s_add_u32 s25, s36, 0xfffc0080
	s_addc_u32 s40, s37, -1
	s_add_i32 s41, 0, 0x10000
	s_cmp_eq_u32 s88, 12
	s_cselect_b32 s47, s17, s40
	s_cselect_b32 s46, s64, s25
	s_cselect_b32 s45, s15, s69
	s_cselect_b32 s44, s65, s68
	s_add_i32 s25, 0, 0x14000
	v_add_u32_e32 v156, s41, v140
	v_add_u32_e32 v172, s25, v140
	ds_read_b128 v[144:147], v156
	ds_read_b128 v[148:151], v156 offset:1024
	ds_read_b128 v[152:155], v156 offset:2048
	ds_read_b128 v[156:159], v156 offset:3072
	ds_read_b128 v[160:163], v172
	ds_read_b128 v[164:167], v172 offset:1024
	ds_read_b128 v[168:171], v172 offset:2048
	ds_read_b128 v[172:175], v172 offset:3072
	v_lshl_add_u64 v[182:183], s[36:37], 0, v[136:137]
	s_add_i32 m0, s49, 0xc000
	ds_read_b128 v[176:179], v143
	ds_read_b128 v[190:193], v143 offset:1024
	ds_read_b128 v[194:197], v143 offset:2048
	ds_read_b128 v[198:201], v143 offset:3072
	ds_read_b128 v[202:205], v143 offset:4096
	ds_read_b128 v[206:209], v143 offset:5120
	ds_read_b128 v[218:221], v143 offset:6144
	ds_read_b128 v[224:227], v143 offset:7168
	global_load_lds_dwordx4 v[182:183], off
	v_lshl_add_u64 v[182:183], s[36:37], 0, v[138:139]
	s_add_i32 m0, s49, 0xe000
	s_nop 0
	global_load_lds_dwordx4 v[182:183], off
	s_waitcnt vmcnt(8)
	s_waitcnt lgkmcnt(0)
	s_barrier
	s_setprio 1
	s_waitcnt lgkmcnt(0)
	v_mfma_f32_16x16x32_bf16 v[128:131], v[144:147], v[176:179], v[128:131]
	v_mfma_f32_16x16x32_bf16 v[124:127], v[152:155], v[176:179], v[124:127]
	v_mfma_f32_16x16x32_bf16 v[120:123], v[144:147], v[194:197], v[120:123]
	v_mfma_f32_16x16x32_bf16 v[112:115], v[152:155], v[194:197], v[112:115]
	v_mfma_f32_16x16x32_bf16 v[96:99], v[144:147], v[202:205], v[96:99]
	v_mfma_f32_16x16x32_bf16 v[92:95], v[152:155], v[202:205], v[92:95]
	v_mfma_f32_16x16x32_bf16 v[88:91], v[144:147], v[218:221], v[88:91]
	v_mfma_f32_16x16x32_bf16 v[80:83], v[152:155], v[218:221], v[80:83]
	v_mfma_f32_16x16x32_bf16 v[128:131], v[148:151], v[190:193], v[128:131]
	v_mfma_f32_16x16x32_bf16 v[124:127], v[156:159], v[190:193], v[124:127]
	v_mfma_f32_16x16x32_bf16 v[120:123], v[148:151], v[198:201], v[120:123]
	v_mfma_f32_16x16x32_bf16 v[112:115], v[156:159], v[198:201], v[112:115]
	v_mfma_f32_16x16x32_bf16 v[96:99], v[148:151], v[206:209], v[96:99]
	v_mfma_f32_16x16x32_bf16 v[92:95], v[156:159], v[206:209], v[92:95]
	v_mfma_f32_16x16x32_bf16 v[88:91], v[148:151], v[224:227], v[88:91]
	v_mfma_f32_16x16x32_bf16 v[80:83], v[156:159], v[224:227], v[80:83]
	v_mfma_f32_16x16x32_bf16 v[116:119], v[160:163], v[176:179], v[116:119]
	v_mfma_f32_16x16x32_bf16 v[108:111], v[168:171], v[176:179], v[108:111]
	v_mfma_f32_16x16x32_bf16 v[104:107], v[160:163], v[194:197], v[104:107]
	v_mfma_f32_16x16x32_bf16 v[100:103], v[168:171], v[194:197], v[100:103]
	v_mfma_f32_16x16x32_bf16 v[84:87], v[160:163], v[202:205], v[84:87]
	v_mfma_f32_16x16x32_bf16 v[76:79], v[168:171], v[202:205], v[76:79]
	v_mfma_f32_16x16x32_bf16 v[72:75], v[160:163], v[218:221], v[72:75]
	v_mfma_f32_16x16x32_bf16 v[68:71], v[168:171], v[218:221], v[68:71]
	v_mfma_f32_16x16x32_bf16 v[116:119], v[164:167], v[190:193], v[116:119]
	v_mfma_f32_16x16x32_bf16 v[108:111], v[172:175], v[190:193], v[108:111]
	v_mfma_f32_16x16x32_bf16 v[104:107], v[164:167], v[198:201], v[104:107]
	v_mfma_f32_16x16x32_bf16 v[100:103], v[172:175], v[198:201], v[100:103]
	v_mfma_f32_16x16x32_bf16 v[84:87], v[164:167], v[206:209], v[84:87]
	v_mfma_f32_16x16x32_bf16 v[76:79], v[172:175], v[206:209], v[76:79]
	v_mfma_f32_16x16x32_bf16 v[72:75], v[164:167], v[224:227], v[72:75]
	v_mfma_f32_16x16x32_bf16 v[68:71], v[172:175], v[224:227], v[68:71]
	s_setprio 0
	s_barrier
	s_add_i32 s40, s41, s48
	v_lshl_add_u64 v[182:183], s[44:45], 0, v[180:181]
	s_mov_b32 m0, s40
	ds_read_b128 v[176:179], v143 offset:16384
	ds_read_b128 v[190:193], v143 offset:17408
	ds_read_b128 v[194:197], v143 offset:18432
	ds_read_b128 v[198:201], v143 offset:19456
	ds_read_b128 v[202:205], v143 offset:20480
	ds_read_b128 v[206:209], v143 offset:21504
	ds_read_b128 v[218:221], v143 offset:22528
	ds_read_b128 v[224:227], v143 offset:23552
	global_load_lds_dwordx4 v[182:183], off
	s_add_i32 m0, s40, 0x2000
	s_add_u32 s40, s44, 0x40000
	v_lshl_add_u64 v[184:185], s[44:45], 0, v[134:135]
	s_addc_u32 s41, s45, 0
	s_add_i32 s25, s25, s48
	global_load_lds_dwordx4 v[184:185], off
	v_lshl_add_u64 v[210:211], s[40:41], 0, v[180:181]
	s_mov_b32 m0, s25
	v_lshl_add_u64 v[228:229], s[46:47], 0, v[132:133]
	global_load_lds_dwordx4 v[210:211], off
	v_lshl_add_u64 v[210:211], s[40:41], 0, v[134:135]
	s_add_i32 m0, s25, 0x2000
	s_nop 0
	global_load_lds_dwordx4 v[210:211], off
	v_lshl_add_u64 v[210:211], s[46:47], 0, v[0:1]
	s_mov_b32 m0, s49
	s_nop 0
	global_load_lds_dwordx4 v[210:211], off
	s_mov_b32 m0, s50
	s_nop 0
	global_load_lds_dwordx4 v[228:229], off
	s_waitcnt vmcnt(8)
	s_waitcnt lgkmcnt(0)
	s_barrier
	s_setprio 1
	s_waitcnt lgkmcnt(0)
	v_mfma_f32_16x16x32_bf16 v[64:67], v[144:147], v[176:179], v[64:67]
	v_mfma_f32_16x16x32_bf16 v[60:63], v[152:155], v[176:179], v[60:63]
	v_mfma_f32_16x16x32_bf16 v[56:59], v[144:147], v[194:197], v[56:59]
	v_mfma_f32_16x16x32_bf16 v[48:51], v[152:155], v[194:197], v[48:51]
	v_mfma_f32_16x16x32_bf16 v[32:35], v[144:147], v[202:205], v[32:35]
	v_mfma_f32_16x16x32_bf16 v[28:31], v[152:155], v[202:205], v[28:31]
	v_mfma_f32_16x16x32_bf16 v[24:27], v[144:147], v[218:221], v[24:27]
	v_mfma_f32_16x16x32_bf16 v[16:19], v[152:155], v[218:221], v[16:19]
	v_mfma_f32_16x16x32_bf16 v[64:67], v[148:151], v[190:193], v[64:67]
	v_mfma_f32_16x16x32_bf16 v[60:63], v[156:159], v[190:193], v[60:63]
	v_mfma_f32_16x16x32_bf16 v[56:59], v[148:151], v[198:201], v[56:59]
	v_mfma_f32_16x16x32_bf16 v[48:51], v[156:159], v[198:201], v[48:51]
	v_mfma_f32_16x16x32_bf16 v[32:35], v[148:151], v[206:209], v[32:35]
	v_mfma_f32_16x16x32_bf16 v[28:31], v[156:159], v[206:209], v[28:31]
	v_mfma_f32_16x16x32_bf16 v[24:27], v[148:151], v[224:227], v[24:27]
	v_mfma_f32_16x16x32_bf16 v[16:19], v[156:159], v[224:227], v[16:19]
	v_mfma_f32_16x16x32_bf16 v[52:55], v[160:163], v[176:179], v[52:55]
	v_mfma_f32_16x16x32_bf16 v[44:47], v[168:171], v[176:179], v[44:47]
	v_mfma_f32_16x16x32_bf16 v[40:43], v[160:163], v[194:197], v[40:43]
	v_mfma_f32_16x16x32_bf16 v[36:39], v[168:171], v[194:197], v[36:39]
	v_mfma_f32_16x16x32_bf16 v[20:23], v[160:163], v[202:205], v[20:23]
	v_mfma_f32_16x16x32_bf16 v[12:15], v[168:171], v[202:205], v[12:15]
	v_mfma_f32_16x16x32_bf16 v[8:11], v[160:163], v[218:221], v[8:11]
	v_mfma_f32_16x16x32_bf16 v[4:7], v[168:171], v[218:221], v[4:7]
	v_mfma_f32_16x16x32_bf16 v[52:55], v[164:167], v[190:193], v[52:55]
	v_mfma_f32_16x16x32_bf16 v[44:47], v[172:175], v[190:193], v[44:47]
	v_mfma_f32_16x16x32_bf16 v[40:43], v[164:167], v[198:201], v[40:43]
	v_mfma_f32_16x16x32_bf16 v[36:39], v[172:175], v[198:201], v[36:39]
	v_mfma_f32_16x16x32_bf16 v[20:23], v[164:167], v[206:209], v[20:23]
	v_mfma_f32_16x16x32_bf16 v[12:15], v[172:175], v[206:209], v[12:15]
	v_mfma_f32_16x16x32_bf16 v[8:11], v[164:167], v[224:227], v[8:11]
	v_mfma_f32_16x16x32_bf16 v[4:7], v[172:175], v[224:227], v[4:7]
	s_setprio 0
	s_barrier
	s_add_i32 s25, 0, 0x18000
	s_add_i32 s70, 0, 0x1c000
	v_add_u32_e32 v156, s25, v140
	v_add_u32_e32 v172, s70, v140
	ds_read_b128 v[144:147], v156
	ds_read_b128 v[148:151], v156 offset:1024
	ds_read_b128 v[152:155], v156 offset:2048
	ds_read_b128 v[156:159], v156 offset:3072
	ds_read_b128 v[160:163], v172
	ds_read_b128 v[164:167], v172 offset:1024
	ds_read_b128 v[168:171], v172 offset:2048
	ds_read_b128 v[172:175], v172 offset:3072
	s_add_u32 s40, s46, 0x40000
	s_addc_u32 s41, s47, 0
	s_mov_b32 m0, s51
	v_lshl_add_u64 v[230:231], s[40:41], 0, v[0:1]
	ds_read_b128 v[176:179], v143 offset:32768
	ds_read_b128 v[190:193], v143 offset:33792
	ds_read_b128 v[194:197], v143 offset:34816
	ds_read_b128 v[198:201], v143 offset:35840
	ds_read_b128 v[202:205], v143 offset:36864
	ds_read_b128 v[206:209], v143 offset:37888
	ds_read_b128 v[218:221], v143 offset:38912
	ds_read_b128 v[224:227], v143 offset:39936
	global_load_lds_dwordx4 v[230:231], off
	v_lshl_add_u64 v[230:231], s[40:41], 0, v[132:133]
	s_mov_b32 m0, s52
	s_nop 0
	global_load_lds_dwordx4 v[230:231], off
	s_waitcnt vmcnt(8)
	s_waitcnt lgkmcnt(0)
	s_barrier
	s_setprio 1
	s_waitcnt lgkmcnt(0)
	v_mfma_f32_16x16x32_bf16 v[128:131], v[144:147], v[176:179], v[128:131]
	v_mfma_f32_16x16x32_bf16 v[124:127], v[152:155], v[176:179], v[124:127]
	v_mfma_f32_16x16x32_bf16 v[120:123], v[144:147], v[194:197], v[120:123]
	v_mfma_f32_16x16x32_bf16 v[112:115], v[152:155], v[194:197], v[112:115]
	v_mfma_f32_16x16x32_bf16 v[96:99], v[144:147], v[202:205], v[96:99]
	v_mfma_f32_16x16x32_bf16 v[92:95], v[152:155], v[202:205], v[92:95]
	v_mfma_f32_16x16x32_bf16 v[88:91], v[144:147], v[218:221], v[88:91]
	v_mfma_f32_16x16x32_bf16 v[80:83], v[152:155], v[218:221], v[80:83]
	v_mfma_f32_16x16x32_bf16 v[128:131], v[148:151], v[190:193], v[128:131]
	v_mfma_f32_16x16x32_bf16 v[124:127], v[156:159], v[190:193], v[124:127]
	v_mfma_f32_16x16x32_bf16 v[120:123], v[148:151], v[198:201], v[120:123]
	v_mfma_f32_16x16x32_bf16 v[112:115], v[156:159], v[198:201], v[112:115]
	v_mfma_f32_16x16x32_bf16 v[96:99], v[148:151], v[206:209], v[96:99]
	v_mfma_f32_16x16x32_bf16 v[92:95], v[156:159], v[206:209], v[92:95]
	v_mfma_f32_16x16x32_bf16 v[88:91], v[148:151], v[224:227], v[88:91]
	v_mfma_f32_16x16x32_bf16 v[80:83], v[156:159], v[224:227], v[80:83]
	v_mfma_f32_16x16x32_bf16 v[116:119], v[160:163], v[176:179], v[116:119]
	v_mfma_f32_16x16x32_bf16 v[108:111], v[168:171], v[176:179], v[108:111]
	v_mfma_f32_16x16x32_bf16 v[104:107], v[160:163], v[194:197], v[104:107]
	v_mfma_f32_16x16x32_bf16 v[100:103], v[168:171], v[194:197], v[100:103]
	v_mfma_f32_16x16x32_bf16 v[84:87], v[160:163], v[202:205], v[84:87]
	v_mfma_f32_16x16x32_bf16 v[76:79], v[168:171], v[202:205], v[76:79]
	v_mfma_f32_16x16x32_bf16 v[72:75], v[160:163], v[218:221], v[72:75]
	v_mfma_f32_16x16x32_bf16 v[68:71], v[168:171], v[218:221], v[68:71]
	v_mfma_f32_16x16x32_bf16 v[116:119], v[164:167], v[190:193], v[116:119]
	v_mfma_f32_16x16x32_bf16 v[108:111], v[172:175], v[190:193], v[108:111]
	v_mfma_f32_16x16x32_bf16 v[104:107], v[164:167], v[198:201], v[104:107]
	v_mfma_f32_16x16x32_bf16 v[100:103], v[172:175], v[198:201], v[100:103]
	v_mfma_f32_16x16x32_bf16 v[84:87], v[164:167], v[206:209], v[84:87]
	v_mfma_f32_16x16x32_bf16 v[76:79], v[172:175], v[206:209], v[76:79]
	v_mfma_f32_16x16x32_bf16 v[72:75], v[164:167], v[224:227], v[72:75]
	v_mfma_f32_16x16x32_bf16 v[68:71], v[172:175], v[224:227], v[68:71]
	s_setprio 0
	s_barrier
	s_add_i32 s25, s25, s48
	v_lshl_add_u64 v[182:183], v[182:183], 0, s[94:95]
	s_mov_b32 m0, s25
	ds_read_b128 v[176:179], v143 offset:49152
	ds_read_b128 v[190:193], v143 offset:50176
	ds_read_b128 v[194:197], v143 offset:51200
	ds_read_b128 v[198:201], v143 offset:52224
	ds_read_b128 v[202:205], v143 offset:53248
	ds_read_b128 v[206:209], v143 offset:54272
	ds_read_b128 v[218:221], v143 offset:55296
	ds_read_b128 v[224:227], v143 offset:56320
	global_load_lds_dwordx4 v[182:183], off
	s_add_i32 m0, s25, 0x2000
	s_add_u32 s40, s44, 0x40080
	v_lshl_add_u64 v[182:183], v[184:185], 0, s[94:95]
	s_addc_u32 s41, s45, 0
	s_add_i32 s25, s70, s48
	global_load_lds_dwordx4 v[182:183], off
	v_lshl_add_u64 v[182:183], s[40:41], 0, v[180:181]
	s_mov_b32 m0, s25
	s_nop 0
	global_load_lds_dwordx4 v[182:183], off
	v_lshl_add_u64 v[182:183], s[40:41], 0, v[134:135]
	s_add_i32 m0, s25, 0x2000
	s_nop 0
	global_load_lds_dwordx4 v[182:183], off
	v_lshl_add_u64 v[182:183], v[210:211], 0, s[94:95]
	s_mov_b32 m0, s53
	s_nop 0
	global_load_lds_dwordx4 v[182:183], off
	v_lshl_add_u64 v[182:183], v[228:229], 0, s[94:95]
	s_mov_b32 m0, s54
	s_nop 0
	global_load_lds_dwordx4 v[182:183], off
	s_waitcnt vmcnt(8)
	s_waitcnt lgkmcnt(0)
	s_barrier
	s_setprio 1
	s_waitcnt lgkmcnt(0)
	v_mfma_f32_16x16x32_bf16 v[64:67], v[144:147], v[176:179], v[64:67]
	v_mfma_f32_16x16x32_bf16 v[60:63], v[152:155], v[176:179], v[60:63]
	v_mfma_f32_16x16x32_bf16 v[56:59], v[144:147], v[194:197], v[56:59]
	v_mfma_f32_16x16x32_bf16 v[48:51], v[152:155], v[194:197], v[48:51]
	v_mfma_f32_16x16x32_bf16 v[32:35], v[144:147], v[202:205], v[32:35]
	v_mfma_f32_16x16x32_bf16 v[28:31], v[152:155], v[202:205], v[28:31]
	v_mfma_f32_16x16x32_bf16 v[24:27], v[144:147], v[218:221], v[24:27]
	v_mfma_f32_16x16x32_bf16 v[16:19], v[152:155], v[218:221], v[16:19]
	v_mfma_f32_16x16x32_bf16 v[64:67], v[148:151], v[190:193], v[64:67]
	v_mfma_f32_16x16x32_bf16 v[60:63], v[156:159], v[190:193], v[60:63]
	v_mfma_f32_16x16x32_bf16 v[56:59], v[148:151], v[198:201], v[56:59]
	v_mfma_f32_16x16x32_bf16 v[48:51], v[156:159], v[198:201], v[48:51]
	v_mfma_f32_16x16x32_bf16 v[32:35], v[148:151], v[206:209], v[32:35]
	v_mfma_f32_16x16x32_bf16 v[28:31], v[156:159], v[206:209], v[28:31]
	v_mfma_f32_16x16x32_bf16 v[24:27], v[148:151], v[224:227], v[24:27]
	v_mfma_f32_16x16x32_bf16 v[16:19], v[156:159], v[224:227], v[16:19]
	v_mfma_f32_16x16x32_bf16 v[52:55], v[160:163], v[176:179], v[52:55]
	v_mfma_f32_16x16x32_bf16 v[44:47], v[168:171], v[176:179], v[44:47]
	v_mfma_f32_16x16x32_bf16 v[40:43], v[160:163], v[194:197], v[40:43]
	v_mfma_f32_16x16x32_bf16 v[36:39], v[168:171], v[194:197], v[36:39]
	v_mfma_f32_16x16x32_bf16 v[20:23], v[160:163], v[202:205], v[20:23]
	v_mfma_f32_16x16x32_bf16 v[12:15], v[168:171], v[202:205], v[12:15]
	v_mfma_f32_16x16x32_bf16 v[8:11], v[160:163], v[218:221], v[8:11]
	v_mfma_f32_16x16x32_bf16 v[4:7], v[168:171], v[218:221], v[4:7]
	v_mfma_f32_16x16x32_bf16 v[52:55], v[164:167], v[190:193], v[52:55]
	v_mfma_f32_16x16x32_bf16 v[44:47], v[172:175], v[190:193], v[44:47]
	v_mfma_f32_16x16x32_bf16 v[40:43], v[164:167], v[198:201], v[40:43]
	v_mfma_f32_16x16x32_bf16 v[36:39], v[172:175], v[198:201], v[36:39]
	v_mfma_f32_16x16x32_bf16 v[20:23], v[164:167], v[206:209], v[20:23]
	v_mfma_f32_16x16x32_bf16 v[12:15], v[172:175], v[206:209], v[12:15]
	v_mfma_f32_16x16x32_bf16 v[8:11], v[164:167], v[224:227], v[8:11]
	v_mfma_f32_16x16x32_bf16 v[4:7], v[172:175], v[224:227], v[4:7]
	s_setprio 0
	s_barrier
	s_add_i32 s88, s88, 2
	s_add_u32 s36, s36, 0x100
	s_addc_u32 s37, s37, 0
	s_add_u32 s68, s68, 0x100
	s_addc_u32 s69, s69, 0
	s_cmp_gt_u32 s88, 13
	s_cbranch_scc0 .LBB0_142
	s_and_b64 vcc, exec, s[12:13]
	s_cbranch_vccz .LBB0_145
	s_barrier

.LBB0_181:
	s_add_u32 s25, s10, 0xfffc0080
	s_addc_u32 s40, s11, -1
	s_add_i32 s41, 0, 0x10000
	s_cmp_eq_u32 s68, 12
	s_cselect_b32 s49, s37, s40
	s_cselect_b32 s48, s36, s25
	s_cselect_b32 s47, s19, s65
	s_cselect_b32 s46, s27, s64
	s_add_i32 s25, 0, 0x14000
	v_add_u32_e32 v144, s41, v187
	v_add_u32_e32 v170, s25, v187
	ds_read_b128 v[132:135], v144
	ds_read_b128 v[136:139], v144 offset:1024
	ds_read_b128 v[140:143], v144 offset:2048
	ds_read_b128 v[144:147], v144 offset:3072
	ds_read_b128 v[148:151], v170
	ds_read_b128 v[152:155], v170 offset:1024
	ds_read_b128 v[156:159], v170 offset:2048
	ds_read_b128 v[170:173], v170 offset:3072
	v_lshl_add_u64 v[178:179], s[10:11], 0, v[166:167]
	s_add_i32 m0, s51, 0xc000
	ds_read_b128 v[174:177], v194
	ds_read_b128 v[196:199], v194 offset:1024
	ds_read_b128 v[200:203], v194 offset:2048
	ds_read_b128 v[204:207], v194 offset:3072
	ds_read_b128 v[208:211], v194 offset:4096
	ds_read_b128 v[218:221], v194 offset:5120
	ds_read_b128 v[224:227], v194 offset:6144
	ds_read_b128 v[228:231], v194 offset:7168
	global_load_lds_dwordx4 v[178:179], off
	v_lshl_add_u64 v[178:179], s[10:11], 0, v[168:169]
	s_add_i32 m0, s51, 0xe000
	s_nop 0
	global_load_lds_dwordx4 v[178:179], off
	s_waitcnt vmcnt(8)
	s_waitcnt lgkmcnt(0)
	s_barrier
	s_setprio 1
	s_waitcnt lgkmcnt(0)
	v_mfma_f32_16x16x32_bf16 v[128:131], v[132:135], v[174:177], v[128:131]
	v_mfma_f32_16x16x32_bf16 v[124:127], v[140:143], v[174:177], v[124:127]
	v_mfma_f32_16x16x32_bf16 v[112:115], v[132:135], v[200:203], v[112:115]
	v_mfma_f32_16x16x32_bf16 v[108:111], v[140:143], v[200:203], v[108:111]
	v_mfma_f32_16x16x32_bf16 v[96:99], v[132:135], v[208:211], v[96:99]
	v_mfma_f32_16x16x32_bf16 v[92:95], v[140:143], v[208:211], v[92:95]
	v_mfma_f32_16x16x32_bf16 v[80:83], v[132:135], v[224:227], v[80:83]
	v_mfma_f32_16x16x32_bf16 v[76:79], v[140:143], v[224:227], v[76:79]
	v_mfma_f32_16x16x32_bf16 v[128:131], v[136:139], v[196:199], v[128:131]
	v_mfma_f32_16x16x32_bf16 v[124:127], v[144:147], v[196:199], v[124:127]
	v_mfma_f32_16x16x32_bf16 v[112:115], v[136:139], v[204:207], v[112:115]
	v_mfma_f32_16x16x32_bf16 v[108:111], v[144:147], v[204:207], v[108:111]
	v_mfma_f32_16x16x32_bf16 v[96:99], v[136:139], v[218:221], v[96:99]
	v_mfma_f32_16x16x32_bf16 v[92:95], v[144:147], v[218:221], v[92:95]
	v_mfma_f32_16x16x32_bf16 v[80:83], v[136:139], v[228:231], v[80:83]
	v_mfma_f32_16x16x32_bf16 v[76:79], v[144:147], v[228:231], v[76:79]
	v_mfma_f32_16x16x32_bf16 v[120:123], v[148:151], v[174:177], v[120:123]
	v_mfma_f32_16x16x32_bf16 v[116:119], v[156:159], v[174:177], v[116:119]
	v_mfma_f32_16x16x32_bf16 v[104:107], v[148:151], v[200:203], v[104:107]
	v_mfma_f32_16x16x32_bf16 v[100:103], v[156:159], v[200:203], v[100:103]
	v_mfma_f32_16x16x32_bf16 v[88:91], v[148:151], v[208:211], v[88:91]
	v_mfma_f32_16x16x32_bf16 v[84:87], v[156:159], v[208:211], v[84:87]
	v_mfma_f32_16x16x32_bf16 v[72:75], v[148:151], v[224:227], v[72:75]
	v_mfma_f32_16x16x32_bf16 v[68:71], v[156:159], v[224:227], v[68:71]
	v_mfma_f32_16x16x32_bf16 v[120:123], v[152:155], v[196:199], v[120:123]
	v_mfma_f32_16x16x32_bf16 v[116:119], v[170:173], v[196:199], v[116:119]
	v_mfma_f32_16x16x32_bf16 v[104:107], v[152:155], v[204:207], v[104:107]
	v_mfma_f32_16x16x32_bf16 v[100:103], v[170:173], v[204:207], v[100:103]
	v_mfma_f32_16x16x32_bf16 v[88:91], v[152:155], v[218:221], v[88:91]
	v_mfma_f32_16x16x32_bf16 v[84:87], v[170:173], v[218:221], v[84:87]
	v_mfma_f32_16x16x32_bf16 v[72:75], v[152:155], v[228:231], v[72:75]
	v_mfma_f32_16x16x32_bf16 v[68:71], v[170:173], v[228:231], v[68:71]
	s_setprio 0
	s_barrier
	s_add_i32 s40, s41, s50
	v_lshl_add_u64 v[178:179], s[46:47], 0, v[162:163]
	s_mov_b32 m0, s40
	ds_read_b128 v[174:177], v194 offset:16384
	ds_read_b128 v[196:199], v194 offset:17408
	ds_read_b128 v[200:203], v194 offset:18432
	ds_read_b128 v[204:207], v194 offset:19456
	ds_read_b128 v[208:211], v194 offset:20480
	ds_read_b128 v[218:221], v194 offset:21504
	ds_read_b128 v[224:227], v194 offset:22528
	ds_read_b128 v[228:231], v194 offset:23552
	global_load_lds_dwordx4 v[178:179], off
	s_add_i32 m0, s40, 0x2000
	s_add_u32 s40, s46, 0x40000
	v_lshl_add_u64 v[182:183], s[46:47], 0, v[0:1]
	s_addc_u32 s41, s47, 0
	s_add_i32 s25, s25, s50
	global_load_lds_dwordx4 v[182:183], off
	v_lshl_add_u64 v[184:185], s[40:41], 0, v[162:163]
	s_mov_b32 m0, s25
	v_lshl_add_u64 v[190:191], s[48:49], 0, v[160:161]
	global_load_lds_dwordx4 v[184:185], off
	v_lshl_add_u64 v[184:185], s[40:41], 0, v[0:1]
	s_add_i32 m0, s25, 0x2000
	s_nop 0
	global_load_lds_dwordx4 v[184:185], off
	v_lshl_add_u64 v[184:185], s[48:49], 0, v[164:165]
	s_mov_b32 m0, s51
	s_nop 0
	global_load_lds_dwordx4 v[184:185], off
	s_mov_b32 m0, s52
	s_nop 0
	global_load_lds_dwordx4 v[190:191], off
	s_waitcnt vmcnt(8)
	s_waitcnt lgkmcnt(0)
	s_barrier
	s_setprio 1
	s_waitcnt lgkmcnt(0)
	v_mfma_f32_16x16x32_bf16 v[64:67], v[132:135], v[174:177], v[64:67]
	v_mfma_f32_16x16x32_bf16 v[60:63], v[140:143], v[174:177], v[60:63]
	v_mfma_f32_16x16x32_bf16 v[48:51], v[132:135], v[200:203], v[48:51]
	v_mfma_f32_16x16x32_bf16 v[44:47], v[140:143], v[200:203], v[44:47]
	v_mfma_f32_16x16x32_bf16 v[32:35], v[132:135], v[208:211], v[32:35]
	v_mfma_f32_16x16x32_bf16 v[28:31], v[140:143], v[208:211], v[28:31]
	v_mfma_f32_16x16x32_bf16 v[16:19], v[132:135], v[224:227], v[16:19]
	v_mfma_f32_16x16x32_bf16 v[12:15], v[140:143], v[224:227], v[12:15]
	v_mfma_f32_16x16x32_bf16 v[64:67], v[136:139], v[196:199], v[64:67]
	v_mfma_f32_16x16x32_bf16 v[60:63], v[144:147], v[196:199], v[60:63]
	v_mfma_f32_16x16x32_bf16 v[48:51], v[136:139], v[204:207], v[48:51]
	v_mfma_f32_16x16x32_bf16 v[44:47], v[144:147], v[204:207], v[44:47]
	v_mfma_f32_16x16x32_bf16 v[32:35], v[136:139], v[218:221], v[32:35]
	v_mfma_f32_16x16x32_bf16 v[28:31], v[144:147], v[218:221], v[28:31]
	v_mfma_f32_16x16x32_bf16 v[16:19], v[136:139], v[228:231], v[16:19]
	v_mfma_f32_16x16x32_bf16 v[12:15], v[144:147], v[228:231], v[12:15]
	v_mfma_f32_16x16x32_bf16 v[56:59], v[148:151], v[174:177], v[56:59]
	v_mfma_f32_16x16x32_bf16 v[52:55], v[156:159], v[174:177], v[52:55]
	v_mfma_f32_16x16x32_bf16 v[40:43], v[148:151], v[200:203], v[40:43]
	v_mfma_f32_16x16x32_bf16 v[36:39], v[156:159], v[200:203], v[36:39]
	v_mfma_f32_16x16x32_bf16 v[24:27], v[148:151], v[208:211], v[24:27]
	v_mfma_f32_16x16x32_bf16 v[20:23], v[156:159], v[208:211], v[20:23]
	v_mfma_f32_16x16x32_bf16 v[8:11], v[148:151], v[224:227], v[8:11]
	v_mfma_f32_16x16x32_bf16 v[4:7], v[156:159], v[224:227], v[4:7]
	v_mfma_f32_16x16x32_bf16 v[56:59], v[152:155], v[196:199], v[56:59]
	v_mfma_f32_16x16x32_bf16 v[52:55], v[170:173], v[196:199], v[52:55]
	v_mfma_f32_16x16x32_bf16 v[40:43], v[152:155], v[204:207], v[40:43]
	v_mfma_f32_16x16x32_bf16 v[36:39], v[170:173], v[204:207], v[36:39]
	v_mfma_f32_16x16x32_bf16 v[24:27], v[152:155], v[218:221], v[24:27]
	v_mfma_f32_16x16x32_bf16 v[20:23], v[170:173], v[218:221], v[20:23]
	v_mfma_f32_16x16x32_bf16 v[8:11], v[152:155], v[228:231], v[8:11]
	v_mfma_f32_16x16x32_bf16 v[4:7], v[170:173], v[228:231], v[4:7]
	s_setprio 0
	s_barrier
	s_add_i32 s25, 0, 0x18000
	s_add_i32 s69, 0, 0x1c000
	v_add_u32_e32 v144, s25, v187
	v_add_u32_e32 v170, s69, v187
	ds_read_b128 v[132:135], v144
	ds_read_b128 v[136:139], v144 offset:1024
	ds_read_b128 v[140:143], v144 offset:2048
	ds_read_b128 v[144:147], v144 offset:3072
	ds_read_b128 v[148:151], v170
	ds_read_b128 v[152:155], v170 offset:1024
	ds_read_b128 v[156:159], v170 offset:2048
	ds_read_b128 v[170:173], v170 offset:3072
	s_add_u32 s40, s48, 0x40000
	s_addc_u32 s41, s49, 0
	s_mov_b32 m0, s53
	v_lshl_add_u64 v[232:233], s[40:41], 0, v[164:165]
	ds_read_b128 v[174:177], v194 offset:32768
	ds_read_b128 v[196:199], v194 offset:33792
	ds_read_b128 v[200:203], v194 offset:34816
	ds_read_b128 v[204:207], v194 offset:35840
	ds_read_b128 v[208:211], v194 offset:36864
	ds_read_b128 v[218:221], v194 offset:37888
	ds_read_b128 v[224:227], v194 offset:38912
	ds_read_b128 v[228:231], v194 offset:39936
	global_load_lds_dwordx4 v[232:233], off
	v_lshl_add_u64 v[232:233], s[40:41], 0, v[160:161]
	s_mov_b32 m0, s54
	s_nop 0
	global_load_lds_dwordx4 v[232:233], off
	s_waitcnt vmcnt(8)
	s_waitcnt lgkmcnt(0)
	s_barrier
	s_setprio 1
	s_waitcnt lgkmcnt(0)
	v_mfma_f32_16x16x32_bf16 v[128:131], v[132:135], v[174:177], v[128:131]
	v_mfma_f32_16x16x32_bf16 v[124:127], v[140:143], v[174:177], v[124:127]
	v_mfma_f32_16x16x32_bf16 v[112:115], v[132:135], v[200:203], v[112:115]
	v_mfma_f32_16x16x32_bf16 v[108:111], v[140:143], v[200:203], v[108:111]
	v_mfma_f32_16x16x32_bf16 v[96:99], v[132:135], v[208:211], v[96:99]
	v_mfma_f32_16x16x32_bf16 v[92:95], v[140:143], v[208:211], v[92:95]
	v_mfma_f32_16x16x32_bf16 v[80:83], v[132:135], v[224:227], v[80:83]
	v_mfma_f32_16x16x32_bf16 v[76:79], v[140:143], v[224:227], v[76:79]
	v_mfma_f32_16x16x32_bf16 v[128:131], v[136:139], v[196:199], v[128:131]
	v_mfma_f32_16x16x32_bf16 v[124:127], v[144:147], v[196:199], v[124:127]
	v_mfma_f32_16x16x32_bf16 v[112:115], v[136:139], v[204:207], v[112:115]
	v_mfma_f32_16x16x32_bf16 v[108:111], v[144:147], v[204:207], v[108:111]
	v_mfma_f32_16x16x32_bf16 v[96:99], v[136:139], v[218:221], v[96:99]
	v_mfma_f32_16x16x32_bf16 v[92:95], v[144:147], v[218:221], v[92:95]
	v_mfma_f32_16x16x32_bf16 v[80:83], v[136:139], v[228:231], v[80:83]
	v_mfma_f32_16x16x32_bf16 v[76:79], v[144:147], v[228:231], v[76:79]
	v_mfma_f32_16x16x32_bf16 v[120:123], v[148:151], v[174:177], v[120:123]
	v_mfma_f32_16x16x32_bf16 v[116:119], v[156:159], v[174:177], v[116:119]
	v_mfma_f32_16x16x32_bf16 v[104:107], v[148:151], v[200:203], v[104:107]
	v_mfma_f32_16x16x32_bf16 v[100:103], v[156:159], v[200:203], v[100:103]
	v_mfma_f32_16x16x32_bf16 v[88:91], v[148:151], v[208:211], v[88:91]
	v_mfma_f32_16x16x32_bf16 v[84:87], v[156:159], v[208:211], v[84:87]
	v_mfma_f32_16x16x32_bf16 v[72:75], v[148:151], v[224:227], v[72:75]
	v_mfma_f32_16x16x32_bf16 v[68:71], v[156:159], v[224:227], v[68:71]
	v_mfma_f32_16x16x32_bf16 v[120:123], v[152:155], v[196:199], v[120:123]
	v_mfma_f32_16x16x32_bf16 v[116:119], v[170:173], v[196:199], v[116:119]
	v_mfma_f32_16x16x32_bf16 v[104:107], v[152:155], v[204:207], v[104:107]
	v_mfma_f32_16x16x32_bf16 v[100:103], v[170:173], v[204:207], v[100:103]
	v_mfma_f32_16x16x32_bf16 v[88:91], v[152:155], v[218:221], v[88:91]
	v_mfma_f32_16x16x32_bf16 v[84:87], v[170:173], v[218:221], v[84:87]
	v_mfma_f32_16x16x32_bf16 v[72:75], v[152:155], v[228:231], v[72:75]
	v_mfma_f32_16x16x32_bf16 v[68:71], v[170:173], v[228:231], v[68:71]
	s_setprio 0
	s_barrier
	s_add_i32 s25, s25, s50
	v_lshl_add_u64 v[178:179], v[178:179], 0, s[94:95]
	s_mov_b32 m0, s25
	ds_read_b128 v[174:177], v194 offset:49152
	ds_read_b128 v[196:199], v194 offset:50176
	ds_read_b128 v[200:203], v194 offset:51200
	ds_read_b128 v[204:207], v194 offset:52224
	ds_read_b128 v[208:211], v194 offset:53248
	ds_read_b128 v[218:221], v194 offset:54272
	ds_read_b128 v[224:227], v194 offset:55296
	ds_read_b128 v[228:231], v194 offset:56320
	global_load_lds_dwordx4 v[178:179], off
	s_add_i32 m0, s25, 0x2000
	s_add_u32 s40, s46, 0x40080
	v_lshl_add_u64 v[178:179], v[182:183], 0, s[94:95]
	s_addc_u32 s41, s47, 0
	s_add_i32 s25, s69, s50
	global_load_lds_dwordx4 v[178:179], off
	v_lshl_add_u64 v[178:179], s[40:41], 0, v[162:163]
	s_mov_b32 m0, s25
	s_nop 0
	global_load_lds_dwordx4 v[178:179], off
	v_lshl_add_u64 v[178:179], s[40:41], 0, v[0:1]
	s_add_i32 m0, s25, 0x2000
	s_nop 0
	global_load_lds_dwordx4 v[178:179], off
	v_lshl_add_u64 v[178:179], v[184:185], 0, s[94:95]
	s_mov_b32 m0, s55
	s_nop 0
	global_load_lds_dwordx4 v[178:179], off
	v_lshl_add_u64 v[178:179], v[190:191], 0, s[94:95]
	s_mov_b32 m0, s58
	s_nop 0
	global_load_lds_dwordx4 v[178:179], off
	s_waitcnt vmcnt(8)
	s_waitcnt lgkmcnt(0)
	s_barrier
	s_setprio 1
	s_waitcnt lgkmcnt(0)
	v_mfma_f32_16x16x32_bf16 v[64:67], v[132:135], v[174:177], v[64:67]
	v_mfma_f32_16x16x32_bf16 v[60:63], v[140:143], v[174:177], v[60:63]
	v_mfma_f32_16x16x32_bf16 v[48:51], v[132:135], v[200:203], v[48:51]
	v_mfma_f32_16x16x32_bf16 v[44:47], v[140:143], v[200:203], v[44:47]
	v_mfma_f32_16x16x32_bf16 v[32:35], v[132:135], v[208:211], v[32:35]
	v_mfma_f32_16x16x32_bf16 v[28:31], v[140:143], v[208:211], v[28:31]
	v_mfma_f32_16x16x32_bf16 v[16:19], v[132:135], v[224:227], v[16:19]
	v_mfma_f32_16x16x32_bf16 v[12:15], v[140:143], v[224:227], v[12:15]
	v_mfma_f32_16x16x32_bf16 v[64:67], v[136:139], v[196:199], v[64:67]
	v_mfma_f32_16x16x32_bf16 v[60:63], v[144:147], v[196:199], v[60:63]
	v_mfma_f32_16x16x32_bf16 v[48:51], v[136:139], v[204:207], v[48:51]
	v_mfma_f32_16x16x32_bf16 v[44:47], v[144:147], v[204:207], v[44:47]
	v_mfma_f32_16x16x32_bf16 v[32:35], v[136:139], v[218:221], v[32:35]
	v_mfma_f32_16x16x32_bf16 v[28:31], v[144:147], v[218:221], v[28:31]
	v_mfma_f32_16x16x32_bf16 v[16:19], v[136:139], v[228:231], v[16:19]
	v_mfma_f32_16x16x32_bf16 v[12:15], v[144:147], v[228:231], v[12:15]
	v_mfma_f32_16x16x32_bf16 v[56:59], v[148:151], v[174:177], v[56:59]
	v_mfma_f32_16x16x32_bf16 v[52:55], v[156:159], v[174:177], v[52:55]
	v_mfma_f32_16x16x32_bf16 v[40:43], v[148:151], v[200:203], v[40:43]
	v_mfma_f32_16x16x32_bf16 v[36:39], v[156:159], v[200:203], v[36:39]
	v_mfma_f32_16x16x32_bf16 v[24:27], v[148:151], v[208:211], v[24:27]
	v_mfma_f32_16x16x32_bf16 v[20:23], v[156:159], v[208:211], v[20:23]
	v_mfma_f32_16x16x32_bf16 v[8:11], v[148:151], v[224:227], v[8:11]
	v_mfma_f32_16x16x32_bf16 v[4:7], v[156:159], v[224:227], v[4:7]
	v_mfma_f32_16x16x32_bf16 v[56:59], v[152:155], v[196:199], v[56:59]
	v_mfma_f32_16x16x32_bf16 v[52:55], v[170:173], v[196:199], v[52:55]
	v_mfma_f32_16x16x32_bf16 v[40:43], v[152:155], v[204:207], v[40:43]
	v_mfma_f32_16x16x32_bf16 v[36:39], v[170:173], v[204:207], v[36:39]
	v_mfma_f32_16x16x32_bf16 v[24:27], v[152:155], v[218:221], v[24:27]
	v_mfma_f32_16x16x32_bf16 v[20:23], v[170:173], v[218:221], v[20:23]
	v_mfma_f32_16x16x32_bf16 v[8:11], v[152:155], v[228:231], v[8:11]
	v_mfma_f32_16x16x32_bf16 v[4:7], v[170:173], v[228:231], v[4:7]
	s_setprio 0
	s_barrier
	s_add_i32 s68, s68, 2
	s_add_u32 s10, s10, 0x100
	s_addc_u32 s11, s11, 0
	s_add_u32 s64, s64, 0x100
	s_addc_u32 s65, s65, 0
	s_cmp_gt_u32 s68, 13
	s_cbranch_scc0 .LBB0_181
	s_and_b64 vcc, exec, s[14:15]
	s_cbranch_vccz .LBB0_184
	s_barrier

.LBB0_231:
	s_add_u32 s12, s10, 0xfffc0080
	s_addc_u32 s13, s11, -1
	s_add_i32 s25, 0, 0x10000
	s_cmp_eq_u32 s97, 12
	s_cselect_b32 s47, s27, s13
	s_cselect_b32 s46, s69, s12
	s_cselect_b32 s13, s19, s90
	s_cselect_b32 s12, s88, s89
	s_add_i32 s50, 0, 0x14000
	v_add_u32_e32 v144, s25, v159
	v_add_u32_e32 v158, s50, v159
	ds_read_b128 v[132:135], v144
	ds_read_b128 v[136:139], v144 offset:1024
	ds_read_b128 v[140:143], v144 offset:2048
	ds_read_b128 v[144:147], v144 offset:3072
	ds_read_b128 v[190:193], v158
	ds_read_b128 v[194:197], v158 offset:1024
	ds_read_b128 v[198:201], v158 offset:2048
	ds_read_b128 v[202:205], v158 offset:3072
	v_lshl_add_u64 v[174:175], s[10:11], 0, v[154:155]
	s_add_i32 m0, s49, 0xc000
	ds_read_b128 v[206:209], v179
	ds_read_b128 v[218:221], v179 offset:1024
	ds_read_b128 v[224:227], v179 offset:2048
	ds_read_b128 v[228:231], v179 offset:3072
	ds_read_b128 v[232:235], v179 offset:4096
	ds_read_b128 v[236:239], v179 offset:5120
	ds_read_b128 v[240:243], v179 offset:6144
	ds_read_b128 v[244:247], v179 offset:7168
	global_load_lds_dwordx4 v[174:175], off
	v_lshl_add_u64 v[174:175], s[10:11], 0, v[156:157]
	s_add_i32 m0, s49, 0xe000
	s_nop 0
	global_load_lds_dwordx4 v[174:175], off
	s_waitcnt vmcnt(8)
	s_waitcnt lgkmcnt(0)
	s_barrier
	s_setprio 1
	s_waitcnt lgkmcnt(0)
	v_mfma_f32_16x16x32_bf16 v[128:131], v[132:135], v[206:209], v[128:131]
	v_mfma_f32_16x16x32_bf16 v[124:127], v[140:143], v[206:209], v[124:127]
	v_mfma_f32_16x16x32_bf16 v[112:115], v[132:135], v[224:227], v[112:115]
	v_mfma_f32_16x16x32_bf16 v[108:111], v[140:143], v[224:227], v[108:111]
	v_mfma_f32_16x16x32_bf16 v[96:99], v[132:135], v[232:235], v[96:99]
	v_mfma_f32_16x16x32_bf16 v[92:95], v[140:143], v[232:235], v[92:95]
	v_mfma_f32_16x16x32_bf16 v[80:83], v[132:135], v[240:243], v[80:83]
	v_mfma_f32_16x16x32_bf16 v[76:79], v[140:143], v[240:243], v[76:79]
	v_mfma_f32_16x16x32_bf16 v[128:131], v[136:139], v[218:221], v[128:131]
	v_mfma_f32_16x16x32_bf16 v[124:127], v[144:147], v[218:221], v[124:127]
	v_mfma_f32_16x16x32_bf16 v[112:115], v[136:139], v[228:231], v[112:115]
	v_mfma_f32_16x16x32_bf16 v[108:111], v[144:147], v[228:231], v[108:111]
	v_mfma_f32_16x16x32_bf16 v[96:99], v[136:139], v[236:239], v[96:99]
	v_mfma_f32_16x16x32_bf16 v[92:95], v[144:147], v[236:239], v[92:95]
	v_mfma_f32_16x16x32_bf16 v[80:83], v[136:139], v[244:247], v[80:83]
	v_mfma_f32_16x16x32_bf16 v[76:79], v[144:147], v[244:247], v[76:79]
	v_mfma_f32_16x16x32_bf16 v[120:123], v[190:193], v[206:209], v[120:123]
	v_mfma_f32_16x16x32_bf16 v[116:119], v[198:201], v[206:209], v[116:119]
	v_mfma_f32_16x16x32_bf16 v[104:107], v[190:193], v[224:227], v[104:107]
	v_mfma_f32_16x16x32_bf16 v[100:103], v[198:201], v[224:227], v[100:103]
	v_mfma_f32_16x16x32_bf16 v[88:91], v[190:193], v[232:235], v[88:91]
	v_mfma_f32_16x16x32_bf16 v[84:87], v[198:201], v[232:235], v[84:87]
	v_mfma_f32_16x16x32_bf16 v[72:75], v[190:193], v[240:243], v[72:75]
	v_mfma_f32_16x16x32_bf16 v[68:71], v[198:201], v[240:243], v[68:71]
	v_mfma_f32_16x16x32_bf16 v[120:123], v[194:197], v[218:221], v[120:123]
	v_mfma_f32_16x16x32_bf16 v[116:119], v[202:205], v[218:221], v[116:119]
	v_mfma_f32_16x16x32_bf16 v[104:107], v[194:197], v[228:231], v[104:107]
	v_mfma_f32_16x16x32_bf16 v[100:103], v[202:205], v[228:231], v[100:103]
	v_mfma_f32_16x16x32_bf16 v[88:91], v[194:197], v[236:239], v[88:91]
	v_mfma_f32_16x16x32_bf16 v[84:87], v[202:205], v[236:239], v[84:87]
	v_mfma_f32_16x16x32_bf16 v[72:75], v[194:197], v[244:247], v[72:75]
	v_mfma_f32_16x16x32_bf16 v[68:71], v[202:205], v[244:247], v[68:71]
	s_setprio 0
	s_barrier
	s_add_i32 s25, s25, s48
	v_lshl_add_u64 v[174:175], s[12:13], 0, v[180:181]
	s_mov_b32 m0, s25
	ds_read_b128 v[206:209], v179 offset:16384
	ds_read_b128 v[218:221], v179 offset:17408
	ds_read_b128 v[224:227], v179 offset:18432
	ds_read_b128 v[228:231], v179 offset:19456
	ds_read_b128 v[232:235], v179 offset:20480
	ds_read_b128 v[236:239], v179 offset:21504
	ds_read_b128 v[240:243], v179 offset:22528
	ds_read_b128 v[244:247], v179 offset:23552
	global_load_lds_dwordx4 v[174:175], off
	s_add_i32 m0, s25, 0x2000
	s_add_u32 s40, s12, 0x40000
	v_lshl_add_u64 v[182:183], s[12:13], 0, v[150:151]
	s_addc_u32 s41, s13, 0
	s_add_i32 s25, s50, s48
	global_load_lds_dwordx4 v[182:183], off
	v_lshl_add_u64 v[184:185], s[40:41], 0, v[180:181]
	s_mov_b32 m0, s25
	v_lshl_add_u64 v[210:211], s[46:47], 0, v[148:149]
	global_load_lds_dwordx4 v[184:185], off
	v_lshl_add_u64 v[184:185], s[40:41], 0, v[150:151]
	s_add_i32 m0, s25, 0x2000
	s_nop 0
	global_load_lds_dwordx4 v[184:185], off
	v_lshl_add_u64 v[184:185], s[46:47], 0, v[0:1]
	s_mov_b32 m0, s49
	s_nop 0
	global_load_lds_dwordx4 v[184:185], off
	s_mov_b32 m0, s52
	s_nop 0
	global_load_lds_dwordx4 v[210:211], off
	s_waitcnt vmcnt(8)
	s_waitcnt lgkmcnt(0)
	s_barrier
	s_setprio 1
	s_waitcnt lgkmcnt(0)
	v_mfma_f32_16x16x32_bf16 v[64:67], v[132:135], v[206:209], v[64:67]
	v_mfma_f32_16x16x32_bf16 v[60:63], v[140:143], v[206:209], v[60:63]
	v_mfma_f32_16x16x32_bf16 v[48:51], v[132:135], v[224:227], v[48:51]
	v_mfma_f32_16x16x32_bf16 v[44:47], v[140:143], v[224:227], v[44:47]
	v_mfma_f32_16x16x32_bf16 v[32:35], v[132:135], v[232:235], v[32:35]
	v_mfma_f32_16x16x32_bf16 v[28:31], v[140:143], v[232:235], v[28:31]
	v_mfma_f32_16x16x32_bf16 v[16:19], v[132:135], v[240:243], v[16:19]
	v_mfma_f32_16x16x32_bf16 v[12:15], v[140:143], v[240:243], v[12:15]
	v_mfma_f32_16x16x32_bf16 v[64:67], v[136:139], v[218:221], v[64:67]
	v_mfma_f32_16x16x32_bf16 v[60:63], v[144:147], v[218:221], v[60:63]
	v_mfma_f32_16x16x32_bf16 v[48:51], v[136:139], v[228:231], v[48:51]
	v_mfma_f32_16x16x32_bf16 v[44:47], v[144:147], v[228:231], v[44:47]
	v_mfma_f32_16x16x32_bf16 v[32:35], v[136:139], v[236:239], v[32:35]
	v_mfma_f32_16x16x32_bf16 v[28:31], v[144:147], v[236:239], v[28:31]
	v_mfma_f32_16x16x32_bf16 v[16:19], v[136:139], v[244:247], v[16:19]
	v_mfma_f32_16x16x32_bf16 v[12:15], v[144:147], v[244:247], v[12:15]
	v_mfma_f32_16x16x32_bf16 v[56:59], v[190:193], v[206:209], v[56:59]
	v_mfma_f32_16x16x32_bf16 v[52:55], v[198:201], v[206:209], v[52:55]
	v_mfma_f32_16x16x32_bf16 v[40:43], v[190:193], v[224:227], v[40:43]
	v_mfma_f32_16x16x32_bf16 v[36:39], v[198:201], v[224:227], v[36:39]
	v_mfma_f32_16x16x32_bf16 v[24:27], v[190:193], v[232:235], v[24:27]
	v_mfma_f32_16x16x32_bf16 v[20:23], v[198:201], v[232:235], v[20:23]
	v_mfma_f32_16x16x32_bf16 v[8:11], v[190:193], v[240:243], v[8:11]
	v_mfma_f32_16x16x32_bf16 v[4:7], v[198:201], v[240:243], v[4:7]
	v_mfma_f32_16x16x32_bf16 v[56:59], v[194:197], v[218:221], v[56:59]
	v_mfma_f32_16x16x32_bf16 v[52:55], v[202:205], v[218:221], v[52:55]
	v_mfma_f32_16x16x32_bf16 v[40:43], v[194:197], v[228:231], v[40:43]
	v_mfma_f32_16x16x32_bf16 v[36:39], v[202:205], v[228:231], v[36:39]
	v_mfma_f32_16x16x32_bf16 v[24:27], v[194:197], v[236:239], v[24:27]
	v_mfma_f32_16x16x32_bf16 v[20:23], v[202:205], v[236:239], v[20:23]
	v_mfma_f32_16x16x32_bf16 v[8:11], v[194:197], v[244:247], v[8:11]
	v_mfma_f32_16x16x32_bf16 v[4:7], v[202:205], v[244:247], v[4:7]
	s_setprio 0
	s_barrier
	s_add_i32 s25, 0, 0x18000
	s_add_i32 s50, 0, 0x1c000
	v_add_u32_e32 v144, s25, v159
	v_add_u32_e32 v158, s50, v159
	ds_read_b128 v[132:135], v144
	ds_read_b128 v[136:139], v144 offset:1024
	ds_read_b128 v[140:143], v144 offset:2048
	ds_read_b128 v[144:147], v144 offset:3072
	ds_read_b128 v[190:193], v158
	ds_read_b128 v[194:197], v158 offset:1024
	ds_read_b128 v[198:201], v158 offset:2048
	ds_read_b128 v[202:205], v158 offset:3072
	s_add_u32 s40, s46, 0x40000
	s_addc_u32 s41, s47, 0
	s_mov_b32 m0, s53
	v_lshl_add_u64 v[248:249], s[40:41], 0, v[0:1]
	ds_read_b128 v[206:209], v179 offset:32768
	ds_read_b128 v[218:221], v179 offset:33792
	ds_read_b128 v[224:227], v179 offset:34816
	ds_read_b128 v[228:231], v179 offset:35840
	ds_read_b128 v[232:235], v179 offset:36864
	ds_read_b128 v[236:239], v179 offset:37888
	ds_read_b128 v[240:243], v179 offset:38912
	ds_read_b128 v[244:247], v179 offset:39936
	global_load_lds_dwordx4 v[248:249], off
	v_lshl_add_u64 v[248:249], s[40:41], 0, v[148:149]
	s_mov_b32 m0, s54
	s_nop 0
	global_load_lds_dwordx4 v[248:249], off
	s_waitcnt vmcnt(8)
	s_waitcnt lgkmcnt(0)
	s_barrier
	s_setprio 1
	s_waitcnt lgkmcnt(0)
	v_mfma_f32_16x16x32_bf16 v[128:131], v[132:135], v[206:209], v[128:131]
	v_mfma_f32_16x16x32_bf16 v[124:127], v[140:143], v[206:209], v[124:127]
	v_mfma_f32_16x16x32_bf16 v[112:115], v[132:135], v[224:227], v[112:115]
	v_mfma_f32_16x16x32_bf16 v[108:111], v[140:143], v[224:227], v[108:111]
	v_mfma_f32_16x16x32_bf16 v[96:99], v[132:135], v[232:235], v[96:99]
	v_mfma_f32_16x16x32_bf16 v[92:95], v[140:143], v[232:235], v[92:95]
	v_mfma_f32_16x16x32_bf16 v[80:83], v[132:135], v[240:243], v[80:83]
	v_mfma_f32_16x16x32_bf16 v[76:79], v[140:143], v[240:243], v[76:79]
	v_mfma_f32_16x16x32_bf16 v[128:131], v[136:139], v[218:221], v[128:131]
	v_mfma_f32_16x16x32_bf16 v[124:127], v[144:147], v[218:221], v[124:127]
	v_mfma_f32_16x16x32_bf16 v[112:115], v[136:139], v[228:231], v[112:115]
	v_mfma_f32_16x16x32_bf16 v[108:111], v[144:147], v[228:231], v[108:111]
	v_mfma_f32_16x16x32_bf16 v[96:99], v[136:139], v[236:239], v[96:99]
	v_mfma_f32_16x16x32_bf16 v[92:95], v[144:147], v[236:239], v[92:95]
	v_mfma_f32_16x16x32_bf16 v[80:83], v[136:139], v[244:247], v[80:83]
	v_mfma_f32_16x16x32_bf16 v[76:79], v[144:147], v[244:247], v[76:79]
	v_mfma_f32_16x16x32_bf16 v[120:123], v[190:193], v[206:209], v[120:123]
	v_mfma_f32_16x16x32_bf16 v[116:119], v[198:201], v[206:209], v[116:119]
	v_mfma_f32_16x16x32_bf16 v[104:107], v[190:193], v[224:227], v[104:107]
	v_mfma_f32_16x16x32_bf16 v[100:103], v[198:201], v[224:227], v[100:103]
	v_mfma_f32_16x16x32_bf16 v[88:91], v[190:193], v[232:235], v[88:91]
	v_mfma_f32_16x16x32_bf16 v[84:87], v[198:201], v[232:235], v[84:87]
	v_mfma_f32_16x16x32_bf16 v[72:75], v[190:193], v[240:243], v[72:75]
	v_mfma_f32_16x16x32_bf16 v[68:71], v[198:201], v[240:243], v[68:71]
	v_mfma_f32_16x16x32_bf16 v[120:123], v[194:197], v[218:221], v[120:123]
	v_mfma_f32_16x16x32_bf16 v[116:119], v[202:205], v[218:221], v[116:119]
	v_mfma_f32_16x16x32_bf16 v[104:107], v[194:197], v[228:231], v[104:107]
	v_mfma_f32_16x16x32_bf16 v[100:103], v[202:205], v[228:231], v[100:103]
	v_mfma_f32_16x16x32_bf16 v[88:91], v[194:197], v[236:239], v[88:91]
	v_mfma_f32_16x16x32_bf16 v[84:87], v[202:205], v[236:239], v[84:87]
	v_mfma_f32_16x16x32_bf16 v[72:75], v[194:197], v[244:247], v[72:75]
	v_mfma_f32_16x16x32_bf16 v[68:71], v[202:205], v[244:247], v[68:71]
	s_setprio 0
	s_barrier
	s_add_i32 s25, s25, s48
	v_lshl_add_u64 v[174:175], v[174:175], 0, s[94:95]
	s_mov_b32 m0, s25
	ds_read_b128 v[206:209], v179 offset:49152
	ds_read_b128 v[218:221], v179 offset:50176
	ds_read_b128 v[224:227], v179 offset:51200
	ds_read_b128 v[228:231], v179 offset:52224
	ds_read_b128 v[232:235], v179 offset:53248
	ds_read_b128 v[236:239], v179 offset:54272
	ds_read_b128 v[240:243], v179 offset:55296
	ds_read_b128 v[244:247], v179 offset:56320
	global_load_lds_dwordx4 v[174:175], off
	s_add_i32 m0, s25, 0x2000
	s_add_u32 s12, s12, 0x40080
	v_lshl_add_u64 v[174:175], v[182:183], 0, s[94:95]
	s_addc_u32 s13, s13, 0
	s_add_i32 s25, s50, s48
	global_load_lds_dwordx4 v[174:175], off
	v_lshl_add_u64 v[174:175], s[12:13], 0, v[180:181]
	s_mov_b32 m0, s25
	s_nop 0
	global_load_lds_dwordx4 v[174:175], off
	v_lshl_add_u64 v[174:175], s[12:13], 0, v[150:151]
	s_add_i32 m0, s25, 0x2000
	s_nop 0
	global_load_lds_dwordx4 v[174:175], off
	v_lshl_add_u64 v[174:175], v[184:185], 0, s[94:95]
	s_mov_b32 m0, s55
	s_nop 0
	global_load_lds_dwordx4 v[174:175], off
	v_lshl_add_u64 v[174:175], v[210:211], 0, s[94:95]
	s_mov_b32 m0, s58
	s_nop 0
	global_load_lds_dwordx4 v[174:175], off
	s_waitcnt vmcnt(8)
	s_waitcnt lgkmcnt(0)
	s_barrier
	s_setprio 1
	s_waitcnt lgkmcnt(0)
	v_mfma_f32_16x16x32_bf16 v[64:67], v[132:135], v[206:209], v[64:67]
	v_mfma_f32_16x16x32_bf16 v[60:63], v[140:143], v[206:209], v[60:63]
	v_mfma_f32_16x16x32_bf16 v[48:51], v[132:135], v[224:227], v[48:51]
	v_mfma_f32_16x16x32_bf16 v[44:47], v[140:143], v[224:227], v[44:47]
	v_mfma_f32_16x16x32_bf16 v[32:35], v[132:135], v[232:235], v[32:35]
	v_mfma_f32_16x16x32_bf16 v[28:31], v[140:143], v[232:235], v[28:31]
	v_mfma_f32_16x16x32_bf16 v[16:19], v[132:135], v[240:243], v[16:19]
	v_mfma_f32_16x16x32_bf16 v[12:15], v[140:143], v[240:243], v[12:15]
	v_mfma_f32_16x16x32_bf16 v[64:67], v[136:139], v[218:221], v[64:67]
	v_mfma_f32_16x16x32_bf16 v[60:63], v[144:147], v[218:221], v[60:63]
	v_mfma_f32_16x16x32_bf16 v[48:51], v[136:139], v[228:231], v[48:51]
	v_mfma_f32_16x16x32_bf16 v[44:47], v[144:147], v[228:231], v[44:47]
	v_mfma_f32_16x16x32_bf16 v[32:35], v[136:139], v[236:239], v[32:35]
	v_mfma_f32_16x16x32_bf16 v[28:31], v[144:147], v[236:239], v[28:31]
	v_mfma_f32_16x16x32_bf16 v[16:19], v[136:139], v[244:247], v[16:19]
	v_mfma_f32_16x16x32_bf16 v[12:15], v[144:147], v[244:247], v[12:15]
	v_mfma_f32_16x16x32_bf16 v[56:59], v[190:193], v[206:209], v[56:59]
	v_mfma_f32_16x16x32_bf16 v[52:55], v[198:201], v[206:209], v[52:55]
	v_mfma_f32_16x16x32_bf16 v[40:43], v[190:193], v[224:227], v[40:43]
	v_mfma_f32_16x16x32_bf16 v[36:39], v[198:201], v[224:227], v[36:39]
	v_mfma_f32_16x16x32_bf16 v[24:27], v[190:193], v[232:235], v[24:27]
	v_mfma_f32_16x16x32_bf16 v[20:23], v[198:201], v[232:235], v[20:23]
	v_mfma_f32_16x16x32_bf16 v[8:11], v[190:193], v[240:243], v[8:11]
	v_mfma_f32_16x16x32_bf16 v[4:7], v[198:201], v[240:243], v[4:7]
	v_mfma_f32_16x16x32_bf16 v[56:59], v[194:197], v[218:221], v[56:59]
	v_mfma_f32_16x16x32_bf16 v[52:55], v[202:205], v[218:221], v[52:55]
	v_mfma_f32_16x16x32_bf16 v[40:43], v[194:197], v[228:231], v[40:43]
	v_mfma_f32_16x16x32_bf16 v[36:39], v[202:205], v[228:231], v[36:39]
	v_mfma_f32_16x16x32_bf16 v[24:27], v[194:197], v[236:239], v[24:27]
	v_mfma_f32_16x16x32_bf16 v[20:23], v[202:205], v[236:239], v[20:23]
	v_mfma_f32_16x16x32_bf16 v[8:11], v[194:197], v[244:247], v[8:11]
	v_mfma_f32_16x16x32_bf16 v[4:7], v[202:205], v[244:247], v[4:7]
	s_setprio 0
	s_barrier
	s_add_i32 s97, s97, 2
	s_add_u32 s10, s10, 0x100
	s_addc_u32 s11, s11, 0
	s_add_u32 s89, s89, 0x100
	s_addc_u32 s90, s90, 0
	s_cmp_gt_u32 s97, 13
	s_cbranch_scc0 .LBB0_231
	s_and_b64 vcc, exec, s[16:17]
	s_cbranch_vccz .LBB0_234
	s_barrier

.LBB0_293:
	s_add_u32 s25, s36, s44
	s_addc_u32 s40, s37, s45
	s_add_u32 s25, s25, 0x100
	s_addc_u32 s40, s40, 0
	s_add_u32 s41, s97, s44
	s_addc_u32 s46, s50, s45
	s_add_i32 s70, 0, 0x10000
	s_cmpk_eq_i32 s44, 0x700
	s_cselect_b32 s49, s17, s40
	s_cselect_b32 s48, vcc_lo, s25
	v_add_u32_e32 v147, s70, v145
	s_cselect_b32 s47, s15, s46
	s_cselect_b32 s46, vcc_hi, s41
	s_add_i32 s25, 0, 0x14000
	ds_read_b128 v[152:155], v147
	ds_read_b128 v[156:159], v147 offset:1024
	ds_read_b128 v[160:163], v147 offset:2048
	ds_read_b128 v[164:167], v147 offset:3072
	v_add_u32_e32 v147, s25, v145
	ds_read_b128 v[168:171], v147
	ds_read_b128 v[172:175], v147 offset:1024
	ds_read_b128 v[176:179], v147 offset:2048
	ds_read_b128 v[190:193], v147 offset:3072
	v_lshl_add_u64 v[182:183], v[140:141], 0, s[44:45]
	s_add_i32 m0, s59, 0xc000
	ds_read_b128 v[194:197], v146
	ds_read_b128 v[198:201], v146 offset:1024
	ds_read_b128 v[202:205], v146 offset:2048
	ds_read_b128 v[206:209], v146 offset:3072
	ds_read_b128 v[218:221], v146 offset:4096
	ds_read_b128 v[224:227], v146 offset:5120
	ds_read_b128 v[228:231], v146 offset:6144
	ds_read_b128 v[232:235], v146 offset:7168
	global_load_lds_dwordx4 v[182:183], off
	v_lshl_add_u64 v[182:183], v[142:143], 0, s[44:45]
	s_add_i32 m0, s59, 0xe000
	s_nop 0
	global_load_lds_dwordx4 v[182:183], off
	s_waitcnt vmcnt(8)
	s_waitcnt lgkmcnt(0)
	s_barrier
	s_setprio 1
	s_waitcnt lgkmcnt(0)
	v_mfma_f32_16x16x32_bf16 v[128:131], v[152:155], v[194:197], v[128:131]
	v_mfma_f32_16x16x32_bf16 v[124:127], v[160:163], v[194:197], v[124:127]
	v_mfma_f32_16x16x32_bf16 v[112:115], v[152:155], v[202:205], v[112:115]
	v_mfma_f32_16x16x32_bf16 v[108:111], v[160:163], v[202:205], v[108:111]
	v_mfma_f32_16x16x32_bf16 v[104:107], v[152:155], v[218:221], v[104:107]
	v_mfma_f32_16x16x32_bf16 v[96:99], v[160:163], v[218:221], v[96:99]
	v_mfma_f32_16x16x32_bf16 v[88:91], v[152:155], v[228:231], v[88:91]
	v_mfma_f32_16x16x32_bf16 v[80:83], v[160:163], v[228:231], v[80:83]
	v_mfma_f32_16x16x32_bf16 v[128:131], v[156:159], v[198:201], v[128:131]
	v_mfma_f32_16x16x32_bf16 v[124:127], v[164:167], v[198:201], v[124:127]
	v_mfma_f32_16x16x32_bf16 v[112:115], v[156:159], v[206:209], v[112:115]
	v_mfma_f32_16x16x32_bf16 v[108:111], v[164:167], v[206:209], v[108:111]
	v_mfma_f32_16x16x32_bf16 v[104:107], v[156:159], v[224:227], v[104:107]
	v_mfma_f32_16x16x32_bf16 v[96:99], v[164:167], v[224:227], v[96:99]
	v_mfma_f32_16x16x32_bf16 v[88:91], v[156:159], v[232:235], v[88:91]
	v_mfma_f32_16x16x32_bf16 v[80:83], v[164:167], v[232:235], v[80:83]
	v_mfma_f32_16x16x32_bf16 v[120:123], v[168:171], v[194:197], v[120:123]
	v_mfma_f32_16x16x32_bf16 v[116:119], v[176:179], v[194:197], v[116:119]
	v_mfma_f32_16x16x32_bf16 v[100:103], v[168:171], v[202:205], v[100:103]
	v_mfma_f32_16x16x32_bf16 v[92:95], v[176:179], v[202:205], v[92:95]
	v_mfma_f32_16x16x32_bf16 v[84:87], v[168:171], v[218:221], v[84:87]
	v_mfma_f32_16x16x32_bf16 v[76:79], v[176:179], v[218:221], v[76:79]
	v_mfma_f32_16x16x32_bf16 v[72:75], v[168:171], v[228:231], v[72:75]
	v_mfma_f32_16x16x32_bf16 v[68:71], v[176:179], v[228:231], v[68:71]
	v_mfma_f32_16x16x32_bf16 v[120:123], v[172:175], v[198:201], v[120:123]
	v_mfma_f32_16x16x32_bf16 v[116:119], v[190:193], v[198:201], v[116:119]
	v_mfma_f32_16x16x32_bf16 v[100:103], v[172:175], v[206:209], v[100:103]
	v_mfma_f32_16x16x32_bf16 v[92:95], v[190:193], v[206:209], v[92:95]
	v_mfma_f32_16x16x32_bf16 v[84:87], v[172:175], v[224:227], v[84:87]
	v_mfma_f32_16x16x32_bf16 v[76:79], v[190:193], v[224:227], v[76:79]
	v_mfma_f32_16x16x32_bf16 v[72:75], v[172:175], v[232:235], v[72:75]
	v_mfma_f32_16x16x32_bf16 v[68:71], v[190:193], v[232:235], v[68:71]
	s_setprio 0
	s_barrier
	s_add_i32 s40, s70, s58
	v_lshl_add_u64 v[182:183], s[46:47], 0, v[180:181]
	s_mov_b32 m0, s40
	ds_read_b128 v[194:197], v146 offset:16384
	ds_read_b128 v[198:201], v146 offset:17408
	ds_read_b128 v[202:205], v146 offset:18432
	ds_read_b128 v[206:209], v146 offset:19456
	ds_read_b128 v[218:221], v146 offset:20480
	ds_read_b128 v[224:227], v146 offset:21504
	ds_read_b128 v[228:231], v146 offset:22528
	ds_read_b128 v[232:235], v146 offset:23552
	global_load_lds_dwordx4 v[182:183], off
	s_add_i32 m0, s40, 0x2000
	s_add_u32 s40, s46, 0x40000
	v_lshl_add_u64 v[184:185], s[46:47], 0, v[134:135]
	s_addc_u32 s41, s47, 0
	s_add_i32 s25, s25, s58
	global_load_lds_dwordx4 v[184:185], off
	v_lshl_add_u64 v[210:211], s[40:41], 0, v[180:181]
	s_mov_b32 m0, s25
	v_lshl_add_u64 v[236:237], s[48:49], 0, v[132:133]
	global_load_lds_dwordx4 v[210:211], off
	v_lshl_add_u64 v[210:211], s[40:41], 0, v[134:135]
	s_add_i32 m0, s25, 0x2000
	s_nop 0
	global_load_lds_dwordx4 v[210:211], off
	v_lshl_add_u64 v[210:211], s[48:49], 0, v[0:1]
	s_mov_b32 m0, s59
	s_nop 0
	global_load_lds_dwordx4 v[210:211], off
	s_mov_b32 m0, s64
	s_nop 0
	global_load_lds_dwordx4 v[236:237], off
	s_waitcnt vmcnt(8)
	s_waitcnt lgkmcnt(0)
	s_barrier
	s_setprio 1
	s_waitcnt lgkmcnt(0)
	v_mfma_f32_16x16x32_bf16 v[64:67], v[152:155], v[194:197], v[64:67]
	v_mfma_f32_16x16x32_bf16 v[4:7], v[160:163], v[194:197], v[4:7]
	v_mfma_f32_16x16x32_bf16 v[60:63], v[152:155], v[202:205], v[60:63]
	v_mfma_f32_16x16x32_bf16 v[56:59], v[160:163], v[202:205], v[56:59]
	v_mfma_f32_16x16x32_bf16 v[52:55], v[152:155], v[218:221], v[52:55]
	v_mfma_f32_16x16x32_bf16 v[48:51], v[160:163], v[218:221], v[48:51]
	v_mfma_f32_16x16x32_bf16 v[44:47], v[152:155], v[228:231], v[44:47]
	v_mfma_f32_16x16x32_bf16 v[40:43], v[160:163], v[228:231], v[40:43]
	v_mfma_f32_16x16x32_bf16 v[64:67], v[156:159], v[198:201], v[64:67]
	v_mfma_f32_16x16x32_bf16 v[4:7], v[164:167], v[198:201], v[4:7]
	v_mfma_f32_16x16x32_bf16 v[60:63], v[156:159], v[206:209], v[60:63]
	v_mfma_f32_16x16x32_bf16 v[56:59], v[164:167], v[206:209], v[56:59]
	v_mfma_f32_16x16x32_bf16 v[52:55], v[156:159], v[224:227], v[52:55]
	v_mfma_f32_16x16x32_bf16 v[48:51], v[164:167], v[224:227], v[48:51]
	v_mfma_f32_16x16x32_bf16 v[44:47], v[156:159], v[232:235], v[44:47]
	v_mfma_f32_16x16x32_bf16 v[40:43], v[164:167], v[232:235], v[40:43]
	v_mfma_f32_16x16x32_bf16 v[12:15], v[168:171], v[194:197], v[12:15]
	v_mfma_f32_16x16x32_bf16 v[8:11], v[176:179], v[194:197], v[8:11]
	v_mfma_f32_16x16x32_bf16 v[20:23], v[168:171], v[202:205], v[20:23]
	v_mfma_f32_16x16x32_bf16 v[16:19], v[176:179], v[202:205], v[16:19]
	v_mfma_f32_16x16x32_bf16 v[28:31], v[168:171], v[218:221], v[28:31]
	v_mfma_f32_16x16x32_bf16 v[24:27], v[176:179], v[218:221], v[24:27]
	v_mfma_f32_16x16x32_bf16 v[36:39], v[168:171], v[228:231], v[36:39]
	v_mfma_f32_16x16x32_bf16 v[32:35], v[176:179], v[228:231], v[32:35]
	v_mfma_f32_16x16x32_bf16 v[12:15], v[172:175], v[198:201], v[12:15]
	v_mfma_f32_16x16x32_bf16 v[8:11], v[190:193], v[198:201], v[8:11]
	v_mfma_f32_16x16x32_bf16 v[20:23], v[172:175], v[206:209], v[20:23]
	v_mfma_f32_16x16x32_bf16 v[16:19], v[190:193], v[206:209], v[16:19]
	v_mfma_f32_16x16x32_bf16 v[28:31], v[172:175], v[224:227], v[28:31]
	v_mfma_f32_16x16x32_bf16 v[24:27], v[190:193], v[224:227], v[24:27]
	v_mfma_f32_16x16x32_bf16 v[36:39], v[172:175], v[232:235], v[36:39]
	v_mfma_f32_16x16x32_bf16 v[32:35], v[190:193], v[232:235], v[32:35]
	s_setprio 0
	s_barrier
	s_add_i32 s25, 0, 0x18000
	v_add_u32_e32 v147, s25, v145
	s_add_i32 s70, 0, 0x1c000
	ds_read_b128 v[152:155], v147
	ds_read_b128 v[156:159], v147 offset:1024
	ds_read_b128 v[160:163], v147 offset:2048
	ds_read_b128 v[164:167], v147 offset:3072
	v_add_u32_e32 v147, s70, v145
	ds_read_b128 v[168:171], v147
	ds_read_b128 v[172:175], v147 offset:1024
	ds_read_b128 v[176:179], v147 offset:2048
	ds_read_b128 v[190:193], v147 offset:3072
	s_add_u32 s40, s48, 0x40000
	s_addc_u32 s41, s49, 0
	s_mov_b32 m0, s65
	v_lshl_add_u64 v[238:239], s[40:41], 0, v[0:1]
	ds_read_b128 v[194:197], v146 offset:32768
	ds_read_b128 v[198:201], v146 offset:33792
	ds_read_b128 v[202:205], v146 offset:34816
	ds_read_b128 v[206:209], v146 offset:35840
	ds_read_b128 v[218:221], v146 offset:36864
	ds_read_b128 v[224:227], v146 offset:37888
	ds_read_b128 v[228:231], v146 offset:38912
	ds_read_b128 v[232:235], v146 offset:39936
	global_load_lds_dwordx4 v[238:239], off
	v_lshl_add_u64 v[238:239], s[40:41], 0, v[132:133]
	s_mov_b32 m0, s68
	s_nop 0
	global_load_lds_dwordx4 v[238:239], off
	s_waitcnt vmcnt(8)
	s_waitcnt lgkmcnt(0)
	s_barrier
	s_setprio 1
	s_waitcnt lgkmcnt(0)
	v_mfma_f32_16x16x32_bf16 v[128:131], v[152:155], v[194:197], v[128:131]
	v_mfma_f32_16x16x32_bf16 v[124:127], v[160:163], v[194:197], v[124:127]
	v_mfma_f32_16x16x32_bf16 v[112:115], v[152:155], v[202:205], v[112:115]
	v_mfma_f32_16x16x32_bf16 v[108:111], v[160:163], v[202:205], v[108:111]
	v_mfma_f32_16x16x32_bf16 v[104:107], v[152:155], v[218:221], v[104:107]
	v_mfma_f32_16x16x32_bf16 v[96:99], v[160:163], v[218:221], v[96:99]
	v_mfma_f32_16x16x32_bf16 v[88:91], v[152:155], v[228:231], v[88:91]
	v_mfma_f32_16x16x32_bf16 v[80:83], v[160:163], v[228:231], v[80:83]
	v_mfma_f32_16x16x32_bf16 v[128:131], v[156:159], v[198:201], v[128:131]
	v_mfma_f32_16x16x32_bf16 v[124:127], v[164:167], v[198:201], v[124:127]
	v_mfma_f32_16x16x32_bf16 v[112:115], v[156:159], v[206:209], v[112:115]
	v_mfma_f32_16x16x32_bf16 v[108:111], v[164:167], v[206:209], v[108:111]
	v_mfma_f32_16x16x32_bf16 v[104:107], v[156:159], v[224:227], v[104:107]
	v_mfma_f32_16x16x32_bf16 v[96:99], v[164:167], v[224:227], v[96:99]
	v_mfma_f32_16x16x32_bf16 v[88:91], v[156:159], v[232:235], v[88:91]
	v_mfma_f32_16x16x32_bf16 v[80:83], v[164:167], v[232:235], v[80:83]
	v_mfma_f32_16x16x32_bf16 v[120:123], v[168:171], v[194:197], v[120:123]
	v_mfma_f32_16x16x32_bf16 v[116:119], v[176:179], v[194:197], v[116:119]
	v_mfma_f32_16x16x32_bf16 v[100:103], v[168:171], v[202:205], v[100:103]
	v_mfma_f32_16x16x32_bf16 v[92:95], v[176:179], v[202:205], v[92:95]
	v_mfma_f32_16x16x32_bf16 v[84:87], v[168:171], v[218:221], v[84:87]
	v_mfma_f32_16x16x32_bf16 v[76:79], v[176:179], v[218:221], v[76:79]
	v_mfma_f32_16x16x32_bf16 v[72:75], v[168:171], v[228:231], v[72:75]
	v_mfma_f32_16x16x32_bf16 v[68:71], v[176:179], v[228:231], v[68:71]
	v_mfma_f32_16x16x32_bf16 v[120:123], v[172:175], v[198:201], v[120:123]
	v_mfma_f32_16x16x32_bf16 v[116:119], v[190:193], v[198:201], v[116:119]
	v_mfma_f32_16x16x32_bf16 v[100:103], v[172:175], v[206:209], v[100:103]
	v_mfma_f32_16x16x32_bf16 v[92:95], v[190:193], v[206:209], v[92:95]
	v_mfma_f32_16x16x32_bf16 v[84:87], v[172:175], v[224:227], v[84:87]
	v_mfma_f32_16x16x32_bf16 v[76:79], v[190:193], v[224:227], v[76:79]
	v_mfma_f32_16x16x32_bf16 v[72:75], v[172:175], v[232:235], v[72:75]
	v_mfma_f32_16x16x32_bf16 v[68:71], v[190:193], v[232:235], v[68:71]
	s_setprio 0
	s_barrier
	s_add_i32 s25, s25, s58
	v_lshl_add_u64 v[182:183], v[182:183], 0, s[94:95]
	s_mov_b32 m0, s25
	ds_read_b128 v[194:197], v146 offset:49152
	ds_read_b128 v[198:201], v146 offset:50176
	ds_read_b128 v[202:205], v146 offset:51200
	ds_read_b128 v[206:209], v146 offset:52224
	ds_read_b128 v[218:221], v146 offset:53248
	ds_read_b128 v[224:227], v146 offset:54272
	ds_read_b128 v[228:231], v146 offset:55296
	ds_read_b128 v[232:235], v146 offset:56320
	global_load_lds_dwordx4 v[182:183], off
	s_add_i32 m0, s25, 0x2000
	s_add_u32 s40, s46, 0x40080
	v_lshl_add_u64 v[182:183], v[184:185], 0, s[94:95]
	s_addc_u32 s41, s47, 0
	s_add_i32 s25, s70, s58
	global_load_lds_dwordx4 v[182:183], off
	v_lshl_add_u64 v[182:183], s[40:41], 0, v[180:181]
	s_mov_b32 m0, s25
	s_nop 0
	global_load_lds_dwordx4 v[182:183], off
	v_lshl_add_u64 v[182:183], s[40:41], 0, v[134:135]
	s_add_i32 m0, s25, 0x2000
	s_nop 0
	global_load_lds_dwordx4 v[182:183], off
	v_lshl_add_u64 v[182:183], v[210:211], 0, s[94:95]
	s_mov_b32 m0, s69
	s_nop 0
	global_load_lds_dwordx4 v[182:183], off
	v_lshl_add_u64 v[182:183], v[236:237], 0, s[94:95]
	s_mov_b32 m0, s88
	s_nop 0
	global_load_lds_dwordx4 v[182:183], off
	s_waitcnt vmcnt(8)
	s_waitcnt lgkmcnt(0)
	s_barrier
	s_setprio 1
	s_waitcnt lgkmcnt(0)
	v_mfma_f32_16x16x32_bf16 v[64:67], v[152:155], v[194:197], v[64:67]
	v_mfma_f32_16x16x32_bf16 v[4:7], v[160:163], v[194:197], v[4:7]
	v_mfma_f32_16x16x32_bf16 v[60:63], v[152:155], v[202:205], v[60:63]
	v_mfma_f32_16x16x32_bf16 v[56:59], v[160:163], v[202:205], v[56:59]
	v_mfma_f32_16x16x32_bf16 v[52:55], v[152:155], v[218:221], v[52:55]
	v_mfma_f32_16x16x32_bf16 v[48:51], v[160:163], v[218:221], v[48:51]
	v_mfma_f32_16x16x32_bf16 v[44:47], v[152:155], v[228:231], v[44:47]
	v_mfma_f32_16x16x32_bf16 v[40:43], v[160:163], v[228:231], v[40:43]
	v_mfma_f32_16x16x32_bf16 v[64:67], v[156:159], v[198:201], v[64:67]
	v_mfma_f32_16x16x32_bf16 v[4:7], v[164:167], v[198:201], v[4:7]
	v_mfma_f32_16x16x32_bf16 v[60:63], v[156:159], v[206:209], v[60:63]
	v_mfma_f32_16x16x32_bf16 v[56:59], v[164:167], v[206:209], v[56:59]
	v_mfma_f32_16x16x32_bf16 v[52:55], v[156:159], v[224:227], v[52:55]
	v_mfma_f32_16x16x32_bf16 v[48:51], v[164:167], v[224:227], v[48:51]
	v_mfma_f32_16x16x32_bf16 v[44:47], v[156:159], v[232:235], v[44:47]
	v_mfma_f32_16x16x32_bf16 v[40:43], v[164:167], v[232:235], v[40:43]
	v_mfma_f32_16x16x32_bf16 v[12:15], v[168:171], v[194:197], v[12:15]
	v_mfma_f32_16x16x32_bf16 v[8:11], v[176:179], v[194:197], v[8:11]
	v_mfma_f32_16x16x32_bf16 v[20:23], v[168:171], v[202:205], v[20:23]
	v_mfma_f32_16x16x32_bf16 v[16:19], v[176:179], v[202:205], v[16:19]
	v_mfma_f32_16x16x32_bf16 v[28:31], v[168:171], v[218:221], v[28:31]
	v_mfma_f32_16x16x32_bf16 v[24:27], v[176:179], v[218:221], v[24:27]
	v_mfma_f32_16x16x32_bf16 v[36:39], v[168:171], v[228:231], v[36:39]
	v_mfma_f32_16x16x32_bf16 v[32:35], v[176:179], v[228:231], v[32:35]
	v_mfma_f32_16x16x32_bf16 v[12:15], v[172:175], v[198:201], v[12:15]
	v_mfma_f32_16x16x32_bf16 v[8:11], v[190:193], v[198:201], v[8:11]
	v_mfma_f32_16x16x32_bf16 v[20:23], v[172:175], v[206:209], v[20:23]
	v_mfma_f32_16x16x32_bf16 v[16:19], v[190:193], v[206:209], v[16:19]
	v_mfma_f32_16x16x32_bf16 v[28:31], v[172:175], v[224:227], v[28:31]
	v_mfma_f32_16x16x32_bf16 v[24:27], v[190:193], v[224:227], v[24:27]
	v_mfma_f32_16x16x32_bf16 v[36:39], v[172:175], v[232:235], v[36:39]
	v_mfma_f32_16x16x32_bf16 v[32:35], v[190:193], v[232:235], v[32:35]
	s_setprio 0
	s_barrier
	s_add_i32 s51, s51, 2
	s_add_u32 s44, s44, 0x100
	s_addc_u32 s45, s45, 0
	s_cmp_gt_u32 s51, 13
	s_cbranch_scc0 .LBB0_293
	s_and_b64 vcc, exec, s[12:13]
	s_cbranch_vccz .LBB0_296
	s_barrier

.LBB0_334:
	s_add_u32 s25, s44, 0xfffc0080
	s_addc_u32 s40, s45, -1
	s_add_i32 s41, 0, 0x10000
	s_cmp_eq_u32 s88, 12
	s_cselect_b32 s49, s19, s40
	s_cselect_b32 s48, s64, s25
	s_cselect_b32 s47, s17, s69
	s_cselect_b32 s46, s65, s68
	s_add_i32 s25, 0, 0x14000
	v_add_u32_e32 v144, s41, v187
	v_add_u32_e32 v170, s25, v187
	ds_read_b128 v[132:135], v144
	ds_read_b128 v[136:139], v144 offset:1024
	ds_read_b128 v[140:143], v144 offset:2048
	ds_read_b128 v[144:147], v144 offset:3072
	ds_read_b128 v[148:151], v170
	ds_read_b128 v[152:155], v170 offset:1024
	ds_read_b128 v[156:159], v170 offset:2048
	ds_read_b128 v[170:173], v170 offset:3072
	v_lshl_add_u64 v[178:179], s[44:45], 0, v[166:167]
	s_add_i32 m0, s51, 0xc000
	ds_read_b128 v[174:177], v194
	ds_read_b128 v[196:199], v194 offset:1024
	ds_read_b128 v[200:203], v194 offset:2048
	ds_read_b128 v[204:207], v194 offset:3072
	ds_read_b128 v[208:211], v194 offset:4096
	ds_read_b128 v[218:221], v194 offset:5120
	ds_read_b128 v[224:227], v194 offset:6144
	ds_read_b128 v[228:231], v194 offset:7168
	global_load_lds_dwordx4 v[178:179], off
	v_lshl_add_u64 v[178:179], s[44:45], 0, v[168:169]
	s_add_i32 m0, s51, 0xe000
	s_nop 0
	global_load_lds_dwordx4 v[178:179], off
	s_waitcnt vmcnt(8)
	s_waitcnt lgkmcnt(0)
	s_barrier
	s_setprio 1
	s_waitcnt lgkmcnt(0)
	v_mfma_f32_16x16x32_bf16 v[128:131], v[132:135], v[174:177], v[128:131]
	v_mfma_f32_16x16x32_bf16 v[124:127], v[140:143], v[174:177], v[124:127]
	v_mfma_f32_16x16x32_bf16 v[112:115], v[132:135], v[200:203], v[112:115]
	v_mfma_f32_16x16x32_bf16 v[108:111], v[140:143], v[200:203], v[108:111]
	v_mfma_f32_16x16x32_bf16 v[96:99], v[132:135], v[208:211], v[96:99]
	v_mfma_f32_16x16x32_bf16 v[92:95], v[140:143], v[208:211], v[92:95]
	v_mfma_f32_16x16x32_bf16 v[80:83], v[132:135], v[224:227], v[80:83]
	v_mfma_f32_16x16x32_bf16 v[76:79], v[140:143], v[224:227], v[76:79]
	v_mfma_f32_16x16x32_bf16 v[128:131], v[136:139], v[196:199], v[128:131]
	v_mfma_f32_16x16x32_bf16 v[124:127], v[144:147], v[196:199], v[124:127]
	v_mfma_f32_16x16x32_bf16 v[112:115], v[136:139], v[204:207], v[112:115]
	v_mfma_f32_16x16x32_bf16 v[108:111], v[144:147], v[204:207], v[108:111]
	v_mfma_f32_16x16x32_bf16 v[96:99], v[136:139], v[218:221], v[96:99]
	v_mfma_f32_16x16x32_bf16 v[92:95], v[144:147], v[218:221], v[92:95]
	v_mfma_f32_16x16x32_bf16 v[80:83], v[136:139], v[228:231], v[80:83]
	v_mfma_f32_16x16x32_bf16 v[76:79], v[144:147], v[228:231], v[76:79]
	v_mfma_f32_16x16x32_bf16 v[120:123], v[148:151], v[174:177], v[120:123]
	v_mfma_f32_16x16x32_bf16 v[116:119], v[156:159], v[174:177], v[116:119]
	v_mfma_f32_16x16x32_bf16 v[104:107], v[148:151], v[200:203], v[104:107]
	v_mfma_f32_16x16x32_bf16 v[100:103], v[156:159], v[200:203], v[100:103]
	v_mfma_f32_16x16x32_bf16 v[88:91], v[148:151], v[208:211], v[88:91]
	v_mfma_f32_16x16x32_bf16 v[84:87], v[156:159], v[208:211], v[84:87]
	v_mfma_f32_16x16x32_bf16 v[72:75], v[148:151], v[224:227], v[72:75]
	v_mfma_f32_16x16x32_bf16 v[68:71], v[156:159], v[224:227], v[68:71]
	v_mfma_f32_16x16x32_bf16 v[120:123], v[152:155], v[196:199], v[120:123]
	v_mfma_f32_16x16x32_bf16 v[116:119], v[170:173], v[196:199], v[116:119]
	v_mfma_f32_16x16x32_bf16 v[104:107], v[152:155], v[204:207], v[104:107]
	v_mfma_f32_16x16x32_bf16 v[100:103], v[170:173], v[204:207], v[100:103]
	v_mfma_f32_16x16x32_bf16 v[88:91], v[152:155], v[218:221], v[88:91]
	v_mfma_f32_16x16x32_bf16 v[84:87], v[170:173], v[218:221], v[84:87]
	v_mfma_f32_16x16x32_bf16 v[72:75], v[152:155], v[228:231], v[72:75]
	v_mfma_f32_16x16x32_bf16 v[68:71], v[170:173], v[228:231], v[68:71]
	s_setprio 0
	s_barrier
	s_add_i32 s40, s41, s50
	v_lshl_add_u64 v[178:179], s[46:47], 0, v[162:163]
	s_mov_b32 m0, s40
	ds_read_b128 v[174:177], v194 offset:16384
	ds_read_b128 v[196:199], v194 offset:17408
	ds_read_b128 v[200:203], v194 offset:18432
	ds_read_b128 v[204:207], v194 offset:19456
	ds_read_b128 v[208:211], v194 offset:20480
	ds_read_b128 v[218:221], v194 offset:21504
	ds_read_b128 v[224:227], v194 offset:22528
	ds_read_b128 v[228:231], v194 offset:23552
	global_load_lds_dwordx4 v[178:179], off
	s_add_i32 m0, s40, 0x2000
	s_add_u32 s40, s46, 0x40000
	v_lshl_add_u64 v[182:183], s[46:47], 0, v[0:1]
	s_addc_u32 s41, s47, 0
	s_add_i32 s25, s25, s50
	global_load_lds_dwordx4 v[182:183], off
	v_lshl_add_u64 v[184:185], s[40:41], 0, v[162:163]
	s_mov_b32 m0, s25
	v_lshl_add_u64 v[190:191], s[48:49], 0, v[160:161]
	global_load_lds_dwordx4 v[184:185], off
	v_lshl_add_u64 v[184:185], s[40:41], 0, v[0:1]
	s_add_i32 m0, s25, 0x2000
	s_nop 0
	global_load_lds_dwordx4 v[184:185], off
	v_lshl_add_u64 v[184:185], s[48:49], 0, v[164:165]
	s_mov_b32 m0, s51
	s_nop 0
	global_load_lds_dwordx4 v[184:185], off
	s_mov_b32 m0, s52
	s_nop 0
	global_load_lds_dwordx4 v[190:191], off
	s_waitcnt vmcnt(8)
	s_waitcnt lgkmcnt(0)
	s_barrier
	s_setprio 1
	s_waitcnt lgkmcnt(0)
	v_mfma_f32_16x16x32_bf16 v[64:67], v[132:135], v[174:177], v[64:67]
	v_mfma_f32_16x16x32_bf16 v[60:63], v[140:143], v[174:177], v[60:63]
	v_mfma_f32_16x16x32_bf16 v[48:51], v[132:135], v[200:203], v[48:51]
	v_mfma_f32_16x16x32_bf16 v[44:47], v[140:143], v[200:203], v[44:47]
	v_mfma_f32_16x16x32_bf16 v[32:35], v[132:135], v[208:211], v[32:35]
	v_mfma_f32_16x16x32_bf16 v[28:31], v[140:143], v[208:211], v[28:31]
	v_mfma_f32_16x16x32_bf16 v[16:19], v[132:135], v[224:227], v[16:19]
	v_mfma_f32_16x16x32_bf16 v[12:15], v[140:143], v[224:227], v[12:15]
	v_mfma_f32_16x16x32_bf16 v[64:67], v[136:139], v[196:199], v[64:67]
	v_mfma_f32_16x16x32_bf16 v[60:63], v[144:147], v[196:199], v[60:63]
	v_mfma_f32_16x16x32_bf16 v[48:51], v[136:139], v[204:207], v[48:51]
	v_mfma_f32_16x16x32_bf16 v[44:47], v[144:147], v[204:207], v[44:47]
	v_mfma_f32_16x16x32_bf16 v[32:35], v[136:139], v[218:221], v[32:35]
	v_mfma_f32_16x16x32_bf16 v[28:31], v[144:147], v[218:221], v[28:31]
	v_mfma_f32_16x16x32_bf16 v[16:19], v[136:139], v[228:231], v[16:19]
	v_mfma_f32_16x16x32_bf16 v[12:15], v[144:147], v[228:231], v[12:15]
	v_mfma_f32_16x16x32_bf16 v[56:59], v[148:151], v[174:177], v[56:59]
	v_mfma_f32_16x16x32_bf16 v[52:55], v[156:159], v[174:177], v[52:55]
	v_mfma_f32_16x16x32_bf16 v[40:43], v[148:151], v[200:203], v[40:43]
	v_mfma_f32_16x16x32_bf16 v[36:39], v[156:159], v[200:203], v[36:39]
	v_mfma_f32_16x16x32_bf16 v[24:27], v[148:151], v[208:211], v[24:27]
	v_mfma_f32_16x16x32_bf16 v[20:23], v[156:159], v[208:211], v[20:23]
	v_mfma_f32_16x16x32_bf16 v[8:11], v[148:151], v[224:227], v[8:11]
	v_mfma_f32_16x16x32_bf16 v[4:7], v[156:159], v[224:227], v[4:7]
	v_mfma_f32_16x16x32_bf16 v[56:59], v[152:155], v[196:199], v[56:59]
	v_mfma_f32_16x16x32_bf16 v[52:55], v[170:173], v[196:199], v[52:55]
	v_mfma_f32_16x16x32_bf16 v[40:43], v[152:155], v[204:207], v[40:43]
	v_mfma_f32_16x16x32_bf16 v[36:39], v[170:173], v[204:207], v[36:39]
	v_mfma_f32_16x16x32_bf16 v[24:27], v[152:155], v[218:221], v[24:27]
	v_mfma_f32_16x16x32_bf16 v[20:23], v[170:173], v[218:221], v[20:23]
	v_mfma_f32_16x16x32_bf16 v[8:11], v[152:155], v[228:231], v[8:11]
	v_mfma_f32_16x16x32_bf16 v[4:7], v[170:173], v[228:231], v[4:7]
	s_setprio 0
	s_barrier
	s_add_i32 s25, 0, 0x18000
	s_add_i32 s70, 0, 0x1c000
	v_add_u32_e32 v144, s25, v187
	v_add_u32_e32 v170, s70, v187
	ds_read_b128 v[132:135], v144
	ds_read_b128 v[136:139], v144 offset:1024
	ds_read_b128 v[140:143], v144 offset:2048
	ds_read_b128 v[144:147], v144 offset:3072
	ds_read_b128 v[148:151], v170
	ds_read_b128 v[152:155], v170 offset:1024
	ds_read_b128 v[156:159], v170 offset:2048
	ds_read_b128 v[170:173], v170 offset:3072
	s_add_u32 s40, s48, 0x40000
	s_addc_u32 s41, s49, 0
	s_mov_b32 m0, s53
	v_lshl_add_u64 v[232:233], s[40:41], 0, v[164:165]
	ds_read_b128 v[174:177], v194 offset:32768
	ds_read_b128 v[196:199], v194 offset:33792
	ds_read_b128 v[200:203], v194 offset:34816
	ds_read_b128 v[204:207], v194 offset:35840
	ds_read_b128 v[208:211], v194 offset:36864
	ds_read_b128 v[218:221], v194 offset:37888
	ds_read_b128 v[224:227], v194 offset:38912
	ds_read_b128 v[228:231], v194 offset:39936
	global_load_lds_dwordx4 v[232:233], off
	v_lshl_add_u64 v[232:233], s[40:41], 0, v[160:161]
	s_mov_b32 m0, s54
	s_nop 0
	global_load_lds_dwordx4 v[232:233], off
	s_waitcnt vmcnt(8)
	s_waitcnt lgkmcnt(0)
	s_barrier
	s_setprio 1
	s_waitcnt lgkmcnt(0)
	v_mfma_f32_16x16x32_bf16 v[128:131], v[132:135], v[174:177], v[128:131]
	v_mfma_f32_16x16x32_bf16 v[124:127], v[140:143], v[174:177], v[124:127]
	v_mfma_f32_16x16x32_bf16 v[112:115], v[132:135], v[200:203], v[112:115]
	v_mfma_f32_16x16x32_bf16 v[108:111], v[140:143], v[200:203], v[108:111]
	v_mfma_f32_16x16x32_bf16 v[96:99], v[132:135], v[208:211], v[96:99]
	v_mfma_f32_16x16x32_bf16 v[92:95], v[140:143], v[208:211], v[92:95]
	v_mfma_f32_16x16x32_bf16 v[80:83], v[132:135], v[224:227], v[80:83]
	v_mfma_f32_16x16x32_bf16 v[76:79], v[140:143], v[224:227], v[76:79]
	v_mfma_f32_16x16x32_bf16 v[128:131], v[136:139], v[196:199], v[128:131]
	v_mfma_f32_16x16x32_bf16 v[124:127], v[144:147], v[196:199], v[124:127]
	v_mfma_f32_16x16x32_bf16 v[112:115], v[136:139], v[204:207], v[112:115]
	v_mfma_f32_16x16x32_bf16 v[108:111], v[144:147], v[204:207], v[108:111]
	v_mfma_f32_16x16x32_bf16 v[96:99], v[136:139], v[218:221], v[96:99]
	v_mfma_f32_16x16x32_bf16 v[92:95], v[144:147], v[218:221], v[92:95]
	v_mfma_f32_16x16x32_bf16 v[80:83], v[136:139], v[228:231], v[80:83]
	v_mfma_f32_16x16x32_bf16 v[76:79], v[144:147], v[228:231], v[76:79]
	v_mfma_f32_16x16x32_bf16 v[120:123], v[148:151], v[174:177], v[120:123]
	v_mfma_f32_16x16x32_bf16 v[116:119], v[156:159], v[174:177], v[116:119]
	v_mfma_f32_16x16x32_bf16 v[104:107], v[148:151], v[200:203], v[104:107]
	v_mfma_f32_16x16x32_bf16 v[100:103], v[156:159], v[200:203], v[100:103]
	v_mfma_f32_16x16x32_bf16 v[88:91], v[148:151], v[208:211], v[88:91]
	v_mfma_f32_16x16x32_bf16 v[84:87], v[156:159], v[208:211], v[84:87]
	v_mfma_f32_16x16x32_bf16 v[72:75], v[148:151], v[224:227], v[72:75]
	v_mfma_f32_16x16x32_bf16 v[68:71], v[156:159], v[224:227], v[68:71]
	v_mfma_f32_16x16x32_bf16 v[120:123], v[152:155], v[196:199], v[120:123]
	v_mfma_f32_16x16x32_bf16 v[116:119], v[170:173], v[196:199], v[116:119]
	v_mfma_f32_16x16x32_bf16 v[104:107], v[152:155], v[204:207], v[104:107]
	v_mfma_f32_16x16x32_bf16 v[100:103], v[170:173], v[204:207], v[100:103]
	v_mfma_f32_16x16x32_bf16 v[88:91], v[152:155], v[218:221], v[88:91]
	v_mfma_f32_16x16x32_bf16 v[84:87], v[170:173], v[218:221], v[84:87]
	v_mfma_f32_16x16x32_bf16 v[72:75], v[152:155], v[228:231], v[72:75]
	v_mfma_f32_16x16x32_bf16 v[68:71], v[170:173], v[228:231], v[68:71]
	s_setprio 0
	s_barrier
	s_add_i32 s25, s25, s50
	v_lshl_add_u64 v[178:179], v[178:179], 0, s[94:95]
	s_mov_b32 m0, s25
	ds_read_b128 v[174:177], v194 offset:49152
	ds_read_b128 v[196:199], v194 offset:50176
	ds_read_b128 v[200:203], v194 offset:51200
	ds_read_b128 v[204:207], v194 offset:52224
	ds_read_b128 v[208:211], v194 offset:53248
	ds_read_b128 v[218:221], v194 offset:54272
	ds_read_b128 v[224:227], v194 offset:55296
	ds_read_b128 v[228:231], v194 offset:56320
	global_load_lds_dwordx4 v[178:179], off
	s_add_i32 m0, s25, 0x2000
	s_add_u32 s40, s46, 0x40080
	v_lshl_add_u64 v[178:179], v[182:183], 0, s[94:95]
	s_addc_u32 s41, s47, 0
	s_add_i32 s25, s70, s50
	global_load_lds_dwordx4 v[178:179], off
	v_lshl_add_u64 v[178:179], s[40:41], 0, v[162:163]
	s_mov_b32 m0, s25
	s_nop 0
	global_load_lds_dwordx4 v[178:179], off
	v_lshl_add_u64 v[178:179], s[40:41], 0, v[0:1]
	s_add_i32 m0, s25, 0x2000
	s_nop 0
	global_load_lds_dwordx4 v[178:179], off
	v_lshl_add_u64 v[178:179], v[184:185], 0, s[94:95]
	s_mov_b32 m0, s55
	s_nop 0
	global_load_lds_dwordx4 v[178:179], off
	v_lshl_add_u64 v[178:179], v[190:191], 0, s[94:95]
	s_mov_b32 m0, s58
	s_nop 0
	global_load_lds_dwordx4 v[178:179], off
	s_waitcnt vmcnt(8)
	s_waitcnt lgkmcnt(0)
	s_barrier
	s_setprio 1
	s_waitcnt lgkmcnt(0)
	v_mfma_f32_16x16x32_bf16 v[64:67], v[132:135], v[174:177], v[64:67]
	v_mfma_f32_16x16x32_bf16 v[60:63], v[140:143], v[174:177], v[60:63]
	v_mfma_f32_16x16x32_bf16 v[48:51], v[132:135], v[200:203], v[48:51]
	v_mfma_f32_16x16x32_bf16 v[44:47], v[140:143], v[200:203], v[44:47]
	v_mfma_f32_16x16x32_bf16 v[32:35], v[132:135], v[208:211], v[32:35]
	v_mfma_f32_16x16x32_bf16 v[28:31], v[140:143], v[208:211], v[28:31]
	v_mfma_f32_16x16x32_bf16 v[16:19], v[132:135], v[224:227], v[16:19]
	v_mfma_f32_16x16x32_bf16 v[12:15], v[140:143], v[224:227], v[12:15]
	v_mfma_f32_16x16x32_bf16 v[64:67], v[136:139], v[196:199], v[64:67]
	v_mfma_f32_16x16x32_bf16 v[60:63], v[144:147], v[196:199], v[60:63]
	v_mfma_f32_16x16x32_bf16 v[48:51], v[136:139], v[204:207], v[48:51]
	v_mfma_f32_16x16x32_bf16 v[44:47], v[144:147], v[204:207], v[44:47]
	v_mfma_f32_16x16x32_bf16 v[32:35], v[136:139], v[218:221], v[32:35]
	v_mfma_f32_16x16x32_bf16 v[28:31], v[144:147], v[218:221], v[28:31]
	v_mfma_f32_16x16x32_bf16 v[16:19], v[136:139], v[228:231], v[16:19]
	v_mfma_f32_16x16x32_bf16 v[12:15], v[144:147], v[228:231], v[12:15]
	v_mfma_f32_16x16x32_bf16 v[56:59], v[148:151], v[174:177], v[56:59]
	v_mfma_f32_16x16x32_bf16 v[52:55], v[156:159], v[174:177], v[52:55]
	v_mfma_f32_16x16x32_bf16 v[40:43], v[148:151], v[200:203], v[40:43]
	v_mfma_f32_16x16x32_bf16 v[36:39], v[156:159], v[200:203], v[36:39]
	v_mfma_f32_16x16x32_bf16 v[24:27], v[148:151], v[208:211], v[24:27]
	v_mfma_f32_16x16x32_bf16 v[20:23], v[156:159], v[208:211], v[20:23]
	v_mfma_f32_16x16x32_bf16 v[8:11], v[148:151], v[224:227], v[8:11]
	v_mfma_f32_16x16x32_bf16 v[4:7], v[156:159], v[224:227], v[4:7]
	v_mfma_f32_16x16x32_bf16 v[56:59], v[152:155], v[196:199], v[56:59]
	v_mfma_f32_16x16x32_bf16 v[52:55], v[170:173], v[196:199], v[52:55]
	v_mfma_f32_16x16x32_bf16 v[40:43], v[152:155], v[204:207], v[40:43]
	v_mfma_f32_16x16x32_bf16 v[36:39], v[170:173], v[204:207], v[36:39]
	v_mfma_f32_16x16x32_bf16 v[24:27], v[152:155], v[218:221], v[24:27]
	v_mfma_f32_16x16x32_bf16 v[20:23], v[170:173], v[218:221], v[20:23]
	v_mfma_f32_16x16x32_bf16 v[8:11], v[152:155], v[228:231], v[8:11]
	v_mfma_f32_16x16x32_bf16 v[4:7], v[170:173], v[228:231], v[4:7]
	s_setprio 0
	s_barrier
	s_add_i32 s88, s88, 2
	s_add_u32 s44, s44, 0x100
	s_addc_u32 s45, s45, 0
	s_add_u32 s68, s68, 0x100
	s_addc_u32 s69, s69, 0
	s_cmp_gt_u32 s88, 13
	s_cbranch_scc0 .LBB0_334
	s_and_b64 vcc, exec, s[12:13]
	s_cbranch_vccz .LBB0_337
	s_barrier

.LBB0_595:
	s_add_u32 s36, s26, 0x100
	s_addc_u32 s37, s27, 0
	s_add_i32 s40, 0, 0x10000
	s_cmp_eq_u32 s89, 40
	s_cselect_b32 s47, s9, s37
	s_cselect_b32 s46, s8, s36
	s_cselect_b32 s45, s19, s88
	s_cselect_b32 s44, s18, s69
	s_add_i32 s41, 0, 0x14000
	v_add_u32_e32 v144, s40, v170
	v_add_u32_e32 v168, s41, v170
	ds_read_b128 v[132:135], v144
	ds_read_b128 v[136:139], v144 offset:1024
	ds_read_b128 v[140:143], v144 offset:2048
	ds_read_b128 v[144:147], v144 offset:3072
	ds_read_b128 v[148:151], v168
	ds_read_b128 v[160:163], v168 offset:1024
	ds_read_b128 v[164:167], v168 offset:2048
	ds_read_b128 v[174:177], v168 offset:3072
	v_lshl_add_u64 v[168:169], s[26:27], 0, v[156:157]
	s_add_i32 m0, s49, 0xc000
	ds_read_b128 v[190:193], v172
	ds_read_b128 v[194:197], v172 offset:1024
	ds_read_b128 v[198:201], v172 offset:2048
	ds_read_b128 v[202:205], v172 offset:3072
	ds_read_b128 v[206:209], v172 offset:4096
	ds_read_b128 v[218:221], v172 offset:5120
	ds_read_b128 v[224:227], v172 offset:6144
	ds_read_b128 v[228:231], v172 offset:7168
	global_load_lds_dwordx4 v[168:169], off
	v_lshl_add_u64 v[168:169], s[26:27], 0, v[158:159]
	s_add_i32 m0, s49, 0xe000
	s_nop 0
	global_load_lds_dwordx4 v[168:169], off
	s_waitcnt vmcnt(8)
	s_waitcnt lgkmcnt(0)
	s_barrier
	s_setprio 1
	s_waitcnt lgkmcnt(0)
	v_mfma_f32_16x16x32_bf16 v[128:131], v[132:135], v[190:193], v[128:131]
	v_mfma_f32_16x16x32_bf16 v[124:127], v[140:143], v[190:193], v[124:127]
	v_mfma_f32_16x16x32_bf16 v[120:123], v[132:135], v[198:201], v[120:123]
	v_mfma_f32_16x16x32_bf16 v[116:119], v[140:143], v[198:201], v[116:119]
	v_mfma_f32_16x16x32_bf16 v[96:99], v[132:135], v[206:209], v[96:99]
	v_mfma_f32_16x16x32_bf16 v[92:95], v[140:143], v[206:209], v[92:95]
	v_mfma_f32_16x16x32_bf16 v[84:87], v[132:135], v[224:227], v[84:87]
	v_mfma_f32_16x16x32_bf16 v[76:79], v[140:143], v[224:227], v[76:79]
	v_mfma_f32_16x16x32_bf16 v[128:131], v[136:139], v[194:197], v[128:131]
	v_mfma_f32_16x16x32_bf16 v[124:127], v[144:147], v[194:197], v[124:127]
	v_mfma_f32_16x16x32_bf16 v[120:123], v[136:139], v[202:205], v[120:123]
	v_mfma_f32_16x16x32_bf16 v[116:119], v[144:147], v[202:205], v[116:119]
	v_mfma_f32_16x16x32_bf16 v[96:99], v[136:139], v[218:221], v[96:99]
	v_mfma_f32_16x16x32_bf16 v[92:95], v[144:147], v[218:221], v[92:95]
	v_mfma_f32_16x16x32_bf16 v[84:87], v[136:139], v[228:231], v[84:87]
	v_mfma_f32_16x16x32_bf16 v[76:79], v[144:147], v[228:231], v[76:79]
	v_mfma_f32_16x16x32_bf16 v[112:115], v[148:151], v[190:193], v[112:115]
	v_mfma_f32_16x16x32_bf16 v[108:111], v[164:167], v[190:193], v[108:111]
	v_mfma_f32_16x16x32_bf16 v[104:107], v[148:151], v[198:201], v[104:107]
	v_mfma_f32_16x16x32_bf16 v[100:103], v[164:167], v[198:201], v[100:103]
	v_mfma_f32_16x16x32_bf16 v[88:91], v[148:151], v[206:209], v[88:91]
	v_mfma_f32_16x16x32_bf16 v[80:83], v[164:167], v[206:209], v[80:83]
	v_mfma_f32_16x16x32_bf16 v[72:75], v[148:151], v[224:227], v[72:75]
	v_mfma_f32_16x16x32_bf16 v[68:71], v[164:167], v[224:227], v[68:71]
	v_mfma_f32_16x16x32_bf16 v[112:115], v[160:163], v[194:197], v[112:115]
	v_mfma_f32_16x16x32_bf16 v[108:111], v[174:177], v[194:197], v[108:111]
	v_mfma_f32_16x16x32_bf16 v[104:107], v[160:163], v[202:205], v[104:107]
	v_mfma_f32_16x16x32_bf16 v[100:103], v[174:177], v[202:205], v[100:103]
	v_mfma_f32_16x16x32_bf16 v[88:91], v[160:163], v[218:221], v[88:91]
	v_mfma_f32_16x16x32_bf16 v[80:83], v[174:177], v[218:221], v[80:83]
	v_mfma_f32_16x16x32_bf16 v[72:75], v[160:163], v[228:231], v[72:75]
	v_mfma_f32_16x16x32_bf16 v[68:71], v[174:177], v[228:231], v[68:71]
	s_setprio 0
	s_barrier
	s_add_i32 s26, s40, s48
	v_lshl_add_u64 v[168:169], s[44:45], 0, v[180:181]
	s_mov_b32 m0, s26
	ds_read_b128 v[190:193], v172 offset:16384
	ds_read_b128 v[194:197], v172 offset:17408
	ds_read_b128 v[198:201], v172 offset:18432
	ds_read_b128 v[202:205], v172 offset:19456
	ds_read_b128 v[206:209], v172 offset:20480
	ds_read_b128 v[218:221], v172 offset:21504
	ds_read_b128 v[224:227], v172 offset:22528
	ds_read_b128 v[228:231], v172 offset:23552
	global_load_lds_dwordx4 v[168:169], off
	s_add_i32 m0, s26, 0x2000
	s_add_u32 s26, s44, 0xb0000
	v_lshl_add_u64 v[178:179], s[44:45], 0, v[0:1]
	s_addc_u32 s27, s45, 0
	s_add_i32 s40, s41, s48
	global_load_lds_dwordx4 v[178:179], off
	v_lshl_add_u64 v[182:183], s[26:27], 0, v[180:181]
	s_mov_b32 m0, s40
	v_lshl_add_u64 v[184:185], s[46:47], 0, v[152:153]
	global_load_lds_dwordx4 v[182:183], off
	v_lshl_add_u64 v[182:183], s[26:27], 0, v[0:1]
	s_add_i32 m0, s40, 0x2000
	s_nop 0
	global_load_lds_dwordx4 v[182:183], off
	v_lshl_add_u64 v[182:183], s[46:47], 0, v[154:155]
	s_mov_b32 m0, s49
	s_nop 0
	global_load_lds_dwordx4 v[182:183], off
	s_mov_b32 m0, s50
	s_nop 0
	global_load_lds_dwordx4 v[184:185], off
	s_waitcnt vmcnt(8)
	s_waitcnt lgkmcnt(0)
	s_barrier
	s_setprio 1
	s_waitcnt lgkmcnt(0)
	v_mfma_f32_16x16x32_bf16 v[64:67], v[132:135], v[190:193], v[64:67]
	v_mfma_f32_16x16x32_bf16 v[60:63], v[140:143], v[190:193], v[60:63]
	v_mfma_f32_16x16x32_bf16 v[52:55], v[132:135], v[198:201], v[52:55]
	v_mfma_f32_16x16x32_bf16 v[44:47], v[140:143], v[198:201], v[44:47]
	v_mfma_f32_16x16x32_bf16 v[36:39], v[132:135], v[206:209], v[36:39]
	v_mfma_f32_16x16x32_bf16 v[28:31], v[140:143], v[206:209], v[28:31]
	v_mfma_f32_16x16x32_bf16 v[20:23], v[132:135], v[224:227], v[20:23]
	v_mfma_f32_16x16x32_bf16 v[12:15], v[140:143], v[224:227], v[12:15]
	v_mfma_f32_16x16x32_bf16 v[64:67], v[136:139], v[194:197], v[64:67]
	v_mfma_f32_16x16x32_bf16 v[60:63], v[144:147], v[194:197], v[60:63]
	v_mfma_f32_16x16x32_bf16 v[52:55], v[136:139], v[202:205], v[52:55]
	v_mfma_f32_16x16x32_bf16 v[44:47], v[144:147], v[202:205], v[44:47]
	v_mfma_f32_16x16x32_bf16 v[36:39], v[136:139], v[218:221], v[36:39]
	v_mfma_f32_16x16x32_bf16 v[28:31], v[144:147], v[218:221], v[28:31]
	v_mfma_f32_16x16x32_bf16 v[20:23], v[136:139], v[228:231], v[20:23]
	v_mfma_f32_16x16x32_bf16 v[12:15], v[144:147], v[228:231], v[12:15]
	v_mfma_f32_16x16x32_bf16 v[56:59], v[148:151], v[190:193], v[56:59]
	v_mfma_f32_16x16x32_bf16 v[48:51], v[164:167], v[190:193], v[48:51]
	v_mfma_f32_16x16x32_bf16 v[40:43], v[148:151], v[198:201], v[40:43]
	v_mfma_f32_16x16x32_bf16 v[32:35], v[164:167], v[198:201], v[32:35]
	v_mfma_f32_16x16x32_bf16 v[24:27], v[148:151], v[206:209], v[24:27]
	v_mfma_f32_16x16x32_bf16 v[16:19], v[164:167], v[206:209], v[16:19]
	v_mfma_f32_16x16x32_bf16 v[8:11], v[148:151], v[224:227], v[8:11]
	v_mfma_f32_16x16x32_bf16 v[4:7], v[164:167], v[224:227], v[4:7]
	v_mfma_f32_16x16x32_bf16 v[56:59], v[160:163], v[194:197], v[56:59]
	v_mfma_f32_16x16x32_bf16 v[48:51], v[174:177], v[194:197], v[48:51]
	v_mfma_f32_16x16x32_bf16 v[40:43], v[160:163], v[202:205], v[40:43]
	v_mfma_f32_16x16x32_bf16 v[32:35], v[174:177], v[202:205], v[32:35]
	v_mfma_f32_16x16x32_bf16 v[24:27], v[160:163], v[218:221], v[24:27]
	v_mfma_f32_16x16x32_bf16 v[16:19], v[174:177], v[218:221], v[16:19]
	v_mfma_f32_16x16x32_bf16 v[8:11], v[160:163], v[228:231], v[8:11]
	v_mfma_f32_16x16x32_bf16 v[4:7], v[174:177], v[228:231], v[4:7]
	s_setprio 0
	s_barrier
	s_add_i32 s40, 0, 0x18000
	s_add_i32 s41, 0, 0x1c000
	v_add_u32_e32 v144, s40, v170
	v_add_u32_e32 v173, s41, v170
	ds_read_b128 v[132:135], v144
	ds_read_b128 v[136:139], v144 offset:1024
	ds_read_b128 v[140:143], v144 offset:2048
	ds_read_b128 v[144:147], v144 offset:3072
	ds_read_b128 v[148:151], v173
	ds_read_b128 v[160:163], v173 offset:1024
	ds_read_b128 v[164:167], v173 offset:2048
	ds_read_b128 v[174:177], v173 offset:3072
	s_add_u32 s26, s46, 0xb0000
	s_addc_u32 s27, s47, 0
	s_mov_b32 m0, s51
	v_lshl_add_u64 v[210:211], s[26:27], 0, v[154:155]
	ds_read_b128 v[190:193], v172 offset:32768
	ds_read_b128 v[194:197], v172 offset:33792
	ds_read_b128 v[198:201], v172 offset:34816
	ds_read_b128 v[202:205], v172 offset:35840
	ds_read_b128 v[206:209], v172 offset:36864
	ds_read_b128 v[218:221], v172 offset:37888
	ds_read_b128 v[224:227], v172 offset:38912
	ds_read_b128 v[228:231], v172 offset:39936
	global_load_lds_dwordx4 v[210:211], off
	v_lshl_add_u64 v[210:211], s[26:27], 0, v[152:153]
	s_mov_b32 m0, s53
	s_nop 0
	global_load_lds_dwordx4 v[210:211], off
	s_waitcnt vmcnt(8)
	s_waitcnt lgkmcnt(0)
	s_barrier
	s_setprio 1
	s_waitcnt lgkmcnt(0)
	v_mfma_f32_16x16x32_bf16 v[128:131], v[132:135], v[190:193], v[128:131]
	v_mfma_f32_16x16x32_bf16 v[124:127], v[140:143], v[190:193], v[124:127]
	v_mfma_f32_16x16x32_bf16 v[120:123], v[132:135], v[198:201], v[120:123]
	v_mfma_f32_16x16x32_bf16 v[116:119], v[140:143], v[198:201], v[116:119]
	v_mfma_f32_16x16x32_bf16 v[96:99], v[132:135], v[206:209], v[96:99]
	v_mfma_f32_16x16x32_bf16 v[92:95], v[140:143], v[206:209], v[92:95]
	v_mfma_f32_16x16x32_bf16 v[84:87], v[132:135], v[224:227], v[84:87]
	v_mfma_f32_16x16x32_bf16 v[76:79], v[140:143], v[224:227], v[76:79]
	v_mfma_f32_16x16x32_bf16 v[128:131], v[136:139], v[194:197], v[128:131]
	v_mfma_f32_16x16x32_bf16 v[124:127], v[144:147], v[194:197], v[124:127]
	v_mfma_f32_16x16x32_bf16 v[120:123], v[136:139], v[202:205], v[120:123]
	v_mfma_f32_16x16x32_bf16 v[116:119], v[144:147], v[202:205], v[116:119]
	v_mfma_f32_16x16x32_bf16 v[96:99], v[136:139], v[218:221], v[96:99]
	v_mfma_f32_16x16x32_bf16 v[92:95], v[144:147], v[218:221], v[92:95]
	v_mfma_f32_16x16x32_bf16 v[84:87], v[136:139], v[228:231], v[84:87]
	v_mfma_f32_16x16x32_bf16 v[76:79], v[144:147], v[228:231], v[76:79]
	v_mfma_f32_16x16x32_bf16 v[112:115], v[148:151], v[190:193], v[112:115]
	v_mfma_f32_16x16x32_bf16 v[108:111], v[164:167], v[190:193], v[108:111]
	v_mfma_f32_16x16x32_bf16 v[104:107], v[148:151], v[198:201], v[104:107]
	v_mfma_f32_16x16x32_bf16 v[100:103], v[164:167], v[198:201], v[100:103]
	v_mfma_f32_16x16x32_bf16 v[88:91], v[148:151], v[206:209], v[88:91]
	v_mfma_f32_16x16x32_bf16 v[80:83], v[164:167], v[206:209], v[80:83]
	v_mfma_f32_16x16x32_bf16 v[72:75], v[148:151], v[224:227], v[72:75]
	v_mfma_f32_16x16x32_bf16 v[68:71], v[164:167], v[224:227], v[68:71]
	v_mfma_f32_16x16x32_bf16 v[112:115], v[160:163], v[194:197], v[112:115]
	v_mfma_f32_16x16x32_bf16 v[108:111], v[174:177], v[194:197], v[108:111]
	v_mfma_f32_16x16x32_bf16 v[104:107], v[160:163], v[202:205], v[104:107]
	v_mfma_f32_16x16x32_bf16 v[100:103], v[174:177], v[202:205], v[100:103]
	v_mfma_f32_16x16x32_bf16 v[88:91], v[160:163], v[218:221], v[88:91]
	v_mfma_f32_16x16x32_bf16 v[80:83], v[174:177], v[218:221], v[80:83]
	v_mfma_f32_16x16x32_bf16 v[72:75], v[160:163], v[228:231], v[72:75]
	v_mfma_f32_16x16x32_bf16 v[68:71], v[174:177], v[228:231], v[68:71]
	s_setprio 0
	s_barrier
	s_add_i32 s26, s40, s48
	v_lshl_add_u64 v[168:169], v[168:169], 0, s[94:95]
	s_mov_b32 m0, s26
	ds_read_b128 v[190:193], v172 offset:49152
	ds_read_b128 v[194:197], v172 offset:50176
	ds_read_b128 v[198:201], v172 offset:51200
	ds_read_b128 v[202:205], v172 offset:52224
	ds_read_b128 v[206:209], v172 offset:53248
	ds_read_b128 v[218:221], v172 offset:54272
	ds_read_b128 v[224:227], v172 offset:55296
	ds_read_b128 v[228:231], v172 offset:56320
	global_load_lds_dwordx4 v[168:169], off
	s_add_i32 m0, s26, 0x2000
	s_add_u32 s26, s44, 0xb0080
	v_lshl_add_u64 v[168:169], v[178:179], 0, s[94:95]
	s_addc_u32 s27, s45, 0
	s_add_i32 s40, s41, s48
	global_load_lds_dwordx4 v[168:169], off
	v_lshl_add_u64 v[168:169], s[26:27], 0, v[180:181]
	s_mov_b32 m0, s40
	s_nop 0
	global_load_lds_dwordx4 v[168:169], off
	v_lshl_add_u64 v[168:169], s[26:27], 0, v[0:1]
	s_add_i32 m0, s40, 0x2000
	s_nop 0
	global_load_lds_dwordx4 v[168:169], off
	v_lshl_add_u64 v[168:169], v[182:183], 0, s[94:95]
	s_mov_b32 m0, s54
	s_nop 0
	global_load_lds_dwordx4 v[168:169], off
	v_lshl_add_u64 v[168:169], v[184:185], 0, s[94:95]
	s_mov_b32 m0, s55
	s_nop 0
	global_load_lds_dwordx4 v[168:169], off
	s_waitcnt vmcnt(8)
	s_waitcnt lgkmcnt(0)
	s_barrier
	s_setprio 1
	s_waitcnt lgkmcnt(0)
	v_mfma_f32_16x16x32_bf16 v[64:67], v[132:135], v[190:193], v[64:67]
	v_mfma_f32_16x16x32_bf16 v[60:63], v[140:143], v[190:193], v[60:63]
	v_mfma_f32_16x16x32_bf16 v[52:55], v[132:135], v[198:201], v[52:55]
	v_mfma_f32_16x16x32_bf16 v[44:47], v[140:143], v[198:201], v[44:47]
	v_mfma_f32_16x16x32_bf16 v[36:39], v[132:135], v[206:209], v[36:39]
	v_mfma_f32_16x16x32_bf16 v[28:31], v[140:143], v[206:209], v[28:31]
	v_mfma_f32_16x16x32_bf16 v[20:23], v[132:135], v[224:227], v[20:23]
	v_mfma_f32_16x16x32_bf16 v[12:15], v[140:143], v[224:227], v[12:15]
	v_mfma_f32_16x16x32_bf16 v[64:67], v[136:139], v[194:197], v[64:67]
	v_mfma_f32_16x16x32_bf16 v[60:63], v[144:147], v[194:197], v[60:63]
	v_mfma_f32_16x16x32_bf16 v[52:55], v[136:139], v[202:205], v[52:55]
	v_mfma_f32_16x16x32_bf16 v[44:47], v[144:147], v[202:205], v[44:47]
	v_mfma_f32_16x16x32_bf16 v[36:39], v[136:139], v[218:221], v[36:39]
	v_mfma_f32_16x16x32_bf16 v[28:31], v[144:147], v[218:221], v[28:31]
	v_mfma_f32_16x16x32_bf16 v[20:23], v[136:139], v[228:231], v[20:23]
	v_mfma_f32_16x16x32_bf16 v[12:15], v[144:147], v[228:231], v[12:15]
	v_mfma_f32_16x16x32_bf16 v[56:59], v[148:151], v[190:193], v[56:59]
	v_mfma_f32_16x16x32_bf16 v[48:51], v[164:167], v[190:193], v[48:51]
	v_mfma_f32_16x16x32_bf16 v[40:43], v[148:151], v[198:201], v[40:43]
	v_mfma_f32_16x16x32_bf16 v[32:35], v[164:167], v[198:201], v[32:35]
	v_mfma_f32_16x16x32_bf16 v[24:27], v[148:151], v[206:209], v[24:27]
	v_mfma_f32_16x16x32_bf16 v[16:19], v[164:167], v[206:209], v[16:19]
	v_mfma_f32_16x16x32_bf16 v[8:11], v[148:151], v[224:227], v[8:11]
	v_mfma_f32_16x16x32_bf16 v[4:7], v[164:167], v[224:227], v[4:7]
	v_mfma_f32_16x16x32_bf16 v[56:59], v[160:163], v[194:197], v[56:59]
	v_mfma_f32_16x16x32_bf16 v[48:51], v[174:177], v[194:197], v[48:51]
	v_mfma_f32_16x16x32_bf16 v[40:43], v[160:163], v[202:205], v[40:43]
	v_mfma_f32_16x16x32_bf16 v[32:35], v[174:177], v[202:205], v[32:35]
	v_mfma_f32_16x16x32_bf16 v[24:27], v[160:163], v[218:221], v[24:27]
	v_mfma_f32_16x16x32_bf16 v[16:19], v[174:177], v[218:221], v[16:19]
	v_mfma_f32_16x16x32_bf16 v[8:11], v[160:163], v[228:231], v[8:11]
	v_mfma_f32_16x16x32_bf16 v[4:7], v[174:177], v[228:231], v[4:7]
	s_setprio 0
	s_barrier
	s_add_i32 s89, s89, 2
	s_add_u32 s69, s69, 0x100
	s_addc_u32 s88, s88, 0
	s_cmp_gt_u32 s89, 41
	s_mov_b64 s[26:27], s[36:37]
	s_cbranch_scc0 .LBB0_595
	s_and_b64 vcc, exec, s[16:17]
	s_cbranch_vccz .LBB0_598
	s_barrier

.LBB0_624:
	s_add_u32 s46, s44, 0x100
	s_addc_u32 s47, s45, 0
	s_add_i32 s40, 0, 0x10000
	s_cmp_eq_u32 s97, 40
	s_cselect_b32 s51, s13, s47
	s_cselect_b32 s50, s12, s46
	s_cselect_b32 s49, s37, s90
	s_cselect_b32 s48, s36, s89
	s_add_i32 s70, 0, 0x14000
	v_add_u32_e32 v144, s40, v187
	v_add_u32_e32 v170, s70, v187
	ds_read_b128 v[132:135], v144
	ds_read_b128 v[136:139], v144 offset:1024
	ds_read_b128 v[140:143], v144 offset:2048
	ds_read_b128 v[144:147], v144 offset:3072
	ds_read_b128 v[148:151], v170
	ds_read_b128 v[152:155], v170 offset:1024
	ds_read_b128 v[156:159], v170 offset:2048
	ds_read_b128 v[170:173], v170 offset:3072
	v_lshl_add_u64 v[178:179], s[44:45], 0, v[166:167]
	s_add_i32 m0, s54, 0xc000
	ds_read_b128 v[174:177], v194
	ds_read_b128 v[196:199], v194 offset:1024
	ds_read_b128 v[200:203], v194 offset:2048
	ds_read_b128 v[204:207], v194 offset:3072
	ds_read_b128 v[208:211], v194 offset:4096
	ds_read_b128 v[218:221], v194 offset:5120
	ds_read_b128 v[224:227], v194 offset:6144
	ds_read_b128 v[228:231], v194 offset:7168
	global_load_lds_dwordx4 v[178:179], off
	v_lshl_add_u64 v[178:179], s[44:45], 0, v[168:169]
	s_add_i32 m0, s54, 0xe000
	s_nop 0
	global_load_lds_dwordx4 v[178:179], off
	s_waitcnt vmcnt(8)
	s_waitcnt lgkmcnt(0)
	s_barrier
	s_setprio 1
	s_waitcnt lgkmcnt(0)
	v_mfma_f32_16x16x32_bf16 v[128:131], v[132:135], v[174:177], v[128:131]
	v_mfma_f32_16x16x32_bf16 v[124:127], v[140:143], v[174:177], v[124:127]
	v_mfma_f32_16x16x32_bf16 v[112:115], v[132:135], v[200:203], v[112:115]
	v_mfma_f32_16x16x32_bf16 v[108:111], v[140:143], v[200:203], v[108:111]
	v_mfma_f32_16x16x32_bf16 v[96:99], v[132:135], v[208:211], v[96:99]
	v_mfma_f32_16x16x32_bf16 v[92:95], v[140:143], v[208:211], v[92:95]
	v_mfma_f32_16x16x32_bf16 v[80:83], v[132:135], v[224:227], v[80:83]
	v_mfma_f32_16x16x32_bf16 v[76:79], v[140:143], v[224:227], v[76:79]
	v_mfma_f32_16x16x32_bf16 v[128:131], v[136:139], v[196:199], v[128:131]
	v_mfma_f32_16x16x32_bf16 v[124:127], v[144:147], v[196:199], v[124:127]
	v_mfma_f32_16x16x32_bf16 v[112:115], v[136:139], v[204:207], v[112:115]
	v_mfma_f32_16x16x32_bf16 v[108:111], v[144:147], v[204:207], v[108:111]
	v_mfma_f32_16x16x32_bf16 v[96:99], v[136:139], v[218:221], v[96:99]
	v_mfma_f32_16x16x32_bf16 v[92:95], v[144:147], v[218:221], v[92:95]
	v_mfma_f32_16x16x32_bf16 v[80:83], v[136:139], v[228:231], v[80:83]
	v_mfma_f32_16x16x32_bf16 v[76:79], v[144:147], v[228:231], v[76:79]
	v_mfma_f32_16x16x32_bf16 v[120:123], v[148:151], v[174:177], v[120:123]
	v_mfma_f32_16x16x32_bf16 v[116:119], v[156:159], v[174:177], v[116:119]
	v_mfma_f32_16x16x32_bf16 v[104:107], v[148:151], v[200:203], v[104:107]
	v_mfma_f32_16x16x32_bf16 v[100:103], v[156:159], v[200:203], v[100:103]
	v_mfma_f32_16x16x32_bf16 v[88:91], v[148:151], v[208:211], v[88:91]
	v_mfma_f32_16x16x32_bf16 v[84:87], v[156:159], v[208:211], v[84:87]
	v_mfma_f32_16x16x32_bf16 v[72:75], v[148:151], v[224:227], v[72:75]
	v_mfma_f32_16x16x32_bf16 v[68:71], v[156:159], v[224:227], v[68:71]
	v_mfma_f32_16x16x32_bf16 v[120:123], v[152:155], v[196:199], v[120:123]
	v_mfma_f32_16x16x32_bf16 v[116:119], v[170:173], v[196:199], v[116:119]
	v_mfma_f32_16x16x32_bf16 v[104:107], v[152:155], v[204:207], v[104:107]
	v_mfma_f32_16x16x32_bf16 v[100:103], v[170:173], v[204:207], v[100:103]
	v_mfma_f32_16x16x32_bf16 v[88:91], v[152:155], v[218:221], v[88:91]
	v_mfma_f32_16x16x32_bf16 v[84:87], v[170:173], v[218:221], v[84:87]
	v_mfma_f32_16x16x32_bf16 v[72:75], v[152:155], v[228:231], v[72:75]
	v_mfma_f32_16x16x32_bf16 v[68:71], v[170:173], v[228:231], v[68:71]
	s_setprio 0
	s_barrier
	s_add_i32 s40, s40, s53
	v_lshl_add_u64 v[178:179], s[48:49], 0, v[162:163]
	s_mov_b32 m0, s40
	ds_read_b128 v[174:177], v194 offset:16384
	ds_read_b128 v[196:199], v194 offset:17408
	ds_read_b128 v[200:203], v194 offset:18432
	ds_read_b128 v[204:207], v194 offset:19456
	ds_read_b128 v[208:211], v194 offset:20480
	ds_read_b128 v[218:221], v194 offset:21504
	ds_read_b128 v[224:227], v194 offset:22528
	ds_read_b128 v[228:231], v194 offset:23552
	global_load_lds_dwordx4 v[178:179], off
	s_add_i32 m0, s40, 0x2000
	s_add_u32 s40, s48, 0xb0000
	v_lshl_add_u64 v[182:183], s[48:49], 0, v[0:1]
	s_addc_u32 s41, s49, 0
	s_add_i32 s44, s70, s53
	global_load_lds_dwordx4 v[182:183], off
	v_lshl_add_u64 v[184:185], s[40:41], 0, v[162:163]
	s_mov_b32 m0, s44
	v_lshl_add_u64 v[190:191], s[50:51], 0, v[160:161]
	global_load_lds_dwordx4 v[184:185], off
	v_lshl_add_u64 v[184:185], s[40:41], 0, v[0:1]
	s_add_i32 m0, s44, 0x2000
	s_nop 0
	global_load_lds_dwordx4 v[184:185], off
	v_lshl_add_u64 v[184:185], s[50:51], 0, v[164:165]
	s_mov_b32 m0, s54
	s_nop 0
	global_load_lds_dwordx4 v[184:185], off
	s_mov_b32 m0, s55
	s_nop 0
	global_load_lds_dwordx4 v[190:191], off
	s_waitcnt vmcnt(8)
	s_waitcnt lgkmcnt(0)
	s_barrier
	s_setprio 1
	s_waitcnt lgkmcnt(0)
	v_mfma_f32_16x16x32_bf16 v[64:67], v[132:135], v[174:177], v[64:67]
	v_mfma_f32_16x16x32_bf16 v[60:63], v[140:143], v[174:177], v[60:63]
	v_mfma_f32_16x16x32_bf16 v[48:51], v[132:135], v[200:203], v[48:51]
	v_mfma_f32_16x16x32_bf16 v[44:47], v[140:143], v[200:203], v[44:47]
	v_mfma_f32_16x16x32_bf16 v[32:35], v[132:135], v[208:211], v[32:35]
	v_mfma_f32_16x16x32_bf16 v[28:31], v[140:143], v[208:211], v[28:31]
	v_mfma_f32_16x16x32_bf16 v[16:19], v[132:135], v[224:227], v[16:19]
	v_mfma_f32_16x16x32_bf16 v[12:15], v[140:143], v[224:227], v[12:15]
	v_mfma_f32_16x16x32_bf16 v[64:67], v[136:139], v[196:199], v[64:67]
	v_mfma_f32_16x16x32_bf16 v[60:63], v[144:147], v[196:199], v[60:63]
	v_mfma_f32_16x16x32_bf16 v[48:51], v[136:139], v[204:207], v[48:51]
	v_mfma_f32_16x16x32_bf16 v[44:47], v[144:147], v[204:207], v[44:47]
	v_mfma_f32_16x16x32_bf16 v[32:35], v[136:139], v[218:221], v[32:35]
	v_mfma_f32_16x16x32_bf16 v[28:31], v[144:147], v[218:221], v[28:31]
	v_mfma_f32_16x16x32_bf16 v[16:19], v[136:139], v[228:231], v[16:19]
	v_mfma_f32_16x16x32_bf16 v[12:15], v[144:147], v[228:231], v[12:15]
	v_mfma_f32_16x16x32_bf16 v[56:59], v[148:151], v[174:177], v[56:59]
	v_mfma_f32_16x16x32_bf16 v[52:55], v[156:159], v[174:177], v[52:55]
	v_mfma_f32_16x16x32_bf16 v[40:43], v[148:151], v[200:203], v[40:43]
	v_mfma_f32_16x16x32_bf16 v[36:39], v[156:159], v[200:203], v[36:39]
	v_mfma_f32_16x16x32_bf16 v[24:27], v[148:151], v[208:211], v[24:27]
	v_mfma_f32_16x16x32_bf16 v[20:23], v[156:159], v[208:211], v[20:23]
	v_mfma_f32_16x16x32_bf16 v[8:11], v[148:151], v[224:227], v[8:11]
	v_mfma_f32_16x16x32_bf16 v[4:7], v[156:159], v[224:227], v[4:7]
	v_mfma_f32_16x16x32_bf16 v[56:59], v[152:155], v[196:199], v[56:59]
	v_mfma_f32_16x16x32_bf16 v[52:55], v[170:173], v[196:199], v[52:55]
	v_mfma_f32_16x16x32_bf16 v[40:43], v[152:155], v[204:207], v[40:43]
	v_mfma_f32_16x16x32_bf16 v[36:39], v[170:173], v[204:207], v[36:39]
	v_mfma_f32_16x16x32_bf16 v[24:27], v[152:155], v[218:221], v[24:27]
	v_mfma_f32_16x16x32_bf16 v[20:23], v[170:173], v[218:221], v[20:23]
	v_mfma_f32_16x16x32_bf16 v[8:11], v[152:155], v[228:231], v[8:11]
	v_mfma_f32_16x16x32_bf16 v[4:7], v[170:173], v[228:231], v[4:7]
	s_setprio 0
	s_barrier
	s_add_i32 s44, 0, 0x18000
	s_add_i32 s45, 0, 0x1c000
	v_add_u32_e32 v144, s44, v187
	v_add_u32_e32 v170, s45, v187
	ds_read_b128 v[132:135], v144
	ds_read_b128 v[136:139], v144 offset:1024
	ds_read_b128 v[140:143], v144 offset:2048
	ds_read_b128 v[144:147], v144 offset:3072
	ds_read_b128 v[148:151], v170
	ds_read_b128 v[152:155], v170 offset:1024
	ds_read_b128 v[156:159], v170 offset:2048
	ds_read_b128 v[170:173], v170 offset:3072
	s_add_u32 s40, s50, 0xb0000
	s_addc_u32 s41, s51, 0
	s_mov_b32 m0, s58
	v_lshl_add_u64 v[232:233], s[40:41], 0, v[164:165]
	ds_read_b128 v[174:177], v194 offset:32768
	ds_read_b128 v[196:199], v194 offset:33792
	ds_read_b128 v[200:203], v194 offset:34816
	ds_read_b128 v[204:207], v194 offset:35840
	ds_read_b128 v[208:211], v194 offset:36864
	ds_read_b128 v[218:221], v194 offset:37888
	ds_read_b128 v[224:227], v194 offset:38912
	ds_read_b128 v[228:231], v194 offset:39936
	global_load_lds_dwordx4 v[232:233], off
	v_lshl_add_u64 v[232:233], s[40:41], 0, v[160:161]
	s_mov_b32 m0, s59
	s_nop 0
	global_load_lds_dwordx4 v[232:233], off
	s_waitcnt vmcnt(8)
	s_waitcnt lgkmcnt(0)
	s_barrier
	s_setprio 1
	s_waitcnt lgkmcnt(0)
	v_mfma_f32_16x16x32_bf16 v[128:131], v[132:135], v[174:177], v[128:131]
	v_mfma_f32_16x16x32_bf16 v[124:127], v[140:143], v[174:177], v[124:127]
	v_mfma_f32_16x16x32_bf16 v[112:115], v[132:135], v[200:203], v[112:115]
	v_mfma_f32_16x16x32_bf16 v[108:111], v[140:143], v[200:203], v[108:111]
	v_mfma_f32_16x16x32_bf16 v[96:99], v[132:135], v[208:211], v[96:99]
	v_mfma_f32_16x16x32_bf16 v[92:95], v[140:143], v[208:211], v[92:95]
	v_mfma_f32_16x16x32_bf16 v[80:83], v[132:135], v[224:227], v[80:83]
	v_mfma_f32_16x16x32_bf16 v[76:79], v[140:143], v[224:227], v[76:79]
	v_mfma_f32_16x16x32_bf16 v[128:131], v[136:139], v[196:199], v[128:131]
	v_mfma_f32_16x16x32_bf16 v[124:127], v[144:147], v[196:199], v[124:127]
	v_mfma_f32_16x16x32_bf16 v[112:115], v[136:139], v[204:207], v[112:115]
	v_mfma_f32_16x16x32_bf16 v[108:111], v[144:147], v[204:207], v[108:111]
	v_mfma_f32_16x16x32_bf16 v[96:99], v[136:139], v[218:221], v[96:99]
	v_mfma_f32_16x16x32_bf16 v[92:95], v[144:147], v[218:221], v[92:95]
	v_mfma_f32_16x16x32_bf16 v[80:83], v[136:139], v[228:231], v[80:83]
	v_mfma_f32_16x16x32_bf16 v[76:79], v[144:147], v[228:231], v[76:79]
	v_mfma_f32_16x16x32_bf16 v[120:123], v[148:151], v[174:177], v[120:123]
	v_mfma_f32_16x16x32_bf16 v[116:119], v[156:159], v[174:177], v[116:119]
	v_mfma_f32_16x16x32_bf16 v[104:107], v[148:151], v[200:203], v[104:107]
	v_mfma_f32_16x16x32_bf16 v[100:103], v[156:159], v[200:203], v[100:103]
	v_mfma_f32_16x16x32_bf16 v[88:91], v[148:151], v[208:211], v[88:91]
	v_mfma_f32_16x16x32_bf16 v[84:87], v[156:159], v[208:211], v[84:87]
	v_mfma_f32_16x16x32_bf16 v[72:75], v[148:151], v[224:227], v[72:75]
	v_mfma_f32_16x16x32_bf16 v[68:71], v[156:159], v[224:227], v[68:71]
	v_mfma_f32_16x16x32_bf16 v[120:123], v[152:155], v[196:199], v[120:123]
	v_mfma_f32_16x16x32_bf16 v[116:119], v[170:173], v[196:199], v[116:119]
	v_mfma_f32_16x16x32_bf16 v[104:107], v[152:155], v[204:207], v[104:107]
	v_mfma_f32_16x16x32_bf16 v[100:103], v[170:173], v[204:207], v[100:103]
	v_mfma_f32_16x16x32_bf16 v[88:91], v[152:155], v[218:221], v[88:91]
	v_mfma_f32_16x16x32_bf16 v[84:87], v[170:173], v[218:221], v[84:87]
	v_mfma_f32_16x16x32_bf16 v[72:75], v[152:155], v[228:231], v[72:75]
	v_mfma_f32_16x16x32_bf16 v[68:71], v[170:173], v[228:231], v[68:71]
	s_setprio 0
	s_barrier
	s_add_i32 s40, s44, s53
	v_lshl_add_u64 v[178:179], v[178:179], 0, s[94:95]
	s_mov_b32 m0, s40
	ds_read_b128 v[174:177], v194 offset:49152
	ds_read_b128 v[196:199], v194 offset:50176
	ds_read_b128 v[200:203], v194 offset:51200
	ds_read_b128 v[204:207], v194 offset:52224
	ds_read_b128 v[208:211], v194 offset:53248
	ds_read_b128 v[218:221], v194 offset:54272
	ds_read_b128 v[224:227], v194 offset:55296
	ds_read_b128 v[228:231], v194 offset:56320
	global_load_lds_dwordx4 v[178:179], off
	s_add_i32 m0, s40, 0x2000
	s_add_u32 s40, s48, 0xb0080
	v_lshl_add_u64 v[178:179], v[182:183], 0, s[94:95]
	s_addc_u32 s41, s49, 0
	s_add_i32 s44, s45, s53
	global_load_lds_dwordx4 v[178:179], off
	v_lshl_add_u64 v[178:179], s[40:41], 0, v[162:163]
	s_mov_b32 m0, s44
	s_nop 0
	global_load_lds_dwordx4 v[178:179], off
	v_lshl_add_u64 v[178:179], s[40:41], 0, v[0:1]
	s_add_i32 m0, s44, 0x2000
	s_nop 0
	global_load_lds_dwordx4 v[178:179], off
	v_lshl_add_u64 v[178:179], v[184:185], 0, s[94:95]
	s_mov_b32 m0, s64
	s_nop 0
	global_load_lds_dwordx4 v[178:179], off
	v_lshl_add_u64 v[178:179], v[190:191], 0, s[94:95]
	s_mov_b32 m0, s65
	s_nop 0
	global_load_lds_dwordx4 v[178:179], off
	s_waitcnt vmcnt(8)
	s_waitcnt lgkmcnt(0)
	s_barrier
	s_setprio 1
	s_waitcnt lgkmcnt(0)
	v_mfma_f32_16x16x32_bf16 v[64:67], v[132:135], v[174:177], v[64:67]
	v_mfma_f32_16x16x32_bf16 v[60:63], v[140:143], v[174:177], v[60:63]
	v_mfma_f32_16x16x32_bf16 v[48:51], v[132:135], v[200:203], v[48:51]
	v_mfma_f32_16x16x32_bf16 v[44:47], v[140:143], v[200:203], v[44:47]
	v_mfma_f32_16x16x32_bf16 v[32:35], v[132:135], v[208:211], v[32:35]
	v_mfma_f32_16x16x32_bf16 v[28:31], v[140:143], v[208:211], v[28:31]
	v_mfma_f32_16x16x32_bf16 v[16:19], v[132:135], v[224:227], v[16:19]
	v_mfma_f32_16x16x32_bf16 v[12:15], v[140:143], v[224:227], v[12:15]
	v_mfma_f32_16x16x32_bf16 v[64:67], v[136:139], v[196:199], v[64:67]
	v_mfma_f32_16x16x32_bf16 v[60:63], v[144:147], v[196:199], v[60:63]
	v_mfma_f32_16x16x32_bf16 v[48:51], v[136:139], v[204:207], v[48:51]
	v_mfma_f32_16x16x32_bf16 v[44:47], v[144:147], v[204:207], v[44:47]
	v_mfma_f32_16x16x32_bf16 v[32:35], v[136:139], v[218:221], v[32:35]
	v_mfma_f32_16x16x32_bf16 v[28:31], v[144:147], v[218:221], v[28:31]
	v_mfma_f32_16x16x32_bf16 v[16:19], v[136:139], v[228:231], v[16:19]
	v_mfma_f32_16x16x32_bf16 v[12:15], v[144:147], v[228:231], v[12:15]
	v_mfma_f32_16x16x32_bf16 v[56:59], v[148:151], v[174:177], v[56:59]
	v_mfma_f32_16x16x32_bf16 v[52:55], v[156:159], v[174:177], v[52:55]
	v_mfma_f32_16x16x32_bf16 v[40:43], v[148:151], v[200:203], v[40:43]
	v_mfma_f32_16x16x32_bf16 v[36:39], v[156:159], v[200:203], v[36:39]
	v_mfma_f32_16x16x32_bf16 v[24:27], v[148:151], v[208:211], v[24:27]
	v_mfma_f32_16x16x32_bf16 v[20:23], v[156:159], v[208:211], v[20:23]
	v_mfma_f32_16x16x32_bf16 v[8:11], v[148:151], v[224:227], v[8:11]
	v_mfma_f32_16x16x32_bf16 v[4:7], v[156:159], v[224:227], v[4:7]
	v_mfma_f32_16x16x32_bf16 v[56:59], v[152:155], v[196:199], v[56:59]
	v_mfma_f32_16x16x32_bf16 v[52:55], v[170:173], v[196:199], v[52:55]
	v_mfma_f32_16x16x32_bf16 v[40:43], v[152:155], v[204:207], v[40:43]
	v_mfma_f32_16x16x32_bf16 v[36:39], v[170:173], v[204:207], v[36:39]
	v_mfma_f32_16x16x32_bf16 v[24:27], v[152:155], v[218:221], v[24:27]
	v_mfma_f32_16x16x32_bf16 v[20:23], v[170:173], v[218:221], v[20:23]
	v_mfma_f32_16x16x32_bf16 v[8:11], v[152:155], v[228:231], v[8:11]
	v_mfma_f32_16x16x32_bf16 v[4:7], v[170:173], v[228:231], v[4:7]
	s_setprio 0
	s_barrier
	s_add_i32 s97, s97, 2
	s_add_u32 s89, s89, 0x100
	s_addc_u32 s90, s90, 0
	s_cmp_gt_u32 s97, 41
	s_mov_b64 s[44:45], s[46:47]
	s_cbranch_scc0 .LBB0_624
	s_and_b64 vcc, exec, s[18:19]
	s_cbranch_vccz .LBB0_627
	s_barrier

.LBB0_668:
	s_add_u32 s36, s26, 0x100
	s_addc_u32 s37, s27, 0
	s_add_i32 s40, 0, 0x10000
	s_cmp_eq_u32 s69, 40
	s_cselect_b32 s47, s11, s37
	s_cselect_b32 s46, s10, s36
	s_cselect_b32 s45, s19, s68
	s_cselect_b32 s44, s18, s65
	s_add_i32 s41, 0, 0x14000
	v_add_u32_e32 v144, s40, v187
	v_add_u32_e32 v160, s41, v187
	ds_read_b128 v[132:135], v144
	ds_read_b128 v[136:139], v144 offset:1024
	ds_read_b128 v[140:143], v144 offset:2048
	ds_read_b128 v[144:147], v144 offset:3072
	ds_read_b128 v[148:151], v160
	ds_read_b128 v[152:155], v160 offset:1024
	ds_read_b128 v[156:159], v160 offset:2048
	ds_read_b128 v[160:163], v160 offset:3072
	v_lshl_add_u64 v[182:183], s[26:27], 0, v[196:197]
	s_add_i32 m0, s49, 0xc000
	ds_read_b128 v[164:167], v229
	ds_read_b128 v[168:171], v229 offset:1024
	ds_read_b128 v[172:175], v229 offset:2048
	ds_read_b128 v[176:179], v229 offset:3072
	ds_read_b128 v[200:203], v229 offset:4096
	ds_read_b128 v[204:207], v229 offset:5120
	ds_read_b128 v[208:211], v229 offset:6144
	ds_read_b128 v[218:221], v229 offset:7168
	global_load_lds_dwordx4 v[182:183], off
	v_lshl_add_u64 v[182:183], s[26:27], 0, v[198:199]
	s_add_i32 m0, s49, 0xe000
	s_nop 0
	global_load_lds_dwordx4 v[182:183], off
	s_waitcnt vmcnt(8)
	s_waitcnt lgkmcnt(0)
	s_barrier
	s_setprio 1
	s_waitcnt lgkmcnt(0)
	v_mfma_f32_16x16x32_bf16 v[128:131], v[132:135], v[164:167], v[128:131]
	v_mfma_f32_16x16x32_bf16 v[124:127], v[140:143], v[164:167], v[124:127]
	v_mfma_f32_16x16x32_bf16 v[112:115], v[132:135], v[172:175], v[112:115]
	v_mfma_f32_16x16x32_bf16 v[108:111], v[140:143], v[172:175], v[108:111]
	v_mfma_f32_16x16x32_bf16 v[96:99], v[132:135], v[200:203], v[96:99]
	v_mfma_f32_16x16x32_bf16 v[92:95], v[140:143], v[200:203], v[92:95]
	v_mfma_f32_16x16x32_bf16 v[80:83], v[132:135], v[208:211], v[80:83]
	v_mfma_f32_16x16x32_bf16 v[76:79], v[140:143], v[208:211], v[76:79]
	v_mfma_f32_16x16x32_bf16 v[128:131], v[136:139], v[168:171], v[128:131]
	v_mfma_f32_16x16x32_bf16 v[124:127], v[144:147], v[168:171], v[124:127]
	v_mfma_f32_16x16x32_bf16 v[112:115], v[136:139], v[176:179], v[112:115]
	v_mfma_f32_16x16x32_bf16 v[108:111], v[144:147], v[176:179], v[108:111]
	v_mfma_f32_16x16x32_bf16 v[96:99], v[136:139], v[204:207], v[96:99]
	v_mfma_f32_16x16x32_bf16 v[92:95], v[144:147], v[204:207], v[92:95]
	v_mfma_f32_16x16x32_bf16 v[80:83], v[136:139], v[218:221], v[80:83]
	v_mfma_f32_16x16x32_bf16 v[76:79], v[144:147], v[218:221], v[76:79]
	v_mfma_f32_16x16x32_bf16 v[120:123], v[148:151], v[164:167], v[120:123]
	v_mfma_f32_16x16x32_bf16 v[116:119], v[156:159], v[164:167], v[116:119]
	v_mfma_f32_16x16x32_bf16 v[104:107], v[148:151], v[172:175], v[104:107]
	v_mfma_f32_16x16x32_bf16 v[100:103], v[156:159], v[172:175], v[100:103]
	v_mfma_f32_16x16x32_bf16 v[88:91], v[148:151], v[200:203], v[88:91]
	v_mfma_f32_16x16x32_bf16 v[84:87], v[156:159], v[200:203], v[84:87]
	v_mfma_f32_16x16x32_bf16 v[72:75], v[148:151], v[208:211], v[72:75]
	v_mfma_f32_16x16x32_bf16 v[68:71], v[156:159], v[208:211], v[68:71]
	v_mfma_f32_16x16x32_bf16 v[120:123], v[152:155], v[168:171], v[120:123]
	v_mfma_f32_16x16x32_bf16 v[116:119], v[160:163], v[168:171], v[116:119]
	v_mfma_f32_16x16x32_bf16 v[104:107], v[152:155], v[176:179], v[104:107]
	v_mfma_f32_16x16x32_bf16 v[100:103], v[160:163], v[176:179], v[100:103]
	v_mfma_f32_16x16x32_bf16 v[88:91], v[152:155], v[204:207], v[88:91]
	v_mfma_f32_16x16x32_bf16 v[84:87], v[160:163], v[204:207], v[84:87]
	v_mfma_f32_16x16x32_bf16 v[72:75], v[152:155], v[218:221], v[72:75]
	v_mfma_f32_16x16x32_bf16 v[68:71], v[160:163], v[218:221], v[68:71]
	s_setprio 0
	s_barrier
	s_add_i32 s26, s40, s48
	v_lshl_add_u64 v[182:183], s[44:45], 0, v[192:193]
	s_mov_b32 m0, s26
	ds_read_b128 v[164:167], v229 offset:16384
	ds_read_b128 v[168:171], v229 offset:17408
	ds_read_b128 v[172:175], v229 offset:18432
	ds_read_b128 v[176:179], v229 offset:19456
	ds_read_b128 v[200:203], v229 offset:20480
	ds_read_b128 v[204:207], v229 offset:21504
	ds_read_b128 v[208:211], v229 offset:22528
	ds_read_b128 v[218:221], v229 offset:23552
	global_load_lds_dwordx4 v[182:183], off
	s_add_i32 m0, s26, 0x2000
	s_add_u32 s26, s44, 0xb0000
	v_lshl_add_u64 v[184:185], s[44:45], 0, v[0:1]
	s_addc_u32 s27, s45, 0
	s_add_i32 s40, s41, s48
	global_load_lds_dwordx4 v[184:185], off
	v_lshl_add_u64 v[224:225], s[26:27], 0, v[192:193]
	s_mov_b32 m0, s40
	v_lshl_add_u64 v[230:231], s[46:47], 0, v[190:191]
	global_load_lds_dwordx4 v[224:225], off
	v_lshl_add_u64 v[224:225], s[26:27], 0, v[0:1]
	s_add_i32 m0, s40, 0x2000
	s_nop 0
	global_load_lds_dwordx4 v[224:225], off
	v_lshl_add_u64 v[224:225], s[46:47], 0, v[194:195]
	s_mov_b32 m0, s49
	s_nop 0
	global_load_lds_dwordx4 v[224:225], off
	s_mov_b32 m0, s50
	s_nop 0
	global_load_lds_dwordx4 v[230:231], off
	s_waitcnt vmcnt(8)
	s_waitcnt lgkmcnt(0)
	s_barrier
	s_setprio 1
	s_waitcnt lgkmcnt(0)
	v_mfma_f32_16x16x32_bf16 v[64:67], v[132:135], v[164:167], v[64:67]
	v_mfma_f32_16x16x32_bf16 v[60:63], v[140:143], v[164:167], v[60:63]
	v_mfma_f32_16x16x32_bf16 v[48:51], v[132:135], v[172:175], v[48:51]
	v_mfma_f32_16x16x32_bf16 v[44:47], v[140:143], v[172:175], v[44:47]
	v_mfma_f32_16x16x32_bf16 v[32:35], v[132:135], v[200:203], v[32:35]
	v_mfma_f32_16x16x32_bf16 v[28:31], v[140:143], v[200:203], v[28:31]
	v_mfma_f32_16x16x32_bf16 v[16:19], v[132:135], v[208:211], v[16:19]
	v_mfma_f32_16x16x32_bf16 v[12:15], v[140:143], v[208:211], v[12:15]
	v_mfma_f32_16x16x32_bf16 v[64:67], v[136:139], v[168:171], v[64:67]
	v_mfma_f32_16x16x32_bf16 v[60:63], v[144:147], v[168:171], v[60:63]
	v_mfma_f32_16x16x32_bf16 v[48:51], v[136:139], v[176:179], v[48:51]
	v_mfma_f32_16x16x32_bf16 v[44:47], v[144:147], v[176:179], v[44:47]
	v_mfma_f32_16x16x32_bf16 v[32:35], v[136:139], v[204:207], v[32:35]
	v_mfma_f32_16x16x32_bf16 v[28:31], v[144:147], v[204:207], v[28:31]
	v_mfma_f32_16x16x32_bf16 v[16:19], v[136:139], v[218:221], v[16:19]
	v_mfma_f32_16x16x32_bf16 v[12:15], v[144:147], v[218:221], v[12:15]
	v_mfma_f32_16x16x32_bf16 v[56:59], v[148:151], v[164:167], v[56:59]
	v_mfma_f32_16x16x32_bf16 v[52:55], v[156:159], v[164:167], v[52:55]
	v_mfma_f32_16x16x32_bf16 v[40:43], v[148:151], v[172:175], v[40:43]
	v_mfma_f32_16x16x32_bf16 v[36:39], v[156:159], v[172:175], v[36:39]
	v_mfma_f32_16x16x32_bf16 v[24:27], v[148:151], v[200:203], v[24:27]
	v_mfma_f32_16x16x32_bf16 v[20:23], v[156:159], v[200:203], v[20:23]
	v_mfma_f32_16x16x32_bf16 v[8:11], v[148:151], v[208:211], v[8:11]
	v_mfma_f32_16x16x32_bf16 v[4:7], v[156:159], v[208:211], v[4:7]
	v_mfma_f32_16x16x32_bf16 v[56:59], v[152:155], v[168:171], v[56:59]
	v_mfma_f32_16x16x32_bf16 v[52:55], v[160:163], v[168:171], v[52:55]
	v_mfma_f32_16x16x32_bf16 v[40:43], v[152:155], v[176:179], v[40:43]
	v_mfma_f32_16x16x32_bf16 v[36:39], v[160:163], v[176:179], v[36:39]
	v_mfma_f32_16x16x32_bf16 v[24:27], v[152:155], v[204:207], v[24:27]
	v_mfma_f32_16x16x32_bf16 v[20:23], v[160:163], v[204:207], v[20:23]
	v_mfma_f32_16x16x32_bf16 v[8:11], v[152:155], v[218:221], v[8:11]
	v_mfma_f32_16x16x32_bf16 v[4:7], v[160:163], v[218:221], v[4:7]
	s_setprio 0
	s_barrier
	s_add_i32 s40, 0, 0x18000
	s_add_i32 s41, 0, 0x1c000
	v_add_u32_e32 v144, s40, v187
	v_add_u32_e32 v160, s41, v187
	ds_read_b128 v[132:135], v144
	ds_read_b128 v[136:139], v144 offset:1024
	ds_read_b128 v[140:143], v144 offset:2048
	ds_read_b128 v[144:147], v144 offset:3072
	ds_read_b128 v[148:151], v160
	ds_read_b128 v[152:155], v160 offset:1024
	ds_read_b128 v[156:159], v160 offset:2048
	ds_read_b128 v[160:163], v160 offset:3072
	s_add_u32 s26, s46, 0xb0000
	s_addc_u32 s27, s47, 0
	s_mov_b32 m0, s51
	v_lshl_add_u64 v[232:233], s[26:27], 0, v[194:195]
	ds_read_b128 v[164:167], v229 offset:32768
	ds_read_b128 v[168:171], v229 offset:33792
	ds_read_b128 v[172:175], v229 offset:34816
	ds_read_b128 v[176:179], v229 offset:35840
	ds_read_b128 v[200:203], v229 offset:36864
	ds_read_b128 v[204:207], v229 offset:37888
	ds_read_b128 v[208:211], v229 offset:38912
	ds_read_b128 v[218:221], v229 offset:39936
	global_load_lds_dwordx4 v[232:233], off
	v_lshl_add_u64 v[232:233], s[26:27], 0, v[190:191]
	s_mov_b32 m0, s53
	s_nop 0
	global_load_lds_dwordx4 v[232:233], off
	s_waitcnt vmcnt(8)
	s_waitcnt lgkmcnt(0)
	s_barrier
	s_setprio 1
	s_waitcnt lgkmcnt(0)
	v_mfma_f32_16x16x32_bf16 v[128:131], v[132:135], v[164:167], v[128:131]
	v_mfma_f32_16x16x32_bf16 v[124:127], v[140:143], v[164:167], v[124:127]
	v_mfma_f32_16x16x32_bf16 v[112:115], v[132:135], v[172:175], v[112:115]
	v_mfma_f32_16x16x32_bf16 v[108:111], v[140:143], v[172:175], v[108:111]
	v_mfma_f32_16x16x32_bf16 v[96:99], v[132:135], v[200:203], v[96:99]
	v_mfma_f32_16x16x32_bf16 v[92:95], v[140:143], v[200:203], v[92:95]
	v_mfma_f32_16x16x32_bf16 v[80:83], v[132:135], v[208:211], v[80:83]
	v_mfma_f32_16x16x32_bf16 v[76:79], v[140:143], v[208:211], v[76:79]
	v_mfma_f32_16x16x32_bf16 v[128:131], v[136:139], v[168:171], v[128:131]
	v_mfma_f32_16x16x32_bf16 v[124:127], v[144:147], v[168:171], v[124:127]
	v_mfma_f32_16x16x32_bf16 v[112:115], v[136:139], v[176:179], v[112:115]
	v_mfma_f32_16x16x32_bf16 v[108:111], v[144:147], v[176:179], v[108:111]
	v_mfma_f32_16x16x32_bf16 v[96:99], v[136:139], v[204:207], v[96:99]
	v_mfma_f32_16x16x32_bf16 v[92:95], v[144:147], v[204:207], v[92:95]
	v_mfma_f32_16x16x32_bf16 v[80:83], v[136:139], v[218:221], v[80:83]
	v_mfma_f32_16x16x32_bf16 v[76:79], v[144:147], v[218:221], v[76:79]
	v_mfma_f32_16x16x32_bf16 v[120:123], v[148:151], v[164:167], v[120:123]
	v_mfma_f32_16x16x32_bf16 v[116:119], v[156:159], v[164:167], v[116:119]
	v_mfma_f32_16x16x32_bf16 v[104:107], v[148:151], v[172:175], v[104:107]
	v_mfma_f32_16x16x32_bf16 v[100:103], v[156:159], v[172:175], v[100:103]
	v_mfma_f32_16x16x32_bf16 v[88:91], v[148:151], v[200:203], v[88:91]
	v_mfma_f32_16x16x32_bf16 v[84:87], v[156:159], v[200:203], v[84:87]
	v_mfma_f32_16x16x32_bf16 v[72:75], v[148:151], v[208:211], v[72:75]
	v_mfma_f32_16x16x32_bf16 v[68:71], v[156:159], v[208:211], v[68:71]
	v_mfma_f32_16x16x32_bf16 v[120:123], v[152:155], v[168:171], v[120:123]
	v_mfma_f32_16x16x32_bf16 v[116:119], v[160:163], v[168:171], v[116:119]
	v_mfma_f32_16x16x32_bf16 v[104:107], v[152:155], v[176:179], v[104:107]
	v_mfma_f32_16x16x32_bf16 v[100:103], v[160:163], v[176:179], v[100:103]
	v_mfma_f32_16x16x32_bf16 v[88:91], v[152:155], v[204:207], v[88:91]
	v_mfma_f32_16x16x32_bf16 v[84:87], v[160:163], v[204:207], v[84:87]
	v_mfma_f32_16x16x32_bf16 v[72:75], v[152:155], v[218:221], v[72:75]
	v_mfma_f32_16x16x32_bf16 v[68:71], v[160:163], v[218:221], v[68:71]
	s_setprio 0
	s_barrier
	s_add_i32 s26, s40, s48
	v_lshl_add_u64 v[182:183], v[182:183], 0, s[94:95]
	s_mov_b32 m0, s26
	ds_read_b128 v[164:167], v229 offset:49152
	ds_read_b128 v[168:171], v229 offset:50176
	ds_read_b128 v[172:175], v229 offset:51200
	ds_read_b128 v[176:179], v229 offset:52224
	ds_read_b128 v[200:203], v229 offset:53248
	ds_read_b128 v[204:207], v229 offset:54272
	ds_read_b128 v[208:211], v229 offset:55296
	ds_read_b128 v[218:221], v229 offset:56320
	global_load_lds_dwordx4 v[182:183], off
	s_add_i32 m0, s26, 0x2000
	s_add_u32 s26, s44, 0xb0080
	v_lshl_add_u64 v[182:183], v[184:185], 0, s[94:95]
	s_addc_u32 s27, s45, 0
	s_add_i32 s40, s41, s48
	global_load_lds_dwordx4 v[182:183], off
	v_lshl_add_u64 v[182:183], s[26:27], 0, v[192:193]
	s_mov_b32 m0, s40
	s_nop 0
	global_load_lds_dwordx4 v[182:183], off
	v_lshl_add_u64 v[182:183], s[26:27], 0, v[0:1]
	s_add_i32 m0, s40, 0x2000
	s_nop 0
	global_load_lds_dwordx4 v[182:183], off
	v_lshl_add_u64 v[182:183], v[224:225], 0, s[94:95]
	s_mov_b32 m0, s54
	s_nop 0
	global_load_lds_dwordx4 v[182:183], off
	v_lshl_add_u64 v[182:183], v[230:231], 0, s[94:95]
	s_mov_b32 m0, s55
	s_nop 0
	global_load_lds_dwordx4 v[182:183], off
	s_waitcnt vmcnt(8)
	s_waitcnt lgkmcnt(0)
	s_barrier
	s_setprio 1
	s_waitcnt lgkmcnt(0)
	v_mfma_f32_16x16x32_bf16 v[64:67], v[132:135], v[164:167], v[64:67]
	v_mfma_f32_16x16x32_bf16 v[60:63], v[140:143], v[164:167], v[60:63]
	v_mfma_f32_16x16x32_bf16 v[48:51], v[132:135], v[172:175], v[48:51]
	v_mfma_f32_16x16x32_bf16 v[44:47], v[140:143], v[172:175], v[44:47]
	v_mfma_f32_16x16x32_bf16 v[32:35], v[132:135], v[200:203], v[32:35]
	v_mfma_f32_16x16x32_bf16 v[28:31], v[140:143], v[200:203], v[28:31]
	v_mfma_f32_16x16x32_bf16 v[16:19], v[132:135], v[208:211], v[16:19]
	v_mfma_f32_16x16x32_bf16 v[12:15], v[140:143], v[208:211], v[12:15]
	v_mfma_f32_16x16x32_bf16 v[64:67], v[136:139], v[168:171], v[64:67]
	v_mfma_f32_16x16x32_bf16 v[60:63], v[144:147], v[168:171], v[60:63]
	v_mfma_f32_16x16x32_bf16 v[48:51], v[136:139], v[176:179], v[48:51]
	v_mfma_f32_16x16x32_bf16 v[44:47], v[144:147], v[176:179], v[44:47]
	v_mfma_f32_16x16x32_bf16 v[32:35], v[136:139], v[204:207], v[32:35]
	v_mfma_f32_16x16x32_bf16 v[28:31], v[144:147], v[204:207], v[28:31]
	v_mfma_f32_16x16x32_bf16 v[16:19], v[136:139], v[218:221], v[16:19]
	v_mfma_f32_16x16x32_bf16 v[12:15], v[144:147], v[218:221], v[12:15]
	v_mfma_f32_16x16x32_bf16 v[56:59], v[148:151], v[164:167], v[56:59]
	v_mfma_f32_16x16x32_bf16 v[52:55], v[156:159], v[164:167], v[52:55]
	v_mfma_f32_16x16x32_bf16 v[40:43], v[148:151], v[172:175], v[40:43]
	v_mfma_f32_16x16x32_bf16 v[36:39], v[156:159], v[172:175], v[36:39]
	v_mfma_f32_16x16x32_bf16 v[24:27], v[148:151], v[200:203], v[24:27]
	v_mfma_f32_16x16x32_bf16 v[20:23], v[156:159], v[200:203], v[20:23]
	v_mfma_f32_16x16x32_bf16 v[8:11], v[148:151], v[208:211], v[8:11]
	v_mfma_f32_16x16x32_bf16 v[4:7], v[156:159], v[208:211], v[4:7]
	v_mfma_f32_16x16x32_bf16 v[56:59], v[152:155], v[168:171], v[56:59]
	v_mfma_f32_16x16x32_bf16 v[52:55], v[160:163], v[168:171], v[52:55]
	v_mfma_f32_16x16x32_bf16 v[40:43], v[152:155], v[176:179], v[40:43]
	v_mfma_f32_16x16x32_bf16 v[36:39], v[160:163], v[176:179], v[36:39]
	v_mfma_f32_16x16x32_bf16 v[24:27], v[152:155], v[204:207], v[24:27]
	v_mfma_f32_16x16x32_bf16 v[20:23], v[160:163], v[204:207], v[20:23]
	v_mfma_f32_16x16x32_bf16 v[8:11], v[152:155], v[218:221], v[8:11]
	v_mfma_f32_16x16x32_bf16 v[4:7], v[160:163], v[218:221], v[4:7]
	s_setprio 0
	s_barrier
	s_add_i32 s69, s69, 2
	s_add_u32 s65, s65, 0x100
	s_addc_u32 s68, s68, 0
	s_cmp_gt_u32 s69, 41
	s_mov_b64 s[26:27], s[36:37]
	s_cbranch_scc0 .LBB0_668
	s_and_b64 vcc, exec, s[14:15]
	s_cbranch_vccz .LBB0_671
	s_barrier
